# K-loop handoff: MFMA-segment closing barrier moved above the last MFMA, leftover MFMA at prio 2
# speedup vs baseline: 1.0145x; 1.0145x over previous
; #define PG8_STAGE(bufoff, gbase, voff) do { _Pragma("unroll") for (int _i = 0; _i < 2; ++_i) \
;         asm volatile("s_mov_b32 m0, %2\n\ts_nop 0\n\tglobal_load_lds_dwordx4 %0, %1" :: "v"((voff)[_i]), "s"((const char*)(gbase)), "s"(ldsbase + (unsigned)(bufoff) + ldsw + (unsigned)_i * 8192u) : "memory", "m0"); } while (0)
; #define PG8_LDA(dst, b, h) do { _Pragma("unroll") for (int m = 0; m < 4; ++m) _Pragma("unroll") for (int k = 0; k < 2; ++k) dst[m][k] = *(const PG8_LAS bf16x8*)(lds + PG8_SA(b, h) + aoff + m * 2048 + k * 1024); } while (0)
; #define PG8_LDB(dst, b, h) do { _Pragma("unroll") for (int n = 0; n < 2; ++n) _Pragma("unroll") for (int k = 0; k < 2; ++k) dst[n][k] = *(const PG8_LAS bf16x8*)(lds + PG8_SB(b, h) + boff + n * 2048 + k * 1024); } while (0)
; #define PG8_MMA(ai, bj, At, Bt) do { __builtin_amdgcn_s_setprio(1); _Pragma("unroll") for (int m = 0; m < 4; ++m) _Pragma("unroll") for (int n = 0; n < 2; ++n) _Pragma("unroll") for (int k = 0; k < 2; ++k) \
;         acc[ai][bj][m][n] = __builtin_amdgcn_mfma_f32_16x16x32_bf16(Bt[n][k], At[m][k], acc[ai][bj][m][n], 0, 0, 0); __builtin_amdgcn_s_setprio(0); } while (0)
; template <class Epi, class Sched, bool ALIGN_EPI = false, bool SP2 = false>
; __device__ __forceinline__ void gemm_phase(PG8_LAS unsigned char* lds, const Gemm g, const Sched& S, const Epi& E) {
;     ...
;             const bool last = (t == nt - 2);
;             const char* a1 = cA + (size_t)(t + 1) * kstep;
;             const char* a2 = last ? nA : cA + (size_t)(t + 2) * kstep; const char* b2 = last ? nB : cB + (size_t)(t + 2) * kstep;
;             const char* a3 = a2 + kstep; const char* b3 = b2 + kstep;
;             if (last && has_next) S.a_ready(nxt);
;             if constexpr (epi_has_mid<Epi>::value) { if (t == Epi::MID_T) E.mid(acc, cur, wr, wc, fr, fq); }
;             if constexpr (SP2) {
;             PG8_LDB(B0, 0, 0); PG8_LDB(B1, 0, 1); PG8_SCHED; PG8_LDA(At, 0, 0); PG8_STAGE(PG8_SA(1, 1), a1 + hstep, voffA);
;             PG8_WAIT_V(8); PG8_WAIT_L(0); PG8_BAR; PG8_MMA(0, 0, At, B0); PG8_MMA(0, 1, At, B1); PG8_BAR; PG8_SCHED;
;             PG8_LDA(At, 0, 1); PG8_STAGE(PG8_SB(0, 0), b2, voffB); PG8_STAGE(PG8_SB(0, 1), b2 + hstep, voffB); PG8_STAGE(PG8_SA(0, 0), a2, voffA);
;             PG8_WAIT_V(8); PG8_WAIT_L(0); PG8_BAR; PG8_MMA(1, 0, At, B0); PG8_MMA(1, 1, At, B1); PG8_BAR; PG8_SCHED;
.LBB0_138:
	ds_read_b128 v[148:151], v142
	ds_read_b128 v[152:155], v142 offset:1024
	ds_read_b128 v[156:159], v142 offset:2048
	ds_read_b128 v[160:163], v142 offset:3072
	ds_read_b128 v[164:167], v143
	ds_read_b128 v[168:171], v143 offset:1024
	ds_read_b128 v[172:175], v143 offset:2048
	ds_read_b128 v[176:179], v143 offset:3072
	s_add_u32 s62, s66, 0x100
	s_addc_u32 s63, s67, 0
	s_cmp_eq_u32 s96, 60
	s_cselect_b32 s86, s92, s62
	s_cselect_b32 s87, s13, s63
	s_cselect_b32 s84, s93, s94
	s_cselect_b32 s85, s11, s95
	s_add_u32 s76, s86, 0x80
	s_addc_u32 s77, s87, 0
	ds_read_b128 v[180:183], v144
	ds_read_b128 v[184:187], v144 offset:1024
	ds_read_b128 v[188:191], v144 offset:2048
	ds_read_b128 v[192:195], v144 offset:3072
	ds_read_b128 v[196:199], v144 offset:4096
	ds_read_b128 v[200:203], v144 offset:5120
	ds_read_b128 v[204:207], v144 offset:6144
	ds_read_b128 v[208:211], v144 offset:7168
	s_add_u32 s66, s66, 0x100080
	s_addc_u32 s67, s67, 0
	s_mov_b32 m0, s83
	s_nop 0
	global_load_lds_dwordx4 v136, s[66:67]
	s_nop 0
	s_mov_b32 m0, s88
	s_nop 0
	global_load_lds_dwordx4 v138, s[66:67]
	s_waitcnt vmcnt(8)
	s_waitcnt lgkmcnt(0)
	s_barrier
	s_setprio 1
	s_waitcnt lgkmcnt(7)
	v_mfma_f32_16x16x32_bf16 v[126:129], v[148:151], v[180:183], v[126:129]
	v_mfma_f32_16x16x32_bf16 v[122:125], v[156:159], v[180:183], v[122:125]
	s_waitcnt lgkmcnt(5)
	v_mfma_f32_16x16x32_bf16 v[110:113], v[148:151], v[188:191], v[110:113]
	v_mfma_f32_16x16x32_bf16 v[106:109], v[156:159], v[188:191], v[106:109]
	s_waitcnt lgkmcnt(3)
	v_mfma_f32_16x16x32_bf16 v[94:97], v[148:151], v[196:199], v[94:97]
	v_mfma_f32_16x16x32_bf16 v[90:93], v[156:159], v[196:199], v[90:93]
	s_waitcnt lgkmcnt(1)
	v_mfma_f32_16x16x32_bf16 v[78:81], v[148:151], v[204:207], v[78:81]
	v_mfma_f32_16x16x32_bf16 v[74:77], v[156:159], v[204:207], v[74:77]
	v_mfma_f32_16x16x32_bf16 v[126:129], v[152:155], v[184:187], v[126:129]
	v_mfma_f32_16x16x32_bf16 v[122:125], v[160:163], v[184:187], v[122:125]
	v_mfma_f32_16x16x32_bf16 v[110:113], v[152:155], v[192:195], v[110:113]
	v_mfma_f32_16x16x32_bf16 v[106:109], v[160:163], v[192:195], v[106:109]
	v_mfma_f32_16x16x32_bf16 v[94:97], v[152:155], v[200:203], v[94:97]
	v_mfma_f32_16x16x32_bf16 v[90:93], v[160:163], v[200:203], v[90:93]
	s_waitcnt lgkmcnt(0)
	v_mfma_f32_16x16x32_bf16 v[78:81], v[152:155], v[208:211], v[78:81]
	v_mfma_f32_16x16x32_bf16 v[74:77], v[160:163], v[208:211], v[74:77]
	s_setprio 0
	s_setprio 1
	v_mfma_f32_16x16x32_bf16 v[118:121], v[164:167], v[180:183], v[118:121]
	v_mfma_f32_16x16x32_bf16 v[114:117], v[172:175], v[180:183], v[114:117]
	v_mfma_f32_16x16x32_bf16 v[102:105], v[164:167], v[188:191], v[102:105]
	v_mfma_f32_16x16x32_bf16 v[98:101], v[172:175], v[188:191], v[98:101]
	v_mfma_f32_16x16x32_bf16 v[86:89], v[164:167], v[196:199], v[86:89]
	v_mfma_f32_16x16x32_bf16 v[82:85], v[172:175], v[196:199], v[82:85]
	v_mfma_f32_16x16x32_bf16 v[70:73], v[164:167], v[204:207], v[70:73]
	v_mfma_f32_16x16x32_bf16 v[66:69], v[172:175], v[204:207], v[66:69]
	v_mfma_f32_16x16x32_bf16 v[118:121], v[168:171], v[184:187], v[118:121]
	v_mfma_f32_16x16x32_bf16 v[114:117], v[176:179], v[184:187], v[114:117]
	v_mfma_f32_16x16x32_bf16 v[102:105], v[168:171], v[192:195], v[102:105]
	v_mfma_f32_16x16x32_bf16 v[98:101], v[176:179], v[192:195], v[98:101]
	v_mfma_f32_16x16x32_bf16 v[86:89], v[168:171], v[200:203], v[86:89]
	v_mfma_f32_16x16x32_bf16 v[82:85], v[176:179], v[200:203], v[82:85]
	v_mfma_f32_16x16x32_bf16 v[70:73], v[168:171], v[208:211], v[70:73]
	s_setprio 2
	s_barrier
	v_mfma_f32_16x16x32_bf16 v[66:69], v[176:179], v[208:211], v[66:69]
	s_setprio 0
	ds_read_b128 v[180:183], v144 offset:16384
	ds_read_b128 v[184:187], v144 offset:17408
	ds_read_b128 v[188:191], v144 offset:18432
	ds_read_b128 v[192:195], v144 offset:19456
	ds_read_b128 v[196:199], v144 offset:20480
	ds_read_b128 v[200:203], v144 offset:21504
	ds_read_b128 v[204:207], v144 offset:22528
	ds_read_b128 v[208:211], v144 offset:23552
	s_mov_b32 m0, s55
	s_nop 0
	global_load_lds_dwordx4 v137, s[84:85]
	s_add_u32 s66, s84, 0x100000
	s_mov_b32 m0, s56
	s_nop 0
	global_load_lds_dwordx4 v139, s[84:85]
	s_addc_u32 s67, s85, 0
	s_mov_b32 m0, s57
	s_nop 0
	global_load_lds_dwordx4 v137, s[66:67]
	s_nop 0
	s_mov_b32 m0, s58
	s_nop 0
	global_load_lds_dwordx4 v139, s[66:67]
	s_nop 0
	s_mov_b32 m0, s54
	s_nop 0
	global_load_lds_dwordx4 v136, s[86:87]
	s_nop 0
	s_mov_b32 m0, s59
	s_nop 0
	global_load_lds_dwordx4 v138, s[86:87]
	s_waitcnt vmcnt(8)
	s_waitcnt lgkmcnt(0)
	s_barrier
; #define PG8_STAGE(bufoff, gbase, voff) do { _Pragma("unroll") for (int _i = 0; _i < 2; ++_i) \
;         asm volatile("s_mov_b32 m0, %2\n\ts_nop 0\n\tglobal_load_lds_dwordx4 %0, %1" :: "v"((voff)[_i]), "s"((const char*)(gbase)), "s"(ldsbase + (unsigned)(bufoff) + ldsw + (unsigned)_i * 8192u) : "memory", "m0"); } while (0)
; #define PG8_LDA(dst, b, h) do { _Pragma("unroll") for (int m = 0; m < 4; ++m) _Pragma("unroll") for (int k = 0; k < 2; ++k) dst[m][k] = *(const PG8_LAS bf16x8*)(lds + PG8_SA(b, h) + aoff + m * 2048 + k * 1024); } while (0)
; #define PG8_LDB(dst, b, h) do { _Pragma("unroll") for (int n = 0; n < 2; ++n) _Pragma("unroll") for (int k = 0; k < 2; ++k) dst[n][k] = *(const PG8_LAS bf16x8*)(lds + PG8_SB(b, h) + boff + n * 2048 + k * 1024); } while (0)
; #define PG8_MMA(ai, bj, At, Bt) do { __builtin_amdgcn_s_setprio(1); _Pragma("unroll") for (int m = 0; m < 4; ++m) _Pragma("unroll") for (int n = 0; n < 2; ++n) _Pragma("unroll") for (int k = 0; k < 2; ++k) \
;         acc[ai][bj][m][n] = __builtin_amdgcn_mfma_f32_16x16x32_bf16(Bt[n][k], At[m][k], acc[ai][bj][m][n], 0, 0, 0); __builtin_amdgcn_s_setprio(0); } while (0)
; #define PG8_WAIT_V(n) asm volatile("s_waitcnt vmcnt(" #n ")" ::: "memory")
; #define PG8_WAIT_L(n) asm volatile("s_waitcnt lgkmcnt(" #n ")" ::: "memory")
; #define PG8_BAR __builtin_amdgcn_s_barrier()
; #define PG8_SCHED __builtin_amdgcn_sched_barrier(0)
; template <class Epi, class Sched, bool ALIGN_EPI = false, bool SP2 = false>
; __device__ __forceinline__ void gemm_phase(PG8_LAS unsigned char* lds, const Gemm g, const Sched& S, const Epi& E) {
;     ...
;             PG8_WAIT_V(8); PG8_WAIT_L(0); PG8_BAR; PG8_MMA(1, 0, At, B0); PG8_MMA(1, 1, At, B1); PG8_BAR; PG8_SCHED;
;             PG8_LDB(B0, 1, 0); PG8_LDB(B1, 1, 1); PG8_SCHED; PG8_LDA(At, 1, 0); PG8_STAGE(PG8_SA(0, 1), a2 + hstep, voffA);
;             PG8_WAIT_V(8); PG8_WAIT_L(0); PG8_BAR; PG8_MMA(0, 0, At, B0); PG8_MMA(0, 1, At, B1); PG8_BAR; PG8_SCHED;
;             PG8_LDA(At, 1, 1); PG8_STAGE(PG8_SB(1, 0), b3, voffB); PG8_STAGE(PG8_SB(1, 1), b3 + hstep, voffB); PG8_STAGE(PG8_SA(1, 0), a3, voffA);
;             PG8_WAIT_V(8); PG8_WAIT_L(0); PG8_BAR; PG8_MMA(1, 0, At, B0); PG8_MMA(1, 1, At, B1); PG8_BAR; PG8_SCHED;
	s_setprio 1
	s_waitcnt lgkmcnt(7)
	v_mfma_f32_16x16x32_bf16 v[62:65], v[148:151], v[180:183], v[62:65]
	v_mfma_f32_16x16x32_bf16 v[58:61], v[156:159], v[180:183], v[58:61]
	s_waitcnt lgkmcnt(5)
	v_mfma_f32_16x16x32_bf16 v[46:49], v[148:151], v[188:191], v[46:49]
	v_mfma_f32_16x16x32_bf16 v[42:45], v[156:159], v[188:191], v[42:45]
	s_waitcnt lgkmcnt(3)
	v_mfma_f32_16x16x32_bf16 v[30:33], v[148:151], v[196:199], v[30:33]
	v_mfma_f32_16x16x32_bf16 v[26:29], v[156:159], v[196:199], v[26:29]
	s_waitcnt lgkmcnt(1)
	v_mfma_f32_16x16x32_bf16 v[14:17], v[148:151], v[204:207], v[14:17]
	v_mfma_f32_16x16x32_bf16 v[10:13], v[156:159], v[204:207], v[10:13]
	v_mfma_f32_16x16x32_bf16 v[62:65], v[152:155], v[184:187], v[62:65]
	v_mfma_f32_16x16x32_bf16 v[58:61], v[160:163], v[184:187], v[58:61]
	v_mfma_f32_16x16x32_bf16 v[46:49], v[152:155], v[192:195], v[46:49]
	v_mfma_f32_16x16x32_bf16 v[42:45], v[160:163], v[192:195], v[42:45]
	v_mfma_f32_16x16x32_bf16 v[30:33], v[152:155], v[200:203], v[30:33]
	v_mfma_f32_16x16x32_bf16 v[26:29], v[160:163], v[200:203], v[26:29]
	s_waitcnt lgkmcnt(0)
	v_mfma_f32_16x16x32_bf16 v[14:17], v[152:155], v[208:211], v[14:17]
	v_mfma_f32_16x16x32_bf16 v[10:13], v[160:163], v[208:211], v[10:13]
	s_setprio 0
	s_setprio 1
	v_mfma_f32_16x16x32_bf16 v[54:57], v[164:167], v[180:183], v[54:57]
	v_mfma_f32_16x16x32_bf16 v[50:53], v[172:175], v[180:183], v[50:53]
	v_mfma_f32_16x16x32_bf16 v[38:41], v[164:167], v[188:191], v[38:41]
	v_mfma_f32_16x16x32_bf16 v[34:37], v[172:175], v[188:191], v[34:37]
	v_mfma_f32_16x16x32_bf16 v[22:25], v[164:167], v[196:199], v[22:25]
	v_mfma_f32_16x16x32_bf16 v[18:21], v[172:175], v[196:199], v[18:21]
	v_mfma_f32_16x16x32_bf16 v[6:9], v[164:167], v[204:207], v[6:9]
	v_mfma_f32_16x16x32_bf16 v[2:5], v[172:175], v[204:207], v[2:5]
	v_mfma_f32_16x16x32_bf16 v[54:57], v[168:171], v[184:187], v[54:57]
	v_mfma_f32_16x16x32_bf16 v[50:53], v[176:179], v[184:187], v[50:53]
	v_mfma_f32_16x16x32_bf16 v[38:41], v[168:171], v[192:195], v[38:41]
	v_mfma_f32_16x16x32_bf16 v[34:37], v[176:179], v[192:195], v[34:37]
	v_mfma_f32_16x16x32_bf16 v[22:25], v[168:171], v[200:203], v[22:25]
	v_mfma_f32_16x16x32_bf16 v[18:21], v[176:179], v[200:203], v[18:21]
	v_mfma_f32_16x16x32_bf16 v[6:9], v[168:171], v[208:211], v[6:9]
	s_setprio 2
	s_barrier
	v_mfma_f32_16x16x32_bf16 v[2:5], v[176:179], v[208:211], v[2:5]
	s_setprio 0
	ds_read_b128 v[148:151], v145
	ds_read_b128 v[152:155], v145 offset:1024
	ds_read_b128 v[156:159], v145 offset:2048
	ds_read_b128 v[160:163], v145 offset:3072
	ds_read_b128 v[164:167], v146
	ds_read_b128 v[168:171], v146 offset:1024
	ds_read_b128 v[172:175], v146 offset:2048
	ds_read_b128 v[176:179], v146 offset:3072
	ds_read_b128 v[180:183], v144 offset:32768
	ds_read_b128 v[184:187], v144 offset:33792
	ds_read_b128 v[188:191], v144 offset:34816
	ds_read_b128 v[192:195], v144 offset:35840
	ds_read_b128 v[196:199], v144 offset:36864
	ds_read_b128 v[200:203], v144 offset:37888
	ds_read_b128 v[204:207], v144 offset:38912
	ds_read_b128 v[208:211], v144 offset:39936
	s_add_u32 s66, s86, 0x100000
	s_addc_u32 s67, s87, 0
	s_mov_b32 m0, s60
	s_nop 0
	global_load_lds_dwordx4 v136, s[66:67]
	s_nop 0
	s_mov_b32 m0, s61
	s_nop 0
	global_load_lds_dwordx4 v138, s[66:67]
	s_waitcnt vmcnt(8)
	s_waitcnt lgkmcnt(0)
	s_barrier
	s_setprio 1
	s_waitcnt lgkmcnt(7)
	v_mfma_f32_16x16x32_bf16 v[126:129], v[148:151], v[180:183], v[126:129]
	v_mfma_f32_16x16x32_bf16 v[122:125], v[156:159], v[180:183], v[122:125]
	s_waitcnt lgkmcnt(5)
	v_mfma_f32_16x16x32_bf16 v[110:113], v[148:151], v[188:191], v[110:113]
	v_mfma_f32_16x16x32_bf16 v[106:109], v[156:159], v[188:191], v[106:109]
	s_waitcnt lgkmcnt(3)
	v_mfma_f32_16x16x32_bf16 v[94:97], v[148:151], v[196:199], v[94:97]
	v_mfma_f32_16x16x32_bf16 v[90:93], v[156:159], v[196:199], v[90:93]
	s_waitcnt lgkmcnt(1)
	v_mfma_f32_16x16x32_bf16 v[78:81], v[148:151], v[204:207], v[78:81]
	v_mfma_f32_16x16x32_bf16 v[74:77], v[156:159], v[204:207], v[74:77]
	v_mfma_f32_16x16x32_bf16 v[126:129], v[152:155], v[184:187], v[126:129]
	v_mfma_f32_16x16x32_bf16 v[122:125], v[160:163], v[184:187], v[122:125]
	v_mfma_f32_16x16x32_bf16 v[110:113], v[152:155], v[192:195], v[110:113]
	v_mfma_f32_16x16x32_bf16 v[106:109], v[160:163], v[192:195], v[106:109]
	v_mfma_f32_16x16x32_bf16 v[94:97], v[152:155], v[200:203], v[94:97]
	v_mfma_f32_16x16x32_bf16 v[90:93], v[160:163], v[200:203], v[90:93]
	s_waitcnt lgkmcnt(0)
	v_mfma_f32_16x16x32_bf16 v[78:81], v[152:155], v[208:211], v[78:81]
	v_mfma_f32_16x16x32_bf16 v[74:77], v[160:163], v[208:211], v[74:77]
	s_setprio 0
	s_setprio 1
	v_mfma_f32_16x16x32_bf16 v[118:121], v[164:167], v[180:183], v[118:121]
	v_mfma_f32_16x16x32_bf16 v[114:117], v[172:175], v[180:183], v[114:117]
	v_mfma_f32_16x16x32_bf16 v[102:105], v[164:167], v[188:191], v[102:105]
	v_mfma_f32_16x16x32_bf16 v[98:101], v[172:175], v[188:191], v[98:101]
	v_mfma_f32_16x16x32_bf16 v[86:89], v[164:167], v[196:199], v[86:89]
	v_mfma_f32_16x16x32_bf16 v[82:85], v[172:175], v[196:199], v[82:85]
	v_mfma_f32_16x16x32_bf16 v[70:73], v[164:167], v[204:207], v[70:73]
	v_mfma_f32_16x16x32_bf16 v[66:69], v[172:175], v[204:207], v[66:69]
	v_mfma_f32_16x16x32_bf16 v[118:121], v[168:171], v[184:187], v[118:121]
	v_mfma_f32_16x16x32_bf16 v[114:117], v[176:179], v[184:187], v[114:117]
	v_mfma_f32_16x16x32_bf16 v[102:105], v[168:171], v[192:195], v[102:105]
	v_mfma_f32_16x16x32_bf16 v[98:101], v[176:179], v[192:195], v[98:101]
	v_mfma_f32_16x16x32_bf16 v[86:89], v[168:171], v[200:203], v[86:89]
	v_mfma_f32_16x16x32_bf16 v[82:85], v[176:179], v[200:203], v[82:85]
	v_mfma_f32_16x16x32_bf16 v[70:73], v[168:171], v[208:211], v[70:73]
	s_setprio 2
	s_barrier
; __device__ __forceinline__ unsigned cvt_pk_bf16(float lo, float hi) { unsigned r; asm volatile("v_cvt_pk_bf16_f32 %0, %1, %2" : "=v"(r) : "v"(lo), "v"(hi)); return r; }
; __device__ __forceinline__ float silu_f(float x) { return x * sigmoid_f(x); }
; #define PG8_STAGE(bufoff, gbase, voff) do { _Pragma("unroll") for (int _i = 0; _i < 2; ++_i) \
;         asm volatile("s_mov_b32 m0, %2\n\ts_nop 0\n\tglobal_load_lds_dwordx4 %0, %1" :: "v"((voff)[_i]), "s"((const char*)(gbase)), "s"(ldsbase + (unsigned)(bufoff) + ldsw + (unsigned)_i * 8192u) : "memory", "m0"); } while (0)
; #define PG8_LDA(dst, b, h) do { _Pragma("unroll") for (int m = 0; m < 4; ++m) _Pragma("unroll") for (int k = 0; k < 2; ++k) dst[m][k] = *(const PG8_LAS bf16x8*)(lds + PG8_SA(b, h) + aoff + m * 2048 + k * 1024); } while (0)
; #define PG8_WAIT_V(n) asm volatile("s_waitcnt vmcnt(" #n ")" ::: "memory")
; #define PG8_WAIT_L(n) asm volatile("s_waitcnt lgkmcnt(" #n ")" ::: "memory")
; #define PG8_BAR __builtin_amdgcn_s_barrier()
;     __device__ __forceinline__ void operator()(const f32x4 (&acc)[2][2][4][2], const Unit& u, int wr, int wc, int fr, int fq) const {
;         const int row0 = u.pm * BM + wr * 64 + fr, col0 = u.pn * HALF + wc * 32 + 8 * fq;
; #pragma unroll
;         for (int ai = 0; ai < 2; ++ai)
; #pragma unroll
;             for (int m = 0; m < 4; ++m) { bf16_t* rowp = O + (size_t)(row0 + ai * HALF + m * 16) * ldc + col0;
;                 const f32x4 g0 = acc[ai][0][m][0], g1 = acc[ai][0][m][1], u0 = acc[ai][1][m][0], u1 = acc[ai][1][m][1];
;                 f32x4 v0, v1;
; #pragma unroll
;                 for (int j = 0; j < 4; ++j) { v0[j] = silu_f(g0[j]) * u0[j]; v1[j] = silu_f(g1[j]) * u1[j]; }
;                 u32x4 w; w.x = cvt_pk_bf16(v0[0], v0[1]); w.y = cvt_pk_bf16(v0[2], v0[3]); w.z = cvt_pk_bf16(v1[0], v1[1]); w.w = cvt_pk_bf16(v1[2], v1[3]);
;                 *(u32x4*)rowp = w; }
; template <class Epi, class Sched, bool ALIGN_EPI = false, bool SP2 = false>
; __device__ __forceinline__ void gemm_phase(PG8_LAS unsigned char* lds, const Gemm g, const Sched& S, const Epi& E) {
;     ...
;             PG8_LDA(At, 1, 1); PG8_STAGE(PG8_SB(1, 0), b3, voffB); PG8_STAGE(PG8_SB(1, 1), b3 + hstep, voffB); PG8_STAGE(PG8_SA(1, 0), a3, voffA);
;             PG8_WAIT_V(8); PG8_WAIT_L(0); PG8_BAR; PG8_MMA(1, 0, At, B0); PG8_MMA(1, 1, At, B1); PG8_BAR; PG8_SCHED;
	v_mfma_f32_16x16x32_bf16 v[66:69], v[176:179], v[208:211], v[66:69]
	s_setprio 0
	ds_read_b128 v[180:183], v144 offset:49152
	ds_read_b128 v[184:187], v144 offset:50176
	ds_read_b128 v[188:191], v144 offset:51200
	ds_read_b128 v[192:195], v144 offset:52224
	ds_read_b128 v[196:199], v144 offset:53248
	ds_read_b128 v[200:203], v144 offset:54272
	ds_read_b128 v[204:207], v144 offset:55296
	ds_read_b128 v[208:211], v144 offset:56320
	s_add_u32 s66, s84, 0x80
	s_addc_u32 s67, s85, 0
	s_mov_b32 m0, s64
	s_nop 0
	global_load_lds_dwordx4 v137, s[66:67]
	s_nop 0
	s_mov_b32 m0, s65
	s_nop 0
	global_load_lds_dwordx4 v139, s[66:67]
	s_add_u32 s66, s84, 0x100080
	s_addc_u32 s67, s85, 0
	s_mov_b32 m0, s70
	s_nop 0
	global_load_lds_dwordx4 v137, s[66:67]
	s_nop 0
	s_mov_b32 m0, s71
	s_nop 0
	global_load_lds_dwordx4 v139, s[66:67]
	s_nop 0
	s_mov_b32 m0, s68
	s_nop 0
	global_load_lds_dwordx4 v136, s[76:77]
	s_nop 0
	s_mov_b32 m0, s69
	s_nop 0
	global_load_lds_dwordx4 v138, s[76:77]
	s_waitcnt vmcnt(8)
	s_waitcnt lgkmcnt(0)
	s_barrier
	s_setprio 1
	s_waitcnt lgkmcnt(7)
	v_mfma_f32_16x16x32_bf16 v[62:65], v[148:151], v[180:183], v[62:65]
	v_mfma_f32_16x16x32_bf16 v[58:61], v[156:159], v[180:183], v[58:61]
	s_waitcnt lgkmcnt(5)
	v_mfma_f32_16x16x32_bf16 v[46:49], v[148:151], v[188:191], v[46:49]
	v_mfma_f32_16x16x32_bf16 v[42:45], v[156:159], v[188:191], v[42:45]
	s_waitcnt lgkmcnt(3)
	v_mfma_f32_16x16x32_bf16 v[30:33], v[148:151], v[196:199], v[30:33]
	v_mfma_f32_16x16x32_bf16 v[26:29], v[156:159], v[196:199], v[26:29]
	s_waitcnt lgkmcnt(1)
	v_mfma_f32_16x16x32_bf16 v[14:17], v[148:151], v[204:207], v[14:17]
	v_mfma_f32_16x16x32_bf16 v[10:13], v[156:159], v[204:207], v[10:13]
	v_mfma_f32_16x16x32_bf16 v[62:65], v[152:155], v[184:187], v[62:65]
	v_mfma_f32_16x16x32_bf16 v[58:61], v[160:163], v[184:187], v[58:61]
	v_mfma_f32_16x16x32_bf16 v[46:49], v[152:155], v[192:195], v[46:49]
	v_mfma_f32_16x16x32_bf16 v[42:45], v[160:163], v[192:195], v[42:45]
	v_mfma_f32_16x16x32_bf16 v[30:33], v[152:155], v[200:203], v[30:33]
	v_mfma_f32_16x16x32_bf16 v[26:29], v[160:163], v[200:203], v[26:29]
	s_waitcnt lgkmcnt(0)
	v_mfma_f32_16x16x32_bf16 v[14:17], v[152:155], v[208:211], v[14:17]
	v_mfma_f32_16x16x32_bf16 v[10:13], v[160:163], v[208:211], v[10:13]
	s_setprio 0
	s_setprio 1
	v_mfma_f32_16x16x32_bf16 v[54:57], v[164:167], v[180:183], v[54:57]
	v_mfma_f32_16x16x32_bf16 v[50:53], v[172:175], v[180:183], v[50:53]
	v_mfma_f32_16x16x32_bf16 v[38:41], v[164:167], v[188:191], v[38:41]
	v_mfma_f32_16x16x32_bf16 v[34:37], v[172:175], v[188:191], v[34:37]
	v_mfma_f32_16x16x32_bf16 v[22:25], v[164:167], v[196:199], v[22:25]
	v_mfma_f32_16x16x32_bf16 v[18:21], v[172:175], v[196:199], v[18:21]
	v_mfma_f32_16x16x32_bf16 v[6:9], v[164:167], v[204:207], v[6:9]
	v_mfma_f32_16x16x32_bf16 v[2:5], v[172:175], v[204:207], v[2:5]
	v_mfma_f32_16x16x32_bf16 v[54:57], v[168:171], v[184:187], v[54:57]
	v_mfma_f32_16x16x32_bf16 v[50:53], v[176:179], v[184:187], v[50:53]
	v_mfma_f32_16x16x32_bf16 v[38:41], v[168:171], v[192:195], v[38:41]
	v_mfma_f32_16x16x32_bf16 v[34:37], v[176:179], v[192:195], v[34:37]
	v_mfma_f32_16x16x32_bf16 v[22:25], v[168:171], v[200:203], v[22:25]
	v_mfma_f32_16x16x32_bf16 v[18:21], v[176:179], v[200:203], v[18:21]
	v_mfma_f32_16x16x32_bf16 v[6:9], v[168:171], v[208:211], v[6:9]
	s_setprio 2
	s_barrier
	v_mfma_f32_16x16x32_bf16 v[2:5], v[176:179], v[208:211], v[2:5]
	s_setprio 0
	s_add_i32 s96, s96, 2
	s_add_u32 s94, s94, 0x100
	s_addc_u32 s95, s95, 0
	s_cmp_gt_u32 s96, 61
	s_mov_b64 s[66:67], s[62:63]
	s_cbranch_scc0 .LBB0_138
	v_mul_f32_e32 v134, 0xbfb8aa3b, v126
	v_exp_f32_e32 v150, v134
	v_mul_f32_e32 v134, 0xbfb8aa3b, v122
	v_exp_f32_e32 v151, v134
	v_lshl_or_b32 v148, s91, 7, v141
	v_add_f32_e32 v150, 1.0, v150
	v_rcp_f32_e32 v152, v150
	v_add_f32_e32 v150, 1.0, v151
	v_rcp_f32_e32 v153, v150
	v_lshl_add_u32 v147, s82, 8, v140
	v_mul_f32_e32 v126, v126, v152
	v_mul_f32_e32 v118, v126, v118
	v_mul_f32_e32 v126, 0xbfb8aa3b, v127
	v_exp_f32_e32 v126, v126
	v_mul_f32_e32 v152, 0xbfb8aa3b, v123
	v_exp_f32_e32 v152, v152
	v_mul_f32_e32 v122, v122, v153
	v_mul_f32_e32 v122, v122, v114
	v_add_f32_e32 v114, 1.0, v126
	v_rcp_f32_e32 v114, v114
	v_add_f32_e32 v126, 1.0, v152
	v_mul_f32_e32 v152, 0xbfb8aa3b, v128
	v_rcp_f32_e32 v126, v126
	v_exp_f32_e32 v152, v152
	v_mul_f32_e32 v114, v127, v114
	v_mul_f32_e32 v119, v114, v119
	v_mul_f32_e32 v114, v123, v126
	v_add_f32_e32 v123, 1.0, v152
	v_rcp_f32_e32 v123, v123
	v_mul_f32_e32 v126, 0xbfb8aa3b, v124
	v_exp_f32_e32 v126, v126
	v_mul_f32_e32 v127, v114, v115
	v_mul_f32_e32 v114, v128, v123
	v_mul_f32_e32 v115, 0xbfb8aa3b, v129
	v_mul_f32_e32 v123, v114, v120
	v_exp_f32_e32 v115, v115
	v_mul_f32_e32 v120, 0xbfb8aa3b, v125
	v_exp_f32_e32 v120, v120
	v_add_f32_e32 v114, 1.0, v126
	v_rcp_f32_e32 v114, v114
	v_add_f32_e32 v115, 1.0, v115
	v_rcp_f32_e32 v115, v115
	v_add_f32_e32 v120, 1.0, v120
	v_rcp_f32_e32 v120, v120
	v_mul_f32_e32 v114, v124, v114
	v_mul_f32_e32 v124, v114, v116
	v_mul_f32_e32 v114, v129, v115
	v_ashrrev_i32_e32 v149, 31, v148
	v_mov_b64_e32 v[134:135], s[72:73]
	v_mul_f32_e32 v126, v114, v121
	v_mul_f32_e32 v114, v125, v120
	v_mad_i64_i32 v[150:151], s[62:63], v147, s90, v[134:135]
	v_mul_f32_e32 v125, v114, v117
	v_lshlrev_b64 v[114:115], 1, v[148:149]
	v_lshl_add_u64 v[120:121], v[150:151], 0, v[114:115]
	v_cvt_pk_bf16_f32 v116, v118, v119
	v_cvt_pk_bf16_f32 v117, v123, v126
	v_cvt_pk_bf16_f32 v118, v122, v127
	v_cvt_pk_bf16_f32 v119, v124, v125
	global_store_dwordx4 v[120:121], v[116:119], off
	s_and_b64 vcc, exec, s[0:1]
	s_mov_b32 s91, s10
	v_mul_f32_e32 v116, 0xbfb8aa3b, v110
	v_exp_f32_e32 v116, v116
; __device__ __forceinline__ unsigned cvt_pk_bf16(float lo, float hi) { unsigned r; asm volatile("v_cvt_pk_bf16_f32 %0, %1, %2" : "=v"(r) : "v"(lo), "v"(hi)); return r; }
; __device__ __forceinline__ float silu_f(float x) { return x * sigmoid_f(x); }
;     __device__ __forceinline__ void operator()(const f32x4 (&acc)[2][2][4][2], const Unit& u, int wr, int wc, int fr, int fq) const {
;         const int row0 = u.pm * BM + wr * 64 + fr, col0 = u.pn * HALF + wc * 32 + 8 * fq;
; #pragma unroll
;         for (int ai = 0; ai < 2; ++ai)
; #pragma unroll
;             for (int m = 0; m < 4; ++m) { bf16_t* rowp = O + (size_t)(row0 + ai * HALF + m * 16) * ldc + col0;
;                 const f32x4 g0 = acc[ai][0][m][0], g1 = acc[ai][0][m][1], u0 = acc[ai][1][m][0], u1 = acc[ai][1][m][1];
;                 f32x4 v0, v1;
; #pragma unroll
;                 for (int j = 0; j < 4; ++j) { v0[j] = silu_f(g0[j]) * u0[j]; v1[j] = silu_f(g1[j]) * u1[j]; }
;                 u32x4 w; w.x = cvt_pk_bf16(v0[0], v0[1]); w.y = cvt_pk_bf16(v0[2], v0[3]); w.z = cvt_pk_bf16(v1[0], v1[1]); w.w = cvt_pk_bf16(v1[2], v1[3]);
;                 *(u32x4*)rowp = w; }
	v_mul_f32_e32 v117, 0xbfb8aa3b, v106
	v_exp_f32_e32 v117, v117
	v_or_b32_e32 v118, 16, v147
	v_add_f32_e32 v116, 1.0, v116
	v_rcp_f32_e32 v119, v116
	v_add_f32_e32 v116, 1.0, v117
	v_rcp_f32_e32 v120, v116
	v_mad_i64_i32 v[116:117], s[62:63], v118, s90, v[134:135]
	v_mul_f32_e32 v110, v110, v119
	v_mul_f32_e32 v110, v110, v102
	v_mul_f32_e32 v102, v106, v120
	v_mul_f32_e32 v106, 0xbfb8aa3b, v111
	v_exp_f32_e32 v106, v106
	v_mul_f32_e32 v118, 0xbfb8aa3b, v107
	v_mul_f32_e32 v119, v102, v98
	v_exp_f32_e32 v118, v118
	v_add_f32_e32 v98, 1.0, v106
	v_rcp_f32_e32 v98, v98
	v_mul_f32_e32 v106, 0xbfb8aa3b, v112
	v_exp_f32_e32 v106, v106
	v_add_f32_e32 v102, 1.0, v118
	v_mul_f32_e32 v98, v111, v98
	v_rcp_f32_e32 v102, v102
	v_mul_f32_e32 v98, v98, v103
	v_add_f32_e32 v103, 1.0, v106
	v_rcp_f32_e32 v103, v103
	v_mul_f32_e32 v102, v107, v102
	v_mul_f32_e32 v106, 0xbfb8aa3b, v108
	v_mul_f32_e32 v107, v102, v99
	v_mul_f32_e32 v99, v112, v103
	v_exp_f32_e32 v106, v106
	v_mul_f32_e32 v99, v99, v104
	v_mul_f32_e32 v103, 0xbfb8aa3b, v113
	v_mul_f32_e32 v104, 0xbfb8aa3b, v109
	v_exp_f32_e32 v103, v103
	v_exp_f32_e32 v104, v104
	v_add_f32_e32 v102, 1.0, v106
	v_rcp_f32_e32 v102, v102
	v_add_f32_e32 v103, 1.0, v103
	v_add_f32_e32 v104, 1.0, v104
	v_rcp_f32_e32 v103, v103
	v_rcp_f32_e32 v104, v104
	v_mul_f32_e32 v102, v108, v102
	v_mul_f32_e32 v106, v102, v100
	v_mul_f32_e32 v100, v113, v103
	v_mul_f32_e32 v102, v109, v104
	v_mul_f32_e32 v100, v100, v105
	v_mul_f32_e32 v101, v102, v101
	v_lshl_add_u64 v[102:103], v[116:117], 0, v[114:115]
	v_cvt_pk_bf16_f32 v98, v110, v98
	v_cvt_pk_bf16_f32 v99, v99, v100
	v_cvt_pk_bf16_f32 v100, v119, v107
	v_cvt_pk_bf16_f32 v101, v106, v101
	global_store_dwordx4 v[102:103], v[98:101], off
	s_mov_b32 s82, s12
	s_mov_b64 s[66:67], s[14:15]
	v_mul_f32_e32 v98, 0xbfb8aa3b, v94
	v_exp_f32_e32 v98, v98
	v_mul_f32_e32 v99, 0xbfb8aa3b, v90
	v_exp_f32_e32 v99, v99
	v_or_b32_e32 v100, 32, v147
	v_add_f32_e32 v98, 1.0, v98
	v_rcp_f32_e32 v101, v98
	v_add_f32_e32 v98, 1.0, v99
	v_rcp_f32_e32 v102, v98
	v_mad_i64_i32 v[98:99], s[62:63], v100, s90, v[134:135]
	v_mul_f32_e32 v94, v94, v101
	v_mul_f32_e32 v94, v94, v86
	v_mul_f32_e32 v86, v90, v102
	v_mul_f32_e32 v90, 0xbfb8aa3b, v95
	v_exp_f32_e32 v90, v90
	v_mul_f32_e32 v100, 0xbfb8aa3b, v91
	v_mul_f32_e32 v101, v86, v82
	v_exp_f32_e32 v100, v100
	v_add_f32_e32 v82, 1.0, v90
	v_rcp_f32_e32 v82, v82
	v_mul_f32_e32 v90, 0xbfb8aa3b, v96
	v_exp_f32_e32 v90, v90
	v_add_f32_e32 v86, 1.0, v100
	v_mul_f32_e32 v82, v95, v82
	v_rcp_f32_e32 v86, v86
	v_mul_f32_e32 v82, v82, v87
	v_add_f32_e32 v87, 1.0, v90
	v_rcp_f32_e32 v87, v87
	v_mul_f32_e32 v86, v91, v86
	v_mul_f32_e32 v90, 0xbfb8aa3b, v92
	v_mul_f32_e32 v91, v86, v83
	v_mul_f32_e32 v83, v96, v87
	v_exp_f32_e32 v90, v90
	v_mul_f32_e32 v83, v83, v88
	v_mul_f32_e32 v87, 0xbfb8aa3b, v97
	v_mul_f32_e32 v88, 0xbfb8aa3b, v93
	v_exp_f32_e32 v87, v87
	v_exp_f32_e32 v88, v88
	v_add_f32_e32 v86, 1.0, v90
	v_rcp_f32_e32 v86, v86
	v_add_f32_e32 v87, 1.0, v87
	v_add_f32_e32 v88, 1.0, v88
	v_rcp_f32_e32 v87, v87
	v_rcp_f32_e32 v88, v88
	v_mul_f32_e32 v86, v92, v86
	v_mul_f32_e32 v90, v86, v84
	v_mul_f32_e32 v84, v97, v87
	v_mul_f32_e32 v86, v93, v88
	v_mul_f32_e32 v84, v84, v89
	v_mul_f32_e32 v85, v86, v85
	v_lshl_add_u64 v[86:87], v[98:99], 0, v[114:115]
	v_cvt_pk_bf16_f32 v82, v94, v82
	v_cvt_pk_bf16_f32 v83, v83, v84
	v_cvt_pk_bf16_f32 v84, v101, v91
	v_cvt_pk_bf16_f32 v85, v90, v85
	global_store_dwordx4 v[86:87], v[82:85], off
	s_nop 1
	v_mul_f32_e32 v82, 0xbfb8aa3b, v78
	v_exp_f32_e32 v82, v82
	v_mul_f32_e32 v83, 0xbfb8aa3b, v74
	v_exp_f32_e32 v83, v83
	v_or_b32_e32 v84, 48, v147
	v_add_f32_e32 v82, 1.0, v82
	v_rcp_f32_e32 v85, v82
	v_add_f32_e32 v82, 1.0, v83
	v_rcp_f32_e32 v86, v82
	v_mad_i64_i32 v[82:83], s[62:63], v84, s90, v[134:135]
	v_mul_f32_e32 v78, v78, v85
	v_mul_f32_e32 v78, v78, v70
	v_mul_f32_e32 v70, v74, v86
	v_mul_f32_e32 v74, 0xbfb8aa3b, v79
	v_exp_f32_e32 v74, v74
	v_mul_f32_e32 v84, 0xbfb8aa3b, v75
	v_mul_f32_e32 v85, v70, v66
	v_exp_f32_e32 v84, v84
	v_add_f32_e32 v66, 1.0, v74
	v_rcp_f32_e32 v66, v66
	v_mul_f32_e32 v74, 0xbfb8aa3b, v80
	v_exp_f32_e32 v74, v74
	v_add_f32_e32 v70, 1.0, v84
	v_mul_f32_e32 v66, v79, v66
	v_rcp_f32_e32 v70, v70
	v_mul_f32_e32 v66, v66, v71
	v_add_f32_e32 v71, 1.0, v74
	v_rcp_f32_e32 v71, v71
	v_mul_f32_e32 v70, v75, v70
	v_mul_f32_e32 v74, 0xbfb8aa3b, v76
	v_mul_f32_e32 v75, v70, v67
	v_mul_f32_e32 v67, v80, v71
	v_exp_f32_e32 v74, v74
	v_mul_f32_e32 v67, v67, v72
	v_mul_f32_e32 v71, 0xbfb8aa3b, v81
	v_mul_f32_e32 v72, 0xbfb8aa3b, v77
	v_exp_f32_e32 v71, v71
	v_exp_f32_e32 v72, v72
	v_add_f32_e32 v70, 1.0, v74
	v_rcp_f32_e32 v70, v70
	v_add_f32_e32 v71, 1.0, v71
	v_add_f32_e32 v72, 1.0, v72
	v_rcp_f32_e32 v71, v71
	v_rcp_f32_e32 v72, v72
	v_mul_f32_e32 v70, v76, v70
	v_mul_f32_e32 v74, v70, v68
	v_mul_f32_e32 v68, v81, v71
	v_mul_f32_e32 v70, v77, v72
	v_mul_f32_e32 v68, v68, v73
	v_mul_f32_e32 v69, v70, v69
	v_lshl_add_u64 v[70:71], v[82:83], 0, v[114:115]
	v_cvt_pk_bf16_f32 v66, v78, v66
	v_cvt_pk_bf16_f32 v67, v67, v68
	v_cvt_pk_bf16_f32 v68, v85, v75
	v_cvt_pk_bf16_f32 v69, v74, v69
	global_store_dwordx4 v[70:71], v[66:69], off
	s_nop 1
	v_mul_f32_e32 v66, 0xbfb8aa3b, v62
	v_exp_f32_e32 v66, v66
	v_mul_f32_e32 v67, 0xbfb8aa3b, v58
	v_exp_f32_e32 v67, v67
	v_add_u32_e32 v68, 0x80, v147
	v_add_f32_e32 v66, 1.0, v66
	v_rcp_f32_e32 v69, v66
	v_add_f32_e32 v66, 1.0, v67
	v_rcp_f32_e32 v70, v66
	v_mad_i64_i32 v[66:67], s[62:63], v68, s90, v[134:135]
	v_mul_f32_e32 v62, v62, v69
	v_mul_f32_e32 v62, v62, v54
	v_mul_f32_e32 v54, v58, v70
	v_mul_f32_e32 v58, 0xbfb8aa3b, v63
	v_exp_f32_e32 v58, v58
; __device__ __forceinline__ unsigned cvt_pk_bf16(float lo, float hi) { unsigned r; asm volatile("v_cvt_pk_bf16_f32 %0, %1, %2" : "=v"(r) : "v"(lo), "v"(hi)); return r; }
; __device__ __forceinline__ float silu_f(float x) { return x * sigmoid_f(x); }
; #define PG8_WAIT_V(n) asm volatile("s_waitcnt vmcnt(" #n ")" ::: "memory")
; #define PG8_BAR __builtin_amdgcn_s_barrier()
;     __device__ __forceinline__ void operator()(const f32x4 (&acc)[2][2][4][2], const Unit& u, int wr, int wc, int fr, int fq) const {
;         const int row0 = u.pm * BM + wr * 64 + fr, col0 = u.pn * HALF + wc * 32 + 8 * fq;
; #pragma unroll
;         for (int ai = 0; ai < 2; ++ai)
; #pragma unroll
;             for (int m = 0; m < 4; ++m) { bf16_t* rowp = O + (size_t)(row0 + ai * HALF + m * 16) * ldc + col0;
;                 const f32x4 g0 = acc[ai][0][m][0], g1 = acc[ai][0][m][1], u0 = acc[ai][1][m][0], u1 = acc[ai][1][m][1];
;                 f32x4 v0, v1;
; #pragma unroll
;                 for (int j = 0; j < 4; ++j) { v0[j] = silu_f(g0[j]) * u0[j]; v1[j] = silu_f(g1[j]) * u1[j]; }
;                 u32x4 w; w.x = cvt_pk_bf16(v0[0], v0[1]); w.y = cvt_pk_bf16(v0[2], v0[3]); w.z = cvt_pk_bf16(v1[0], v1[1]); w.w = cvt_pk_bf16(v1[2], v1[3]);
;                 *(u32x4*)rowp = w; }
; template <class Epi, class Sched, bool ALIGN_EPI = false, bool SP2 = false>
; __device__ __forceinline__ void gemm_phase(PG8_LAS unsigned char* lds, const Gemm g, const Sched& S, const Epi& E) {
;     ...
;         if constexpr (!Epi::AFTER_DRAIN) { E(acc, cur, wr, wc, fr, fq); S.done(cur); }
;         if (!has_next) break;
; #pragma unroll
;         for (int a = 0; a < 2; ++a)
; #pragma unroll
;             for (int b = 0; b < 2; ++b)
; #pragma unroll
;                 for (int m = 0; m < 4; ++m)
; #pragma unroll
;                     for (int n = 0; n < 2; ++n) acc[a][b][m][n] = (f32x4){0.f, 0.f, 0.f, 0.f};
;         cur = nxt; cA = nA; cB = nB; ++ui;
;         if constexpr (ALIGN_EPI) { if (wr == 1) PG8_BAR; }
;     }
;     PG8_WAIT_V(0);
;     if constexpr (!ALIGN_EPI) { if (wr == 0) PG8_BAR; }
	v_mul_f32_e32 v68, 0xbfb8aa3b, v59
	v_mul_f32_e32 v69, v54, v50
	v_exp_f32_e32 v68, v68
	v_add_f32_e32 v50, 1.0, v58
	v_rcp_f32_e32 v50, v50
	v_mul_f32_e32 v58, 0xbfb8aa3b, v64
	v_exp_f32_e32 v58, v58
	v_add_f32_e32 v54, 1.0, v68
	v_mul_f32_e32 v50, v63, v50
	v_rcp_f32_e32 v54, v54
	v_mul_f32_e32 v50, v50, v55
	v_add_f32_e32 v55, 1.0, v58
	v_rcp_f32_e32 v55, v55
	v_mul_f32_e32 v54, v59, v54
	v_mul_f32_e32 v58, 0xbfb8aa3b, v60
	v_mul_f32_e32 v59, v54, v51
	v_mul_f32_e32 v51, v64, v55
	v_exp_f32_e32 v58, v58
	v_mul_f32_e32 v51, v51, v56
	v_mul_f32_e32 v55, 0xbfb8aa3b, v65
	v_mul_f32_e32 v56, 0xbfb8aa3b, v61
	v_exp_f32_e32 v55, v55
	v_exp_f32_e32 v56, v56
	v_add_f32_e32 v54, 1.0, v58
	v_rcp_f32_e32 v54, v54
	v_add_f32_e32 v55, 1.0, v55
	v_add_f32_e32 v56, 1.0, v56
	v_rcp_f32_e32 v55, v55
	v_rcp_f32_e32 v56, v56
	v_mul_f32_e32 v54, v60, v54
	v_mul_f32_e32 v58, v54, v52
	v_mul_f32_e32 v52, v65, v55
	v_mul_f32_e32 v54, v61, v56
	v_mul_f32_e32 v52, v52, v57
	v_mul_f32_e32 v53, v54, v53
	v_lshl_add_u64 v[54:55], v[66:67], 0, v[114:115]
	v_cvt_pk_bf16_f32 v50, v62, v50
	v_cvt_pk_bf16_f32 v51, v51, v52
	v_cvt_pk_bf16_f32 v52, v69, v59
	v_cvt_pk_bf16_f32 v53, v58, v53
	global_store_dwordx4 v[54:55], v[50:53], off
	s_nop 1
	v_mul_f32_e32 v50, 0xbfb8aa3b, v46
	v_exp_f32_e32 v50, v50
	v_mul_f32_e32 v51, 0xbfb8aa3b, v42
	v_exp_f32_e32 v51, v51
	v_add_u32_e32 v52, 0x90, v147
	v_add_f32_e32 v50, 1.0, v50
	v_rcp_f32_e32 v53, v50
	v_add_f32_e32 v50, 1.0, v51
	v_rcp_f32_e32 v54, v50
	v_mad_i64_i32 v[50:51], s[62:63], v52, s90, v[134:135]
	v_mul_f32_e32 v46, v46, v53
	v_mul_f32_e32 v46, v46, v38
	v_mul_f32_e32 v38, v42, v54
	v_mul_f32_e32 v42, 0xbfb8aa3b, v47
	v_exp_f32_e32 v42, v42
	v_mul_f32_e32 v52, 0xbfb8aa3b, v43
	v_mul_f32_e32 v53, v38, v34
	v_exp_f32_e32 v52, v52
	v_add_f32_e32 v34, 1.0, v42
	v_rcp_f32_e32 v34, v34
	v_mul_f32_e32 v42, 0xbfb8aa3b, v48
	v_exp_f32_e32 v42, v42
	v_add_f32_e32 v38, 1.0, v52
	v_mul_f32_e32 v34, v47, v34
	v_rcp_f32_e32 v38, v38
	v_mul_f32_e32 v34, v34, v39
	v_add_f32_e32 v39, 1.0, v42
	v_rcp_f32_e32 v39, v39
	v_mul_f32_e32 v38, v43, v38
	v_mul_f32_e32 v42, 0xbfb8aa3b, v44
	v_mul_f32_e32 v43, v38, v35
	v_mul_f32_e32 v35, v48, v39
	v_exp_f32_e32 v42, v42
	v_mul_f32_e32 v35, v35, v40
	v_mul_f32_e32 v39, 0xbfb8aa3b, v49
	v_mul_f32_e32 v40, 0xbfb8aa3b, v45
	v_exp_f32_e32 v39, v39
	v_exp_f32_e32 v40, v40
	v_add_f32_e32 v38, 1.0, v42
	v_rcp_f32_e32 v38, v38
	v_add_f32_e32 v39, 1.0, v39
	v_add_f32_e32 v40, 1.0, v40
	v_rcp_f32_e32 v39, v39
	v_rcp_f32_e32 v40, v40
	v_mul_f32_e32 v38, v44, v38
	v_mul_f32_e32 v42, v38, v36
	v_mul_f32_e32 v36, v49, v39
	v_mul_f32_e32 v38, v45, v40
	v_mul_f32_e32 v36, v36, v41
	v_mul_f32_e32 v37, v38, v37
	v_lshl_add_u64 v[38:39], v[50:51], 0, v[114:115]
	v_cvt_pk_bf16_f32 v34, v46, v34
	v_cvt_pk_bf16_f32 v35, v35, v36
	v_cvt_pk_bf16_f32 v36, v53, v43
	v_cvt_pk_bf16_f32 v37, v42, v37
	global_store_dwordx4 v[38:39], v[34:37], off
	s_nop 1
	v_mul_f32_e32 v34, 0xbfb8aa3b, v30
	v_exp_f32_e32 v34, v34
	v_mul_f32_e32 v35, 0xbfb8aa3b, v26
	v_exp_f32_e32 v35, v35
	v_add_u32_e32 v36, 0xa0, v147
	v_add_f32_e32 v34, 1.0, v34
	v_rcp_f32_e32 v37, v34
	v_add_f32_e32 v34, 1.0, v35
	v_rcp_f32_e32 v38, v34
	v_mad_i64_i32 v[34:35], s[62:63], v36, s90, v[134:135]
	v_mul_f32_e32 v30, v30, v37
	v_mul_f32_e32 v30, v30, v22
	v_mul_f32_e32 v22, v26, v38
	v_mul_f32_e32 v26, 0xbfb8aa3b, v31
	v_exp_f32_e32 v26, v26
	v_mul_f32_e32 v36, 0xbfb8aa3b, v27
	v_mul_f32_e32 v37, v22, v18
	v_exp_f32_e32 v36, v36
	v_add_f32_e32 v18, 1.0, v26
	v_rcp_f32_e32 v18, v18
	v_mul_f32_e32 v26, 0xbfb8aa3b, v32
	v_exp_f32_e32 v26, v26
	v_add_f32_e32 v22, 1.0, v36
	v_mul_f32_e32 v18, v31, v18
	v_rcp_f32_e32 v22, v22
	v_mul_f32_e32 v18, v18, v23
	v_add_f32_e32 v23, 1.0, v26
	v_rcp_f32_e32 v23, v23
	v_mul_f32_e32 v22, v27, v22
	v_mul_f32_e32 v26, 0xbfb8aa3b, v28
	v_mul_f32_e32 v27, v22, v19
	v_mul_f32_e32 v19, v32, v23
	v_exp_f32_e32 v26, v26
	v_mul_f32_e32 v19, v19, v24
	v_mul_f32_e32 v23, 0xbfb8aa3b, v33
	v_mul_f32_e32 v24, 0xbfb8aa3b, v29
	v_exp_f32_e32 v23, v23
	v_exp_f32_e32 v24, v24
	v_add_f32_e32 v22, 1.0, v26
	v_rcp_f32_e32 v22, v22
	v_add_f32_e32 v23, 1.0, v23
	v_add_f32_e32 v24, 1.0, v24
	v_rcp_f32_e32 v23, v23
	v_rcp_f32_e32 v24, v24
	v_mul_f32_e32 v22, v28, v22
	v_mul_f32_e32 v26, v22, v20
	v_mul_f32_e32 v20, v33, v23
	v_mul_f32_e32 v22, v29, v24
	v_mul_f32_e32 v20, v20, v25
	v_mul_f32_e32 v21, v22, v21
	v_lshl_add_u64 v[22:23], v[34:35], 0, v[114:115]
	v_cvt_pk_bf16_f32 v18, v30, v18
	v_cvt_pk_bf16_f32 v19, v19, v20
	v_cvt_pk_bf16_f32 v20, v37, v27
	v_cvt_pk_bf16_f32 v21, v26, v21
	global_store_dwordx4 v[22:23], v[18:21], off
	s_nop 1
	v_mul_f32_e32 v18, 0xbfb8aa3b, v14
	v_exp_f32_e32 v18, v18
	v_mul_f32_e32 v19, 0xbfb8aa3b, v10
	v_exp_f32_e32 v19, v19
	v_add_u32_e32 v20, 0xb0, v147
	v_add_f32_e32 v18, 1.0, v18
	v_rcp_f32_e32 v21, v18
	v_add_f32_e32 v18, 1.0, v19
	v_rcp_f32_e32 v22, v18
	v_mad_i64_i32 v[18:19], s[62:63], v20, s90, v[134:135]
	v_mul_f32_e32 v14, v14, v21
	v_mul_f32_e32 v14, v14, v6
	v_mul_f32_e32 v6, v10, v22
	v_mul_f32_e32 v10, 0xbfb8aa3b, v15
	v_exp_f32_e32 v10, v10
	v_mul_f32_e32 v20, 0xbfb8aa3b, v11
	v_mul_f32_e32 v21, v6, v2
	v_exp_f32_e32 v20, v20
	v_add_f32_e32 v2, 1.0, v10
	v_rcp_f32_e32 v2, v2
	v_mul_f32_e32 v10, 0xbfb8aa3b, v16
	v_exp_f32_e32 v10, v10
	v_add_f32_e32 v6, 1.0, v20
	v_mul_f32_e32 v2, v15, v2
	v_rcp_f32_e32 v6, v6
	v_mul_f32_e32 v2, v2, v7
	v_add_f32_e32 v7, 1.0, v10
	v_rcp_f32_e32 v7, v7
	v_mul_f32_e32 v6, v11, v6
	v_mul_f32_e32 v10, 0xbfb8aa3b, v12
	v_mul_f32_e32 v11, v6, v3
	v_mul_f32_e32 v3, v16, v7
	v_exp_f32_e32 v10, v10
	v_mul_f32_e32 v3, v3, v8
	v_mul_f32_e32 v7, 0xbfb8aa3b, v17
	v_mul_f32_e32 v8, 0xbfb8aa3b, v13
	v_exp_f32_e32 v7, v7
	v_exp_f32_e32 v8, v8
	v_add_f32_e32 v6, 1.0, v10
	v_rcp_f32_e32 v6, v6
	v_add_f32_e32 v7, 1.0, v7
	v_add_f32_e32 v8, 1.0, v8
	v_rcp_f32_e32 v7, v7
	v_rcp_f32_e32 v8, v8
	v_mul_f32_e32 v6, v12, v6
	v_mul_f32_e32 v10, v6, v4
	v_mul_f32_e32 v4, v17, v7
	v_mul_f32_e32 v6, v13, v8
	v_mul_f32_e32 v4, v4, v9
	v_mul_f32_e32 v5, v6, v5
	v_lshl_add_u64 v[6:7], v[18:19], 0, v[114:115]
	s_mov_b64 s[62:63], s[16:17]
	v_cvt_pk_bf16_f32 v2, v14, v2
	v_cvt_pk_bf16_f32 v3, v3, v4
	v_cvt_pk_bf16_f32 v4, v21, v11
	v_cvt_pk_bf16_f32 v5, v10, v5
	global_store_dwordx4 v[6:7], v[2:5], off
	s_cbranch_vccz .LBB0_135
	s_waitcnt vmcnt(0)
	s_cmpk_gt_u32 s3, 0xff
	s_cbranch_scc1 .LBB0_142
	s_barrier

; #define PG8_STAGE(bufoff, gbase, voff) do { _Pragma("unroll") for (int _i = 0; _i < 2; ++_i) \
;         asm volatile("s_mov_b32 m0, %2\n\ts_nop 0\n\tglobal_load_lds_dwordx4 %0, %1" :: "v"((voff)[_i]), "s"((const char*)(gbase)), "s"(ldsbase + (unsigned)(bufoff) + ldsw + (unsigned)_i * 8192u) : "memory", "m0"); } while (0)
; #define PG8_LDA(dst, b, h) do { _Pragma("unroll") for (int m = 0; m < 4; ++m) _Pragma("unroll") for (int k = 0; k < 2; ++k) dst[m][k] = *(const PG8_LAS bf16x8*)(lds + PG8_SA(b, h) + aoff + m * 2048 + k * 1024); } while (0)
; #define PG8_LDB(dst, b, h) do { _Pragma("unroll") for (int n = 0; n < 2; ++n) _Pragma("unroll") for (int k = 0; k < 2; ++k) dst[n][k] = *(const PG8_LAS bf16x8*)(lds + PG8_SB(b, h) + boff + n * 2048 + k * 1024); } while (0)
; #define PG8_MMA(ai, bj, At, Bt) do { __builtin_amdgcn_s_setprio(1); _Pragma("unroll") for (int m = 0; m < 4; ++m) _Pragma("unroll") for (int n = 0; n < 2; ++n) _Pragma("unroll") for (int k = 0; k < 2; ++k) \
;         acc[ai][bj][m][n] = __builtin_amdgcn_mfma_f32_16x16x32_bf16(Bt[n][k], At[m][k], acc[ai][bj][m][n], 0, 0, 0); __builtin_amdgcn_s_setprio(0); } while (0)
; template <class Epi, class Sched, bool ALIGN_EPI = false, bool SP2 = false>
; __device__ __forceinline__ void gemm_phase(PG8_LAS unsigned char* lds, const Gemm g, const Sched& S, const Epi& E) {
;     ...
;             const bool last = (t == nt - 2);
;             const char* a1 = cA + (size_t)(t + 1) * kstep;
;             const char* a2 = last ? nA : cA + (size_t)(t + 2) * kstep; const char* b2 = last ? nB : cB + (size_t)(t + 2) * kstep;
;             const char* a3 = a2 + kstep; const char* b3 = b2 + kstep;
;             if (last && has_next) S.a_ready(nxt);
;             if constexpr (epi_has_mid<Epi>::value) { if (t == Epi::MID_T) E.mid(acc, cur, wr, wc, fr, fq); }
;             if constexpr (SP2) {
;             PG8_LDB(B0, 0, 0); PG8_LDB(B1, 0, 1); PG8_SCHED; PG8_LDA(At, 0, 0); PG8_STAGE(PG8_SA(1, 1), a1 + hstep, voffA);
;             PG8_WAIT_V(8); PG8_WAIT_L(0); PG8_BAR; PG8_MMA(0, 0, At, B0); PG8_MMA(0, 1, At, B1); PG8_BAR; PG8_SCHED;
;             PG8_LDA(At, 0, 1); PG8_STAGE(PG8_SB(0, 0), b2, voffB); PG8_STAGE(PG8_SB(0, 1), b2 + hstep, voffB); PG8_STAGE(PG8_SA(0, 0), a2, voffA);
;             PG8_WAIT_V(8); PG8_WAIT_L(0); PG8_BAR; PG8_MMA(1, 0, At, B0); PG8_MMA(1, 1, At, B1); PG8_BAR; PG8_SCHED;
.LBB0_234:
	ds_read_b128 v[134:137], v145
	ds_read_b128 v[152:155], v145 offset:1024
	ds_read_b128 v[156:159], v145 offset:2048
	ds_read_b128 v[160:163], v145 offset:3072
	ds_read_b128 v[164:167], v146
	ds_read_b128 v[168:171], v146 offset:1024
	ds_read_b128 v[172:175], v146 offset:2048
	ds_read_b128 v[176:179], v146 offset:3072
	s_cmpk_eq_i32 s57, 0xa8
	s_cselect_b32 s76, s4, s53
	s_cselect_b32 s77, s5, s54
	s_cselect_b32 s66, s46, s55
	s_cselect_b32 s67, s47, s56
	s_add_u32 s62, s76, 0x80
	s_addc_u32 s63, s77, 0
	ds_read_b128 v[180:183], v147
	ds_read_b128 v[184:187], v147 offset:1024
	ds_read_b128 v[188:191], v147 offset:2048
	ds_read_b128 v[192:195], v147 offset:3072
	ds_read_b128 v[196:199], v147 offset:4096
	ds_read_b128 v[200:203], v147 offset:5120
	ds_read_b128 v[204:207], v147 offset:6144
	ds_read_b128 v[208:211], v147 offset:7168
	s_mov_b32 m0, s94
	s_nop 0
	global_load_lds_dwordx4 v1, s[50:51]
	s_nop 0
	s_mov_b32 m0, s95
	s_nop 0
	global_load_lds_dwordx4 v141, s[50:51]
	s_waitcnt vmcnt(8)
	s_waitcnt lgkmcnt(0)
	s_barrier
	s_setprio 1
	s_waitcnt lgkmcnt(7)
	v_mfma_f32_16x16x32_bf16 v[126:129], v[134:137], v[180:183], v[126:129]
	v_mfma_f32_16x16x32_bf16 v[122:125], v[156:159], v[180:183], v[122:125]
	s_waitcnt lgkmcnt(5)
	v_mfma_f32_16x16x32_bf16 v[110:113], v[134:137], v[188:191], v[110:113]
	v_mfma_f32_16x16x32_bf16 v[106:109], v[156:159], v[188:191], v[106:109]
	s_waitcnt lgkmcnt(3)
	v_mfma_f32_16x16x32_bf16 v[94:97], v[134:137], v[196:199], v[94:97]
	v_mfma_f32_16x16x32_bf16 v[90:93], v[156:159], v[196:199], v[90:93]
	s_waitcnt lgkmcnt(1)
	v_mfma_f32_16x16x32_bf16 v[78:81], v[134:137], v[204:207], v[78:81]
	v_mfma_f32_16x16x32_bf16 v[74:77], v[156:159], v[204:207], v[74:77]
	v_mfma_f32_16x16x32_bf16 v[126:129], v[152:155], v[184:187], v[126:129]
	v_mfma_f32_16x16x32_bf16 v[122:125], v[160:163], v[184:187], v[122:125]
	v_mfma_f32_16x16x32_bf16 v[110:113], v[152:155], v[192:195], v[110:113]
	v_mfma_f32_16x16x32_bf16 v[106:109], v[160:163], v[192:195], v[106:109]
	v_mfma_f32_16x16x32_bf16 v[94:97], v[152:155], v[200:203], v[94:97]
	v_mfma_f32_16x16x32_bf16 v[90:93], v[160:163], v[200:203], v[90:93]
	s_waitcnt lgkmcnt(0)
	v_mfma_f32_16x16x32_bf16 v[78:81], v[152:155], v[208:211], v[78:81]
	v_mfma_f32_16x16x32_bf16 v[74:77], v[160:163], v[208:211], v[74:77]
	s_setprio 0
	s_setprio 1
	v_mfma_f32_16x16x32_bf16 v[118:121], v[164:167], v[180:183], v[118:121]
	v_mfma_f32_16x16x32_bf16 v[114:117], v[172:175], v[180:183], v[114:117]
	v_mfma_f32_16x16x32_bf16 v[102:105], v[164:167], v[188:191], v[102:105]
	v_mfma_f32_16x16x32_bf16 v[98:101], v[172:175], v[188:191], v[98:101]
	v_mfma_f32_16x16x32_bf16 v[86:89], v[164:167], v[196:199], v[86:89]
	v_mfma_f32_16x16x32_bf16 v[82:85], v[172:175], v[196:199], v[82:85]
	v_mfma_f32_16x16x32_bf16 v[70:73], v[164:167], v[204:207], v[70:73]
	v_mfma_f32_16x16x32_bf16 v[66:69], v[172:175], v[204:207], v[66:69]
	v_mfma_f32_16x16x32_bf16 v[118:121], v[168:171], v[184:187], v[118:121]
	v_mfma_f32_16x16x32_bf16 v[114:117], v[176:179], v[184:187], v[114:117]
	v_mfma_f32_16x16x32_bf16 v[102:105], v[168:171], v[192:195], v[102:105]
	v_mfma_f32_16x16x32_bf16 v[98:101], v[176:179], v[192:195], v[98:101]
	v_mfma_f32_16x16x32_bf16 v[86:89], v[168:171], v[200:203], v[86:89]
	v_mfma_f32_16x16x32_bf16 v[82:85], v[176:179], v[200:203], v[82:85]
	v_mfma_f32_16x16x32_bf16 v[70:73], v[168:171], v[208:211], v[70:73]
	s_setprio 2
	s_barrier
	v_mfma_f32_16x16x32_bf16 v[66:69], v[176:179], v[208:211], v[66:69]
	s_setprio 0
	ds_read_b128 v[180:183], v147 offset:16384
	ds_read_b128 v[184:187], v147 offset:17408
	ds_read_b128 v[188:191], v147 offset:18432
	ds_read_b128 v[192:195], v147 offset:19456
	ds_read_b128 v[196:199], v147 offset:20480
	ds_read_b128 v[200:203], v147 offset:21504
	ds_read_b128 v[204:207], v147 offset:22528
	ds_read_b128 v[208:211], v147 offset:23552
	s_mov_b32 m0, s64
	s_nop 0
	global_load_lds_dwordx4 v140, s[66:67]
	s_add_u32 s58, s66, 0x2b0000
	s_mov_b32 m0, s65
	s_nop 0
	global_load_lds_dwordx4 v142, s[66:67]
	s_addc_u32 s59, s67, 0
	s_mov_b32 m0, s82
	s_nop 0
	global_load_lds_dwordx4 v140, s[58:59]
	s_nop 0
	s_mov_b32 m0, s83
	s_nop 0
	global_load_lds_dwordx4 v142, s[58:59]
	s_nop 0
	s_mov_b32 m0, s35
	s_nop 0
	global_load_lds_dwordx4 v1, s[76:77]
	s_nop 0
	s_mov_b32 m0, s84
	s_nop 0
	global_load_lds_dwordx4 v141, s[76:77]
	s_waitcnt vmcnt(8)
	s_waitcnt lgkmcnt(0)
	s_barrier
	s_setprio 1
	s_waitcnt lgkmcnt(7)
	v_mfma_f32_16x16x32_bf16 v[62:65], v[134:137], v[180:183], v[62:65]
	v_mfma_f32_16x16x32_bf16 v[58:61], v[156:159], v[180:183], v[58:61]
	s_waitcnt lgkmcnt(5)
	v_mfma_f32_16x16x32_bf16 v[46:49], v[134:137], v[188:191], v[46:49]
	v_mfma_f32_16x16x32_bf16 v[42:45], v[156:159], v[188:191], v[42:45]
	s_waitcnt lgkmcnt(3)
	v_mfma_f32_16x16x32_bf16 v[30:33], v[134:137], v[196:199], v[30:33]
	v_mfma_f32_16x16x32_bf16 v[26:29], v[156:159], v[196:199], v[26:29]
	s_waitcnt lgkmcnt(1)
	v_mfma_f32_16x16x32_bf16 v[14:17], v[134:137], v[204:207], v[14:17]
	v_mfma_f32_16x16x32_bf16 v[10:13], v[156:159], v[204:207], v[10:13]
	v_mfma_f32_16x16x32_bf16 v[62:65], v[152:155], v[184:187], v[62:65]
	v_mfma_f32_16x16x32_bf16 v[58:61], v[160:163], v[184:187], v[58:61]
	v_mfma_f32_16x16x32_bf16 v[46:49], v[152:155], v[192:195], v[46:49]
	v_mfma_f32_16x16x32_bf16 v[42:45], v[160:163], v[192:195], v[42:45]
	v_mfma_f32_16x16x32_bf16 v[30:33], v[152:155], v[200:203], v[30:33]
	v_mfma_f32_16x16x32_bf16 v[26:29], v[160:163], v[200:203], v[26:29]
	s_waitcnt lgkmcnt(0)
	v_mfma_f32_16x16x32_bf16 v[14:17], v[152:155], v[208:211], v[14:17]
	v_mfma_f32_16x16x32_bf16 v[10:13], v[160:163], v[208:211], v[10:13]
	s_setprio 0
	s_setprio 1
	v_mfma_f32_16x16x32_bf16 v[54:57], v[164:167], v[180:183], v[54:57]
	v_mfma_f32_16x16x32_bf16 v[50:53], v[172:175], v[180:183], v[50:53]
	v_mfma_f32_16x16x32_bf16 v[38:41], v[164:167], v[188:191], v[38:41]
	v_mfma_f32_16x16x32_bf16 v[34:37], v[172:175], v[188:191], v[34:37]
	v_mfma_f32_16x16x32_bf16 v[22:25], v[164:167], v[196:199], v[22:25]
	v_mfma_f32_16x16x32_bf16 v[18:21], v[172:175], v[196:199], v[18:21]
	v_mfma_f32_16x16x32_bf16 v[6:9], v[164:167], v[204:207], v[6:9]
	v_mfma_f32_16x16x32_bf16 v[2:5], v[172:175], v[204:207], v[2:5]
	v_mfma_f32_16x16x32_bf16 v[54:57], v[168:171], v[184:187], v[54:57]
	v_mfma_f32_16x16x32_bf16 v[50:53], v[176:179], v[184:187], v[50:53]
	v_mfma_f32_16x16x32_bf16 v[38:41], v[168:171], v[192:195], v[38:41]
	v_mfma_f32_16x16x32_bf16 v[34:37], v[176:179], v[192:195], v[34:37]
	v_mfma_f32_16x16x32_bf16 v[22:25], v[168:171], v[200:203], v[22:25]
	v_mfma_f32_16x16x32_bf16 v[18:21], v[176:179], v[200:203], v[18:21]
	v_mfma_f32_16x16x32_bf16 v[6:9], v[168:171], v[208:211], v[6:9]
	s_setprio 2
	s_barrier
; #define PG8_STAGE(bufoff, gbase, voff) do { _Pragma("unroll") for (int _i = 0; _i < 2; ++_i) \
;         asm volatile("s_mov_b32 m0, %2\n\ts_nop 0\n\tglobal_load_lds_dwordx4 %0, %1" :: "v"((voff)[_i]), "s"((const char*)(gbase)), "s"(ldsbase + (unsigned)(bufoff) + ldsw + (unsigned)_i * 8192u) : "memory", "m0"); } while (0)
; #define PG8_LDA(dst, b, h) do { _Pragma("unroll") for (int m = 0; m < 4; ++m) _Pragma("unroll") for (int k = 0; k < 2; ++k) dst[m][k] = *(const PG8_LAS bf16x8*)(lds + PG8_SA(b, h) + aoff + m * 2048 + k * 1024); } while (0)
; #define PG8_LDB(dst, b, h) do { _Pragma("unroll") for (int n = 0; n < 2; ++n) _Pragma("unroll") for (int k = 0; k < 2; ++k) dst[n][k] = *(const PG8_LAS bf16x8*)(lds + PG8_SB(b, h) + boff + n * 2048 + k * 1024); } while (0)
; #define PG8_MMA(ai, bj, At, Bt) do { __builtin_amdgcn_s_setprio(1); _Pragma("unroll") for (int m = 0; m < 4; ++m) _Pragma("unroll") for (int n = 0; n < 2; ++n) _Pragma("unroll") for (int k = 0; k < 2; ++k) \
;         acc[ai][bj][m][n] = __builtin_amdgcn_mfma_f32_16x16x32_bf16(Bt[n][k], At[m][k], acc[ai][bj][m][n], 0, 0, 0); __builtin_amdgcn_s_setprio(0); } while (0)
; #define PG8_WAIT_V(n) asm volatile("s_waitcnt vmcnt(" #n ")" ::: "memory")
; #define PG8_WAIT_L(n) asm volatile("s_waitcnt lgkmcnt(" #n ")" ::: "memory")
; #define PG8_BAR __builtin_amdgcn_s_barrier()
; #define PG8_SCHED __builtin_amdgcn_sched_barrier(0)
; template <class Epi, class Sched, bool ALIGN_EPI = false, bool SP2 = false>
; __device__ __forceinline__ void gemm_phase(PG8_LAS unsigned char* lds, const Gemm g, const Sched& S, const Epi& E) {
;     ...
;             PG8_WAIT_V(8); PG8_WAIT_L(0); PG8_BAR; PG8_MMA(1, 0, At, B0); PG8_MMA(1, 1, At, B1); PG8_BAR; PG8_SCHED;
;             PG8_LDB(B0, 1, 0); PG8_LDB(B1, 1, 1); PG8_SCHED; PG8_LDA(At, 1, 0); PG8_STAGE(PG8_SA(0, 1), a2 + hstep, voffA);
;             PG8_WAIT_V(8); PG8_WAIT_L(0); PG8_BAR; PG8_MMA(0, 0, At, B0); PG8_MMA(0, 1, At, B1); PG8_BAR; PG8_SCHED;
	v_mfma_f32_16x16x32_bf16 v[2:5], v[176:179], v[208:211], v[2:5]
	s_setprio 0
	ds_read_b128 v[134:137], v148
	ds_read_b128 v[152:155], v148 offset:1024
	ds_read_b128 v[156:159], v148 offset:2048
	ds_read_b128 v[160:163], v148 offset:3072
	ds_read_b128 v[164:167], v149
	ds_read_b128 v[168:171], v149 offset:1024
	ds_read_b128 v[172:175], v149 offset:2048
	ds_read_b128 v[176:179], v149 offset:3072
	ds_read_b128 v[180:183], v147 offset:32768
	ds_read_b128 v[184:187], v147 offset:33792
	ds_read_b128 v[188:191], v147 offset:34816
	ds_read_b128 v[192:195], v147 offset:35840
	ds_read_b128 v[196:199], v147 offset:36864
	ds_read_b128 v[200:203], v147 offset:37888
	ds_read_b128 v[204:207], v147 offset:38912
	ds_read_b128 v[208:211], v147 offset:39936
	s_add_u32 s58, s76, 0x2b0000
	s_addc_u32 s59, s77, 0
	s_mov_b32 m0, s85
	s_nop 0
	global_load_lds_dwordx4 v1, s[58:59]
	s_nop 0
	s_mov_b32 m0, s86
	s_nop 0
	global_load_lds_dwordx4 v141, s[58:59]
	s_waitcnt vmcnt(8)
	s_waitcnt lgkmcnt(0)
	s_barrier
	s_setprio 1
	s_waitcnt lgkmcnt(7)
	v_mfma_f32_16x16x32_bf16 v[126:129], v[134:137], v[180:183], v[126:129]
	v_mfma_f32_16x16x32_bf16 v[122:125], v[156:159], v[180:183], v[122:125]
	s_waitcnt lgkmcnt(5)
	v_mfma_f32_16x16x32_bf16 v[110:113], v[134:137], v[188:191], v[110:113]
	v_mfma_f32_16x16x32_bf16 v[106:109], v[156:159], v[188:191], v[106:109]
	s_waitcnt lgkmcnt(3)
	v_mfma_f32_16x16x32_bf16 v[94:97], v[134:137], v[196:199], v[94:97]
	v_mfma_f32_16x16x32_bf16 v[90:93], v[156:159], v[196:199], v[90:93]
	s_waitcnt lgkmcnt(1)
	v_mfma_f32_16x16x32_bf16 v[78:81], v[134:137], v[204:207], v[78:81]
	v_mfma_f32_16x16x32_bf16 v[74:77], v[156:159], v[204:207], v[74:77]
	v_mfma_f32_16x16x32_bf16 v[126:129], v[152:155], v[184:187], v[126:129]
	v_mfma_f32_16x16x32_bf16 v[122:125], v[160:163], v[184:187], v[122:125]
	v_mfma_f32_16x16x32_bf16 v[110:113], v[152:155], v[192:195], v[110:113]
	v_mfma_f32_16x16x32_bf16 v[106:109], v[160:163], v[192:195], v[106:109]
	v_mfma_f32_16x16x32_bf16 v[94:97], v[152:155], v[200:203], v[94:97]
	v_mfma_f32_16x16x32_bf16 v[90:93], v[160:163], v[200:203], v[90:93]
	s_waitcnt lgkmcnt(0)
	v_mfma_f32_16x16x32_bf16 v[78:81], v[152:155], v[208:211], v[78:81]
	v_mfma_f32_16x16x32_bf16 v[74:77], v[160:163], v[208:211], v[74:77]
	s_setprio 0
	s_setprio 1
	v_mfma_f32_16x16x32_bf16 v[118:121], v[164:167], v[180:183], v[118:121]
	v_mfma_f32_16x16x32_bf16 v[114:117], v[172:175], v[180:183], v[114:117]
	v_mfma_f32_16x16x32_bf16 v[102:105], v[164:167], v[188:191], v[102:105]
	v_mfma_f32_16x16x32_bf16 v[98:101], v[172:175], v[188:191], v[98:101]
	v_mfma_f32_16x16x32_bf16 v[86:89], v[164:167], v[196:199], v[86:89]
	v_mfma_f32_16x16x32_bf16 v[82:85], v[172:175], v[196:199], v[82:85]
	v_mfma_f32_16x16x32_bf16 v[70:73], v[164:167], v[204:207], v[70:73]
	v_mfma_f32_16x16x32_bf16 v[66:69], v[172:175], v[204:207], v[66:69]
	v_mfma_f32_16x16x32_bf16 v[118:121], v[168:171], v[184:187], v[118:121]
	v_mfma_f32_16x16x32_bf16 v[114:117], v[176:179], v[184:187], v[114:117]
	v_mfma_f32_16x16x32_bf16 v[102:105], v[168:171], v[192:195], v[102:105]
	v_mfma_f32_16x16x32_bf16 v[98:101], v[176:179], v[192:195], v[98:101]
	v_mfma_f32_16x16x32_bf16 v[86:89], v[168:171], v[200:203], v[86:89]
	v_mfma_f32_16x16x32_bf16 v[82:85], v[176:179], v[200:203], v[82:85]
	v_mfma_f32_16x16x32_bf16 v[70:73], v[168:171], v[208:211], v[70:73]
	s_setprio 2
	s_barrier
; #define PG8_STAGE(bufoff, gbase, voff) do { _Pragma("unroll") for (int _i = 0; _i < 2; ++_i) \
;         asm volatile("s_mov_b32 m0, %2\n\ts_nop 0\n\tglobal_load_lds_dwordx4 %0, %1" :: "v"((voff)[_i]), "s"((const char*)(gbase)), "s"(ldsbase + (unsigned)(bufoff) + ldsw + (unsigned)_i * 8192u) : "memory", "m0"); } while (0)
; #define PG8_LDA(dst, b, h) do { _Pragma("unroll") for (int m = 0; m < 4; ++m) _Pragma("unroll") for (int k = 0; k < 2; ++k) dst[m][k] = *(const PG8_LAS bf16x8*)(lds + PG8_SA(b, h) + aoff + m * 2048 + k * 1024); } while (0)
; #define PG8_MMA(ai, bj, At, Bt) do { __builtin_amdgcn_s_setprio(1); _Pragma("unroll") for (int m = 0; m < 4; ++m) _Pragma("unroll") for (int n = 0; n < 2; ++n) _Pragma("unroll") for (int k = 0; k < 2; ++k) \
;         acc[ai][bj][m][n] = __builtin_amdgcn_mfma_f32_16x16x32_bf16(Bt[n][k], At[m][k], acc[ai][bj][m][n], 0, 0, 0); __builtin_amdgcn_s_setprio(0); } while (0)
; #define PG8_WAIT_V(n) asm volatile("s_waitcnt vmcnt(" #n ")" ::: "memory")
; #define PG8_WAIT_L(n) asm volatile("s_waitcnt lgkmcnt(" #n ")" ::: "memory")
; #define PG8_BAR __builtin_amdgcn_s_barrier()
; #define PG8_SCHED __builtin_amdgcn_sched_barrier(0)
; template <class Epi, class Sched, bool ALIGN_EPI = false, bool SP2 = false>
; __device__ __forceinline__ void gemm_phase(PG8_LAS unsigned char* lds, const Gemm g, const Sched& S, const Epi& E) {
;     ...
;             PG8_WAIT_V(8); PG8_WAIT_L(0); PG8_BAR; PG8_MMA(0, 0, At, B0); PG8_MMA(0, 1, At, B1); PG8_BAR; PG8_SCHED;
;             PG8_LDA(At, 1, 1); PG8_STAGE(PG8_SB(1, 0), b3, voffB); PG8_STAGE(PG8_SB(1, 1), b3 + hstep, voffB); PG8_STAGE(PG8_SA(1, 0), a3, voffA);
;             PG8_WAIT_V(8); PG8_WAIT_L(0); PG8_BAR; PG8_MMA(1, 0, At, B0); PG8_MMA(1, 1, At, B1); PG8_BAR; PG8_SCHED;
;     ...
;         if constexpr (ALIGN_EPI) { if (wr == 0) PG8_BAR; }
	v_mfma_f32_16x16x32_bf16 v[66:69], v[176:179], v[208:211], v[66:69]
	s_setprio 0
	ds_read_b128 v[180:183], v147 offset:49152
	ds_read_b128 v[184:187], v147 offset:50176
	ds_read_b128 v[188:191], v147 offset:51200
	ds_read_b128 v[192:195], v147 offset:52224
	ds_read_b128 v[196:199], v147 offset:53248
	ds_read_b128 v[200:203], v147 offset:54272
	ds_read_b128 v[204:207], v147 offset:55296
	ds_read_b128 v[208:211], v147 offset:56320
	s_add_u32 s58, s66, 0x80
	s_addc_u32 s59, s67, 0
	s_mov_b32 m0, s88
	s_nop 0
	global_load_lds_dwordx4 v140, s[58:59]
	s_nop 0
	s_mov_b32 m0, s89
	s_nop 0
	global_load_lds_dwordx4 v142, s[58:59]
	s_add_u32 s58, s66, 0x2b0080
	s_addc_u32 s59, s67, 0
	s_mov_b32 m0, s92
	s_nop 0
	global_load_lds_dwordx4 v140, s[58:59]
	s_nop 0
	s_mov_b32 m0, s93
	s_nop 0
	global_load_lds_dwordx4 v142, s[58:59]
	s_nop 0
	s_mov_b32 m0, s90
	s_nop 0
	global_load_lds_dwordx4 v1, s[62:63]
	s_nop 0
	s_mov_b32 m0, s91
	s_nop 0
	global_load_lds_dwordx4 v141, s[62:63]
	s_waitcnt vmcnt(8)
	s_waitcnt lgkmcnt(0)
	s_barrier
	s_setprio 1
	s_waitcnt lgkmcnt(7)
	v_mfma_f32_16x16x32_bf16 v[62:65], v[134:137], v[180:183], v[62:65]
	v_mfma_f32_16x16x32_bf16 v[58:61], v[156:159], v[180:183], v[58:61]
	s_waitcnt lgkmcnt(5)
	v_mfma_f32_16x16x32_bf16 v[46:49], v[134:137], v[188:191], v[46:49]
	v_mfma_f32_16x16x32_bf16 v[42:45], v[156:159], v[188:191], v[42:45]
	s_waitcnt lgkmcnt(3)
	v_mfma_f32_16x16x32_bf16 v[30:33], v[134:137], v[196:199], v[30:33]
	v_mfma_f32_16x16x32_bf16 v[26:29], v[156:159], v[196:199], v[26:29]
	s_waitcnt lgkmcnt(1)
	v_mfma_f32_16x16x32_bf16 v[14:17], v[134:137], v[204:207], v[14:17]
	v_mfma_f32_16x16x32_bf16 v[10:13], v[156:159], v[204:207], v[10:13]
	v_mfma_f32_16x16x32_bf16 v[62:65], v[152:155], v[184:187], v[62:65]
	v_mfma_f32_16x16x32_bf16 v[58:61], v[160:163], v[184:187], v[58:61]
	v_mfma_f32_16x16x32_bf16 v[46:49], v[152:155], v[192:195], v[46:49]
	v_mfma_f32_16x16x32_bf16 v[42:45], v[160:163], v[192:195], v[42:45]
	v_mfma_f32_16x16x32_bf16 v[30:33], v[152:155], v[200:203], v[30:33]
	v_mfma_f32_16x16x32_bf16 v[26:29], v[160:163], v[200:203], v[26:29]
	s_waitcnt lgkmcnt(0)
	v_mfma_f32_16x16x32_bf16 v[14:17], v[152:155], v[208:211], v[14:17]
	v_mfma_f32_16x16x32_bf16 v[10:13], v[160:163], v[208:211], v[10:13]
	s_setprio 0
	s_setprio 1
	v_mfma_f32_16x16x32_bf16 v[54:57], v[164:167], v[180:183], v[54:57]
	v_mfma_f32_16x16x32_bf16 v[50:53], v[172:175], v[180:183], v[50:53]
	v_mfma_f32_16x16x32_bf16 v[38:41], v[164:167], v[188:191], v[38:41]
	v_mfma_f32_16x16x32_bf16 v[34:37], v[172:175], v[188:191], v[34:37]
	v_mfma_f32_16x16x32_bf16 v[22:25], v[164:167], v[196:199], v[22:25]
	v_mfma_f32_16x16x32_bf16 v[18:21], v[172:175], v[196:199], v[18:21]
	v_mfma_f32_16x16x32_bf16 v[6:9], v[164:167], v[204:207], v[6:9]
	v_mfma_f32_16x16x32_bf16 v[2:5], v[172:175], v[204:207], v[2:5]
	v_mfma_f32_16x16x32_bf16 v[54:57], v[168:171], v[184:187], v[54:57]
	v_mfma_f32_16x16x32_bf16 v[50:53], v[176:179], v[184:187], v[50:53]
	v_mfma_f32_16x16x32_bf16 v[38:41], v[168:171], v[192:195], v[38:41]
	v_mfma_f32_16x16x32_bf16 v[34:37], v[176:179], v[192:195], v[34:37]
	v_mfma_f32_16x16x32_bf16 v[22:25], v[168:171], v[200:203], v[22:25]
	v_mfma_f32_16x16x32_bf16 v[18:21], v[176:179], v[200:203], v[18:21]
	v_mfma_f32_16x16x32_bf16 v[6:9], v[168:171], v[208:211], v[6:9]
	s_setprio 2
	s_barrier
	v_mfma_f32_16x16x32_bf16 v[2:5], v[176:179], v[208:211], v[2:5]
	s_setprio 0
	s_add_i32 s57, s57, 2
	s_add_u32 s53, s53, 0x100
	s_addc_u32 s54, s54, 0
	s_add_u32 s55, s55, 0x100
	s_addc_u32 s56, s56, 0
	s_add_u32 s50, s50, 0x100
	s_addc_u32 s51, s51, 0
	s_cmpk_gt_u32 s57, 0xa9
	s_cbranch_scc0 .LBB0_234
	s_and_b64 vcc, exec, s[16:17]
	s_cbranch_vccz .LBB0_237
	s_barrier

; #define PG8_STAGE(bufoff, gbase, voff) do { _Pragma("unroll") for (int _i = 0; _i < 2; ++_i) \
;         asm volatile("s_mov_b32 m0, %2\n\ts_nop 0\n\tglobal_load_lds_dwordx4 %0, %1" :: "v"((voff)[_i]), "s"((const char*)(gbase)), "s"(ldsbase + (unsigned)(bufoff) + ldsw + (unsigned)_i * 8192u) : "memory", "m0"); } while (0)
; #define PG8_LDA(dst, b, h) do { _Pragma("unroll") for (int m = 0; m < 4; ++m) _Pragma("unroll") for (int k = 0; k < 2; ++k) dst[m][k] = *(const PG8_LAS bf16x8*)(lds + PG8_SA(b, h) + aoff + m * 2048 + k * 1024); } while (0)
; #define PG8_LDB(dst, b, h) do { _Pragma("unroll") for (int n = 0; n < 2; ++n) _Pragma("unroll") for (int k = 0; k < 2; ++k) dst[n][k] = *(const PG8_LAS bf16x8*)(lds + PG8_SB(b, h) + boff + n * 2048 + k * 1024); } while (0)
; #define PG8_MMA(ai, bj, At, Bt) do { __builtin_amdgcn_s_setprio(1); _Pragma("unroll") for (int m = 0; m < 4; ++m) _Pragma("unroll") for (int n = 0; n < 2; ++n) _Pragma("unroll") for (int k = 0; k < 2; ++k) \
;         acc[ai][bj][m][n] = __builtin_amdgcn_mfma_f32_16x16x32_bf16(Bt[n][k], At[m][k], acc[ai][bj][m][n], 0, 0, 0); __builtin_amdgcn_s_setprio(0); } while (0)
; #define PG8_WAIT_V(n) asm volatile("s_waitcnt vmcnt(" #n ")" ::: "memory")
; #define PG8_BAR __builtin_amdgcn_s_barrier()
; template <class Epi, class Sched, bool ALIGN_EPI = false, bool SP2 = false>
; __device__ __forceinline__ void gemm_phase(PG8_LAS unsigned char* lds, const Gemm g, const Sched& S, const Epi& E) {
;     ...
;             const char* a2 = last ? nA : cA + (size_t)(t + 2) * kstep; const char* b2 = last ? nB : cB + (size_t)(t + 2) * kstep;
;             const char* a3 = a2 + kstep; const char* b3 = b2 + kstep;
;             if (last && has_next) S.a_ready(nxt);
;             if constexpr (epi_has_mid<Epi>::value) { if (t == Epi::MID_T) E.mid(acc, cur, wr, wc, fr, fq); }
;             if constexpr (SP2) {
;             PG8_LDB(B0, 0, 0); PG8_LDB(B1, 0, 1); PG8_SCHED; PG8_LDA(At, 0, 0); PG8_STAGE(PG8_SA(1, 1), a1 + hstep, voffA);
;             PG8_WAIT_V(8); PG8_WAIT_L(0); PG8_BAR; PG8_MMA(0, 0, At, B0); PG8_MMA(0, 1, At, B1); PG8_BAR; PG8_SCHED;
;             PG8_LDA(At, 0, 1); PG8_STAGE(PG8_SB(0, 0), b2, voffB); PG8_STAGE(PG8_SB(0, 1), b2 + hstep, voffB); PG8_STAGE(PG8_SA(0, 0), a2, voffA);
;             PG8_WAIT_V(8); PG8_WAIT_L(0); PG8_BAR; PG8_MMA(1, 0, At, B0); PG8_MMA(1, 1, At, B1); PG8_BAR; PG8_SCHED;
.LBB0_325:
	v_add_u32_e32 v138, 0x10000, v151
	ds_read_b128 v[154:157], v138
	ds_read_b128 v[158:161], v138 offset:1024
	ds_read_b128 v[162:165], v138 offset:2048
	ds_read_b128 v[166:169], v138 offset:3072
	v_add_u32_e32 v138, 0x14000, v151
	s_add_u32 s8, s82, 0x100
	ds_read_b128 v[170:173], v138
	ds_read_b128 v[174:177], v138 offset:1024
	ds_read_b128 v[178:181], v138 offset:2048
	ds_read_b128 v[182:185], v138 offset:3072
	s_addc_u32 s9, s83, 0
	s_and_b64 s[60:61], s[62:63], exec
	s_cselect_b32 s84, s54, s8
	s_cselect_b32 s85, s19, s9
	s_cselect_b32 s63, s17, s57
	s_cselect_b32 s62, s55, s56
	s_add_u32 s66, s84, 0x80
	s_addc_u32 s67, s85, 0
	s_add_u32 s76, s62, 0x80
	s_addc_u32 s77, s63, 0
	ds_read_b128 v[186:189], v152
	ds_read_b128 v[190:193], v152 offset:1024
	ds_read_b128 v[194:197], v152 offset:2048
	ds_read_b128 v[198:201], v152 offset:3072
	ds_read_b128 v[202:205], v152 offset:4096
	ds_read_b128 v[206:209], v152 offset:5120
	ds_read_b128 v[210:213], v152 offset:6144
	ds_read_b128 v[214:217], v152 offset:7168
	s_add_u32 s60, s82, 0x100080
	s_addc_u32 s61, s83, 0
	s_mov_b32 m0, s97
	s_nop 0
	global_load_lds_dwordx4 v141, s[60:61]
	s_nop 0
	s_mov_b32 m0, s70
	s_nop 0
	global_load_lds_dwordx4 v143, s[60:61]
	s_waitcnt vmcnt(8)
	s_waitcnt lgkmcnt(0)
	s_barrier
	s_setprio 1
	s_waitcnt lgkmcnt(7)
	v_mfma_f32_16x16x32_bf16 v[126:129], v[154:157], v[186:189], v[126:129]
	v_mfma_f32_16x16x32_bf16 v[122:125], v[162:165], v[186:189], v[122:125]
	s_waitcnt lgkmcnt(5)
	v_mfma_f32_16x16x32_bf16 v[110:113], v[154:157], v[194:197], v[110:113]
	v_mfma_f32_16x16x32_bf16 v[106:109], v[162:165], v[194:197], v[106:109]
	s_waitcnt lgkmcnt(3)
	v_mfma_f32_16x16x32_bf16 v[94:97], v[154:157], v[202:205], v[94:97]
	v_mfma_f32_16x16x32_bf16 v[90:93], v[162:165], v[202:205], v[90:93]
	s_waitcnt lgkmcnt(1)
	v_mfma_f32_16x16x32_bf16 v[78:81], v[154:157], v[210:213], v[78:81]
	v_mfma_f32_16x16x32_bf16 v[74:77], v[162:165], v[210:213], v[74:77]
	v_mfma_f32_16x16x32_bf16 v[126:129], v[158:161], v[190:193], v[126:129]
	v_mfma_f32_16x16x32_bf16 v[122:125], v[166:169], v[190:193], v[122:125]
	v_mfma_f32_16x16x32_bf16 v[110:113], v[158:161], v[198:201], v[110:113]
	v_mfma_f32_16x16x32_bf16 v[106:109], v[166:169], v[198:201], v[106:109]
	v_mfma_f32_16x16x32_bf16 v[94:97], v[158:161], v[206:209], v[94:97]
	v_mfma_f32_16x16x32_bf16 v[90:93], v[166:169], v[206:209], v[90:93]
	s_waitcnt lgkmcnt(0)
	v_mfma_f32_16x16x32_bf16 v[78:81], v[158:161], v[214:217], v[78:81]
	v_mfma_f32_16x16x32_bf16 v[74:77], v[166:169], v[214:217], v[74:77]
	s_setprio 0
	s_setprio 1
	v_mfma_f32_16x16x32_bf16 v[118:121], v[170:173], v[186:189], v[118:121]
	v_mfma_f32_16x16x32_bf16 v[114:117], v[178:181], v[186:189], v[114:117]
	v_mfma_f32_16x16x32_bf16 v[102:105], v[170:173], v[194:197], v[102:105]
	v_mfma_f32_16x16x32_bf16 v[98:101], v[178:181], v[194:197], v[98:101]
	v_mfma_f32_16x16x32_bf16 v[86:89], v[170:173], v[202:205], v[86:89]
	v_mfma_f32_16x16x32_bf16 v[82:85], v[178:181], v[202:205], v[82:85]
	v_mfma_f32_16x16x32_bf16 v[70:73], v[170:173], v[210:213], v[70:73]
	v_mfma_f32_16x16x32_bf16 v[66:69], v[178:181], v[210:213], v[66:69]
	v_mfma_f32_16x16x32_bf16 v[118:121], v[174:177], v[190:193], v[118:121]
	v_mfma_f32_16x16x32_bf16 v[114:117], v[182:185], v[190:193], v[114:117]
	v_mfma_f32_16x16x32_bf16 v[102:105], v[174:177], v[198:201], v[102:105]
	v_mfma_f32_16x16x32_bf16 v[98:101], v[182:185], v[198:201], v[98:101]
	v_mfma_f32_16x16x32_bf16 v[86:89], v[174:177], v[206:209], v[86:89]
	v_mfma_f32_16x16x32_bf16 v[82:85], v[182:185], v[206:209], v[82:85]
	v_mfma_f32_16x16x32_bf16 v[70:73], v[174:177], v[214:217], v[70:73]
	s_setprio 2
	s_barrier
	v_mfma_f32_16x16x32_bf16 v[66:69], v[182:185], v[214:217], v[66:69]
	s_setprio 0
	ds_read_b128 v[186:189], v152 offset:16384
	ds_read_b128 v[190:193], v152 offset:17408
	ds_read_b128 v[194:197], v152 offset:18432
	ds_read_b128 v[198:201], v152 offset:19456
	ds_read_b128 v[202:205], v152 offset:20480
	ds_read_b128 v[206:209], v152 offset:21504
	ds_read_b128 v[210:213], v152 offset:22528
	ds_read_b128 v[214:217], v152 offset:23552
	s_mov_b32 m0, s68
	s_nop 0
	global_load_lds_dwordx4 v142, s[62:63]
	s_add_u32 s60, s62, 0x100000
	s_mov_b32 m0, s69
	s_nop 0
	global_load_lds_dwordx4 v144, s[62:63]
	s_addc_u32 s61, s63, 0
	s_mov_b32 m0, s81
	s_nop 0
	global_load_lds_dwordx4 v142, s[60:61]
	s_nop 0
	s_mov_b32 m0, s86
	s_nop 0
	global_load_lds_dwordx4 v144, s[60:61]
	s_nop 0
	s_mov_b32 m0, s65
	s_nop 0
	global_load_lds_dwordx4 v141, s[84:85]
	s_nop 0
	s_mov_b32 m0, s87
	s_nop 0
	global_load_lds_dwordx4 v143, s[84:85]
	s_waitcnt vmcnt(8)
	s_waitcnt lgkmcnt(0)
	s_barrier
; #define PG8_STAGE(bufoff, gbase, voff) do { _Pragma("unroll") for (int _i = 0; _i < 2; ++_i) \
;         asm volatile("s_mov_b32 m0, %2\n\ts_nop 0\n\tglobal_load_lds_dwordx4 %0, %1" :: "v"((voff)[_i]), "s"((const char*)(gbase)), "s"(ldsbase + (unsigned)(bufoff) + ldsw + (unsigned)_i * 8192u) : "memory", "m0"); } while (0)
; #define PG8_LDA(dst, b, h) do { _Pragma("unroll") for (int m = 0; m < 4; ++m) _Pragma("unroll") for (int k = 0; k < 2; ++k) dst[m][k] = *(const PG8_LAS bf16x8*)(lds + PG8_SA(b, h) + aoff + m * 2048 + k * 1024); } while (0)
; #define PG8_LDB(dst, b, h) do { _Pragma("unroll") for (int n = 0; n < 2; ++n) _Pragma("unroll") for (int k = 0; k < 2; ++k) dst[n][k] = *(const PG8_LAS bf16x8*)(lds + PG8_SB(b, h) + boff + n * 2048 + k * 1024); } while (0)
; #define PG8_MMA(ai, bj, At, Bt) do { __builtin_amdgcn_s_setprio(1); _Pragma("unroll") for (int m = 0; m < 4; ++m) _Pragma("unroll") for (int n = 0; n < 2; ++n) _Pragma("unroll") for (int k = 0; k < 2; ++k) \
;         acc[ai][bj][m][n] = __builtin_amdgcn_mfma_f32_16x16x32_bf16(Bt[n][k], At[m][k], acc[ai][bj][m][n], 0, 0, 0); __builtin_amdgcn_s_setprio(0); } while (0)
; #define PG8_WAIT_V(n) asm volatile("s_waitcnt vmcnt(" #n ")" ::: "memory")
; #define PG8_WAIT_L(n) asm volatile("s_waitcnt lgkmcnt(" #n ")" ::: "memory")
; #define PG8_BAR __builtin_amdgcn_s_barrier()
; #define PG8_SCHED __builtin_amdgcn_sched_barrier(0)
; template <class Epi, class Sched, bool ALIGN_EPI = false, bool SP2 = false>
; __device__ __forceinline__ void gemm_phase(PG8_LAS unsigned char* lds, const Gemm g, const Sched& S, const Epi& E) {
;     ...
;             PG8_WAIT_V(8); PG8_WAIT_L(0); PG8_BAR; PG8_MMA(1, 0, At, B0); PG8_MMA(1, 1, At, B1); PG8_BAR; PG8_SCHED;
;             PG8_LDB(B0, 1, 0); PG8_LDB(B1, 1, 1); PG8_SCHED; PG8_LDA(At, 1, 0); PG8_STAGE(PG8_SA(0, 1), a2 + hstep, voffA);
;             PG8_WAIT_V(8); PG8_WAIT_L(0); PG8_BAR; PG8_MMA(0, 0, At, B0); PG8_MMA(0, 1, At, B1); PG8_BAR; PG8_SCHED;
	s_setprio 1
	s_waitcnt lgkmcnt(7)
	v_mfma_f32_16x16x32_bf16 v[62:65], v[154:157], v[186:189], v[62:65]
	v_mfma_f32_16x16x32_bf16 v[58:61], v[162:165], v[186:189], v[58:61]
	s_waitcnt lgkmcnt(5)
	v_mfma_f32_16x16x32_bf16 v[46:49], v[154:157], v[194:197], v[46:49]
	v_mfma_f32_16x16x32_bf16 v[42:45], v[162:165], v[194:197], v[42:45]
	s_waitcnt lgkmcnt(3)
	v_mfma_f32_16x16x32_bf16 v[30:33], v[154:157], v[202:205], v[30:33]
	v_mfma_f32_16x16x32_bf16 v[26:29], v[162:165], v[202:205], v[26:29]
	s_waitcnt lgkmcnt(1)
	v_mfma_f32_16x16x32_bf16 v[14:17], v[154:157], v[210:213], v[14:17]
	v_mfma_f32_16x16x32_bf16 v[10:13], v[162:165], v[210:213], v[10:13]
	v_mfma_f32_16x16x32_bf16 v[62:65], v[158:161], v[190:193], v[62:65]
	v_mfma_f32_16x16x32_bf16 v[58:61], v[166:169], v[190:193], v[58:61]
	v_mfma_f32_16x16x32_bf16 v[46:49], v[158:161], v[198:201], v[46:49]
	v_mfma_f32_16x16x32_bf16 v[42:45], v[166:169], v[198:201], v[42:45]
	v_mfma_f32_16x16x32_bf16 v[30:33], v[158:161], v[206:209], v[30:33]
	v_mfma_f32_16x16x32_bf16 v[26:29], v[166:169], v[206:209], v[26:29]
	s_waitcnt lgkmcnt(0)
	v_mfma_f32_16x16x32_bf16 v[14:17], v[158:161], v[214:217], v[14:17]
	v_mfma_f32_16x16x32_bf16 v[10:13], v[166:169], v[214:217], v[10:13]
	s_setprio 0
	s_setprio 1
	v_mfma_f32_16x16x32_bf16 v[54:57], v[170:173], v[186:189], v[54:57]
	v_mfma_f32_16x16x32_bf16 v[50:53], v[178:181], v[186:189], v[50:53]
	v_mfma_f32_16x16x32_bf16 v[38:41], v[170:173], v[194:197], v[38:41]
	v_mfma_f32_16x16x32_bf16 v[34:37], v[178:181], v[194:197], v[34:37]
	v_mfma_f32_16x16x32_bf16 v[22:25], v[170:173], v[202:205], v[22:25]
	v_mfma_f32_16x16x32_bf16 v[18:21], v[178:181], v[202:205], v[18:21]
	v_mfma_f32_16x16x32_bf16 v[6:9], v[170:173], v[210:213], v[6:9]
	v_mfma_f32_16x16x32_bf16 v[2:5], v[178:181], v[210:213], v[2:5]
	v_mfma_f32_16x16x32_bf16 v[54:57], v[174:177], v[190:193], v[54:57]
	v_mfma_f32_16x16x32_bf16 v[50:53], v[182:185], v[190:193], v[50:53]
	v_mfma_f32_16x16x32_bf16 v[38:41], v[174:177], v[198:201], v[38:41]
	v_mfma_f32_16x16x32_bf16 v[34:37], v[182:185], v[198:201], v[34:37]
	v_mfma_f32_16x16x32_bf16 v[22:25], v[174:177], v[206:209], v[22:25]
	v_mfma_f32_16x16x32_bf16 v[18:21], v[182:185], v[206:209], v[18:21]
	v_mfma_f32_16x16x32_bf16 v[6:9], v[174:177], v[214:217], v[6:9]
	s_setprio 2
	s_barrier
	v_mfma_f32_16x16x32_bf16 v[2:5], v[182:185], v[214:217], v[2:5]
	s_setprio 0
	v_add_u32_e32 v138, 0x18000, v151
	ds_read_b128 v[154:157], v138
	ds_read_b128 v[158:161], v138 offset:1024
	ds_read_b128 v[162:165], v138 offset:2048
	ds_read_b128 v[166:169], v138 offset:3072
	v_add_u32_e32 v138, 0x1c000, v151
	ds_read_b128 v[170:173], v138
	ds_read_b128 v[174:177], v138 offset:1024
	ds_read_b128 v[178:181], v138 offset:2048
	ds_read_b128 v[182:185], v138 offset:3072
	ds_read_b128 v[186:189], v152 offset:32768
	ds_read_b128 v[190:193], v152 offset:33792
	ds_read_b128 v[194:197], v152 offset:34816
	ds_read_b128 v[198:201], v152 offset:35840
	ds_read_b128 v[202:205], v152 offset:36864
	ds_read_b128 v[206:209], v152 offset:37888
	ds_read_b128 v[210:213], v152 offset:38912
	ds_read_b128 v[214:217], v152 offset:39936
	s_add_u32 s60, s84, 0x100000
	s_addc_u32 s61, s85, 0
	s_mov_b32 m0, s88
	s_nop 0
	global_load_lds_dwordx4 v141, s[60:61]
	s_nop 0
	s_mov_b32 m0, s89
	s_nop 0
	global_load_lds_dwordx4 v143, s[60:61]
	s_waitcnt vmcnt(8)
	s_waitcnt lgkmcnt(0)
	s_barrier
	s_setprio 1
	s_waitcnt lgkmcnt(7)
	v_mfma_f32_16x16x32_bf16 v[126:129], v[154:157], v[186:189], v[126:129]
	v_mfma_f32_16x16x32_bf16 v[122:125], v[162:165], v[186:189], v[122:125]
	s_waitcnt lgkmcnt(5)
	v_mfma_f32_16x16x32_bf16 v[110:113], v[154:157], v[194:197], v[110:113]
	v_mfma_f32_16x16x32_bf16 v[106:109], v[162:165], v[194:197], v[106:109]
	s_waitcnt lgkmcnt(3)
	v_mfma_f32_16x16x32_bf16 v[94:97], v[154:157], v[202:205], v[94:97]
	v_mfma_f32_16x16x32_bf16 v[90:93], v[162:165], v[202:205], v[90:93]
	s_waitcnt lgkmcnt(1)
	v_mfma_f32_16x16x32_bf16 v[78:81], v[154:157], v[210:213], v[78:81]
	v_mfma_f32_16x16x32_bf16 v[74:77], v[162:165], v[210:213], v[74:77]
	v_mfma_f32_16x16x32_bf16 v[126:129], v[158:161], v[190:193], v[126:129]
	v_mfma_f32_16x16x32_bf16 v[122:125], v[166:169], v[190:193], v[122:125]
	v_mfma_f32_16x16x32_bf16 v[110:113], v[158:161], v[198:201], v[110:113]
	v_mfma_f32_16x16x32_bf16 v[106:109], v[166:169], v[198:201], v[106:109]
	v_mfma_f32_16x16x32_bf16 v[94:97], v[158:161], v[206:209], v[94:97]
	v_mfma_f32_16x16x32_bf16 v[90:93], v[166:169], v[206:209], v[90:93]
	s_waitcnt lgkmcnt(0)
	v_mfma_f32_16x16x32_bf16 v[78:81], v[158:161], v[214:217], v[78:81]
	v_mfma_f32_16x16x32_bf16 v[74:77], v[166:169], v[214:217], v[74:77]
	s_setprio 0
	s_setprio 1
	v_mfma_f32_16x16x32_bf16 v[118:121], v[170:173], v[186:189], v[118:121]
	v_mfma_f32_16x16x32_bf16 v[114:117], v[178:181], v[186:189], v[114:117]
	v_mfma_f32_16x16x32_bf16 v[102:105], v[170:173], v[194:197], v[102:105]
	v_mfma_f32_16x16x32_bf16 v[98:101], v[178:181], v[194:197], v[98:101]
	v_mfma_f32_16x16x32_bf16 v[86:89], v[170:173], v[202:205], v[86:89]
	v_mfma_f32_16x16x32_bf16 v[82:85], v[178:181], v[202:205], v[82:85]
	v_mfma_f32_16x16x32_bf16 v[70:73], v[170:173], v[210:213], v[70:73]
	v_mfma_f32_16x16x32_bf16 v[66:69], v[178:181], v[210:213], v[66:69]
	v_mfma_f32_16x16x32_bf16 v[118:121], v[174:177], v[190:193], v[118:121]
	v_mfma_f32_16x16x32_bf16 v[114:117], v[182:185], v[190:193], v[114:117]
	v_mfma_f32_16x16x32_bf16 v[102:105], v[174:177], v[198:201], v[102:105]
	v_mfma_f32_16x16x32_bf16 v[98:101], v[182:185], v[198:201], v[98:101]
	v_mfma_f32_16x16x32_bf16 v[86:89], v[174:177], v[206:209], v[86:89]
	v_mfma_f32_16x16x32_bf16 v[82:85], v[182:185], v[206:209], v[82:85]
	v_mfma_f32_16x16x32_bf16 v[70:73], v[174:177], v[214:217], v[70:73]
	s_setprio 2
	s_barrier
; #define PG8_STAGE(bufoff, gbase, voff) do { _Pragma("unroll") for (int _i = 0; _i < 2; ++_i) \
;         asm volatile("s_mov_b32 m0, %2\n\ts_nop 0\n\tglobal_load_lds_dwordx4 %0, %1" :: "v"((voff)[_i]), "s"((const char*)(gbase)), "s"(ldsbase + (unsigned)(bufoff) + ldsw + (unsigned)_i * 8192u) : "memory", "m0"); } while (0)
; #define PG8_LDA(dst, b, h) do { _Pragma("unroll") for (int m = 0; m < 4; ++m) _Pragma("unroll") for (int k = 0; k < 2; ++k) dst[m][k] = *(const PG8_LAS bf16x8*)(lds + PG8_SA(b, h) + aoff + m * 2048 + k * 1024); } while (0)
; #define PG8_MMA(ai, bj, At, Bt) do { __builtin_amdgcn_s_setprio(1); _Pragma("unroll") for (int m = 0; m < 4; ++m) _Pragma("unroll") for (int n = 0; n < 2; ++n) _Pragma("unroll") for (int k = 0; k < 2; ++k) \
;         acc[ai][bj][m][n] = __builtin_amdgcn_mfma_f32_16x16x32_bf16(Bt[n][k], At[m][k], acc[ai][bj][m][n], 0, 0, 0); __builtin_amdgcn_s_setprio(0); } while (0)
; #define PG8_WAIT_V(n) asm volatile("s_waitcnt vmcnt(" #n ")" ::: "memory")
; #define PG8_WAIT_L(n) asm volatile("s_waitcnt lgkmcnt(" #n ")" ::: "memory")
; #define PG8_BAR __builtin_amdgcn_s_barrier()
; #define PG8_SCHED __builtin_amdgcn_sched_barrier(0)
; template <class Epi, class Sched, bool ALIGN_EPI = false, bool SP2 = false>
; __device__ __forceinline__ void gemm_phase(PG8_LAS unsigned char* lds, const Gemm g, const Sched& S, const Epi& E) {
;     ...
;             PG8_WAIT_V(8); PG8_WAIT_L(0); PG8_BAR; PG8_MMA(0, 0, At, B0); PG8_MMA(0, 1, At, B1); PG8_BAR; PG8_SCHED;
;             PG8_LDA(At, 1, 1); PG8_STAGE(PG8_SB(1, 0), b3, voffB); PG8_STAGE(PG8_SB(1, 1), b3 + hstep, voffB); PG8_STAGE(PG8_SA(1, 0), a3, voffA);
;             PG8_WAIT_V(8); PG8_WAIT_L(0); PG8_BAR; PG8_MMA(1, 0, At, B0); PG8_MMA(1, 1, At, B1); PG8_BAR; PG8_SCHED;
	v_mfma_f32_16x16x32_bf16 v[66:69], v[182:185], v[214:217], v[66:69]
	s_setprio 0
	ds_read_b128 v[186:189], v152 offset:49152
	ds_read_b128 v[190:193], v152 offset:50176
	ds_read_b128 v[194:197], v152 offset:51200
	ds_read_b128 v[198:201], v152 offset:52224
	ds_read_b128 v[202:205], v152 offset:53248
	ds_read_b128 v[206:209], v152 offset:54272
	ds_read_b128 v[210:213], v152 offset:55296
	ds_read_b128 v[214:217], v152 offset:56320
	s_mov_b32 m0, s90
	s_nop 0
	global_load_lds_dwordx4 v142, s[76:77]
	s_add_u32 s60, s62, 0x100080
	s_mov_b32 m0, s91
	s_nop 0
	global_load_lds_dwordx4 v144, s[76:77]
	s_addc_u32 s61, s63, 0
	s_mov_b32 m0, s95
	s_nop 0
	global_load_lds_dwordx4 v142, s[60:61]
	s_nop 0
	s_mov_b32 m0, s96
	s_nop 0
	global_load_lds_dwordx4 v144, s[60:61]
	s_nop 0
	s_mov_b32 m0, s92
	s_nop 0
	global_load_lds_dwordx4 v141, s[66:67]
	s_nop 0
	s_mov_b32 m0, s94
	s_nop 0
	global_load_lds_dwordx4 v143, s[66:67]
	s_waitcnt vmcnt(8)
	s_waitcnt lgkmcnt(0)
	s_barrier
	s_setprio 1
	s_waitcnt lgkmcnt(7)
	v_mfma_f32_16x16x32_bf16 v[62:65], v[154:157], v[186:189], v[62:65]
	v_mfma_f32_16x16x32_bf16 v[58:61], v[162:165], v[186:189], v[58:61]
	s_waitcnt lgkmcnt(5)
	v_mfma_f32_16x16x32_bf16 v[46:49], v[154:157], v[194:197], v[46:49]
	v_mfma_f32_16x16x32_bf16 v[42:45], v[162:165], v[194:197], v[42:45]
	s_waitcnt lgkmcnt(3)
	v_mfma_f32_16x16x32_bf16 v[30:33], v[154:157], v[202:205], v[30:33]
	v_mfma_f32_16x16x32_bf16 v[26:29], v[162:165], v[202:205], v[26:29]
	s_waitcnt lgkmcnt(1)
	v_mfma_f32_16x16x32_bf16 v[14:17], v[154:157], v[210:213], v[14:17]
	v_mfma_f32_16x16x32_bf16 v[10:13], v[162:165], v[210:213], v[10:13]
	v_mfma_f32_16x16x32_bf16 v[62:65], v[158:161], v[190:193], v[62:65]
	v_mfma_f32_16x16x32_bf16 v[58:61], v[166:169], v[190:193], v[58:61]
	v_mfma_f32_16x16x32_bf16 v[46:49], v[158:161], v[198:201], v[46:49]
	v_mfma_f32_16x16x32_bf16 v[42:45], v[166:169], v[198:201], v[42:45]
	v_mfma_f32_16x16x32_bf16 v[30:33], v[158:161], v[206:209], v[30:33]
	v_mfma_f32_16x16x32_bf16 v[26:29], v[166:169], v[206:209], v[26:29]
	s_waitcnt lgkmcnt(0)
	v_mfma_f32_16x16x32_bf16 v[14:17], v[158:161], v[214:217], v[14:17]
	v_mfma_f32_16x16x32_bf16 v[10:13], v[166:169], v[214:217], v[10:13]
	s_setprio 0
	s_setprio 1
	v_mfma_f32_16x16x32_bf16 v[54:57], v[170:173], v[186:189], v[54:57]
	v_mfma_f32_16x16x32_bf16 v[50:53], v[178:181], v[186:189], v[50:53]
	v_mfma_f32_16x16x32_bf16 v[38:41], v[170:173], v[194:197], v[38:41]
	v_mfma_f32_16x16x32_bf16 v[34:37], v[178:181], v[194:197], v[34:37]
	v_mfma_f32_16x16x32_bf16 v[22:25], v[170:173], v[202:205], v[22:25]
	v_mfma_f32_16x16x32_bf16 v[18:21], v[178:181], v[202:205], v[18:21]
	v_mfma_f32_16x16x32_bf16 v[6:9], v[170:173], v[210:213], v[6:9]
	v_mfma_f32_16x16x32_bf16 v[2:5], v[178:181], v[210:213], v[2:5]
	v_mfma_f32_16x16x32_bf16 v[54:57], v[174:177], v[190:193], v[54:57]
	v_mfma_f32_16x16x32_bf16 v[50:53], v[182:185], v[190:193], v[50:53]
	v_mfma_f32_16x16x32_bf16 v[38:41], v[174:177], v[198:201], v[38:41]
	v_mfma_f32_16x16x32_bf16 v[34:37], v[182:185], v[198:201], v[34:37]
	v_mfma_f32_16x16x32_bf16 v[22:25], v[174:177], v[206:209], v[22:25]
	v_mfma_f32_16x16x32_bf16 v[18:21], v[182:185], v[206:209], v[18:21]
	v_mfma_f32_16x16x32_bf16 v[6:9], v[174:177], v[214:217], v[6:9]
	s_setprio 2
	s_barrier
	v_mfma_f32_16x16x32_bf16 v[2:5], v[182:185], v[214:217], v[2:5]
	s_setprio 0
	s_add_i32 s58, s58, 2
	s_add_u32 s56, s56, 0x100
	s_addc_u32 s57, s57, 0
	s_cmp_gt_u32 s58, 61
	s_cbranch_scc1 .LBB0_316
	s_mov_b64 s[82:83], s[8:9]
	s_branch .LBB0_320

; #define PG8_STAGE(bufoff, gbase, voff) do { _Pragma("unroll") for (int _i = 0; _i < 2; ++_i) \
;         asm volatile("s_mov_b32 m0, %2\n\ts_nop 0\n\tglobal_load_lds_dwordx4 %0, %1" :: "v"((voff)[_i]), "s"((const char*)(gbase)), "s"(ldsbase + (unsigned)(bufoff) + ldsw + (unsigned)_i * 8192u) : "memory", "m0"); } while (0)
; #define PG8_LDA(dst, b, h) do { _Pragma("unroll") for (int m = 0; m < 4; ++m) _Pragma("unroll") for (int k = 0; k < 2; ++k) dst[m][k] = *(const PG8_LAS bf16x8*)(lds + PG8_SA(b, h) + aoff + m * 2048 + k * 1024); } while (0)
; #define PG8_LDB(dst, b, h) do { _Pragma("unroll") for (int n = 0; n < 2; ++n) _Pragma("unroll") for (int k = 0; k < 2; ++k) dst[n][k] = *(const PG8_LAS bf16x8*)(lds + PG8_SB(b, h) + boff + n * 2048 + k * 1024); } while (0)
; #define PG8_MMA(ai, bj, At, Bt) do { __builtin_amdgcn_s_setprio(1); _Pragma("unroll") for (int m = 0; m < 4; ++m) _Pragma("unroll") for (int n = 0; n < 2; ++n) _Pragma("unroll") for (int k = 0; k < 2; ++k) \
;         acc[ai][bj][m][n] = __builtin_amdgcn_mfma_f32_16x16x32_bf16(Bt[n][k], At[m][k], acc[ai][bj][m][n], 0, 0, 0); __builtin_amdgcn_s_setprio(0); } while (0)
; template <class Epi, class Sched, bool ALIGN_EPI = false, bool SP2 = false>
; __device__ __forceinline__ void gemm_phase(PG8_LAS unsigned char* lds, const Gemm g, const Sched& S, const Epi& E) {
;     ...
;             const bool last = (t == nt - 2);
;             const char* a1 = cA + (size_t)(t + 1) * kstep;
;             const char* a2 = last ? nA : cA + (size_t)(t + 2) * kstep; const char* b2 = last ? nB : cB + (size_t)(t + 2) * kstep;
;             const char* a3 = a2 + kstep; const char* b3 = b2 + kstep;
;             if (last && has_next) S.a_ready(nxt);
;             if constexpr (epi_has_mid<Epi>::value) { if (t == Epi::MID_T) E.mid(acc, cur, wr, wc, fr, fq); }
;             if constexpr (SP2) {
;             PG8_LDB(B0, 0, 0); PG8_LDB(B1, 0, 1); PG8_SCHED; PG8_LDA(At, 0, 0); PG8_STAGE(PG8_SA(1, 1), a1 + hstep, voffA);
;             PG8_WAIT_V(8); PG8_WAIT_L(0); PG8_BAR; PG8_MMA(0, 0, At, B0); PG8_MMA(0, 1, At, B1); PG8_BAR; PG8_SCHED;
;             PG8_LDA(At, 0, 1); PG8_STAGE(PG8_SB(0, 0), b2, voffB); PG8_STAGE(PG8_SB(0, 1), b2 + hstep, voffB); PG8_STAGE(PG8_SA(0, 0), a2, voffA);
;             PG8_WAIT_V(8); PG8_WAIT_L(0); PG8_BAR; PG8_MMA(1, 0, At, B0); PG8_MMA(1, 1, At, B1); PG8_BAR; PG8_SCHED;
.LBB0_620:
	v_add_u32_e32 v3, 0x10000, v199
	ds_read_b128 v[134:137], v3
	ds_read_b128 v[138:141], v3 offset:1024
	ds_read_b128 v[142:145], v3 offset:2048
	ds_read_b128 v[146:149], v3 offset:3072
	v_add_u32_e32 v3, 0x14000, v199
	s_add_u32 s44, s42, 0x100
	ds_read_b128 v[158:161], v3
	ds_read_b128 v[162:165], v3 offset:1024
	ds_read_b128 v[166:169], v3 offset:2048
	ds_read_b128 v[170:173], v3 offset:3072
	s_addc_u32 s45, s43, 0
	s_cmp_eq_u32 s92, 60
	s_cselect_b32 s56, s88, s44
	s_cselect_b32 s57, s23, s45
	s_cselect_b32 s47, s19, s91
	s_cselect_b32 s46, s89, s90
	s_add_u32 s50, s56, 0x80
	s_addc_u32 s51, s57, 0
	s_add_u32 s54, s46, 0x80
	s_addc_u32 s55, s47, 0
	ds_read_b128 v[174:177], v200
	ds_read_b128 v[178:181], v200 offset:1024
	ds_read_b128 v[182:185], v200 offset:2048
	ds_read_b128 v[186:189], v200 offset:3072
	ds_read_b128 v[190:193], v200 offset:4096
	ds_read_b128 v[202:205], v200 offset:5120
	ds_read_b128 v[206:209], v200 offset:6144
	ds_read_b128 v[210:213], v200 offset:7168
	s_add_u32 s42, s42, 0x100080
	s_addc_u32 s43, s43, 0
	s_mov_b32 m0, s85
	s_nop 0
	global_load_lds_dwordx4 v1, s[42:43]
	s_nop 0
	s_mov_b32 m0, s86
	s_nop 0
	global_load_lds_dwordx4 v195, s[42:43]
	s_waitcnt vmcnt(8)
	s_waitcnt lgkmcnt(0)
	s_barrier
	s_setprio 1
	s_waitcnt lgkmcnt(7)
	v_mfma_f32_16x16x32_bf16 v[130:133], v[134:137], v[174:177], v[130:133]
	v_mfma_f32_16x16x32_bf16 v[126:129], v[142:145], v[174:177], v[126:129]
	s_waitcnt lgkmcnt(5)
	v_mfma_f32_16x16x32_bf16 v[122:125], v[134:137], v[182:185], v[122:125]
	v_mfma_f32_16x16x32_bf16 v[118:121], v[142:145], v[182:185], v[118:121]
	s_waitcnt lgkmcnt(3)
	v_mfma_f32_16x16x32_bf16 v[114:117], v[134:137], v[190:193], v[114:117]
	v_mfma_f32_16x16x32_bf16 v[110:113], v[142:145], v[190:193], v[110:113]
	s_waitcnt lgkmcnt(1)
	v_mfma_f32_16x16x32_bf16 v[106:109], v[134:137], v[206:209], v[106:109]
	v_mfma_f32_16x16x32_bf16 v[102:105], v[142:145], v[206:209], v[102:105]
	v_mfma_f32_16x16x32_bf16 v[130:133], v[138:141], v[178:181], v[130:133]
	v_mfma_f32_16x16x32_bf16 v[126:129], v[146:149], v[178:181], v[126:129]
	v_mfma_f32_16x16x32_bf16 v[122:125], v[138:141], v[186:189], v[122:125]
	v_mfma_f32_16x16x32_bf16 v[118:121], v[146:149], v[186:189], v[118:121]
	v_mfma_f32_16x16x32_bf16 v[114:117], v[138:141], v[202:205], v[114:117]
	v_mfma_f32_16x16x32_bf16 v[110:113], v[146:149], v[202:205], v[110:113]
	s_waitcnt lgkmcnt(0)
	v_mfma_f32_16x16x32_bf16 v[106:109], v[138:141], v[210:213], v[106:109]
	v_mfma_f32_16x16x32_bf16 v[102:105], v[146:149], v[210:213], v[102:105]
	s_setprio 0
	s_setprio 1
	v_mfma_f32_16x16x32_bf16 v[66:69], v[158:161], v[174:177], v[66:69]
	v_mfma_f32_16x16x32_bf16 v[62:65], v[166:169], v[174:177], v[62:65]
	v_mfma_f32_16x16x32_bf16 v[58:61], v[158:161], v[182:185], v[58:61]
	v_mfma_f32_16x16x32_bf16 v[54:57], v[166:169], v[182:185], v[54:57]
	v_mfma_f32_16x16x32_bf16 v[50:53], v[158:161], v[190:193], v[50:53]
	v_mfma_f32_16x16x32_bf16 v[46:49], v[166:169], v[190:193], v[46:49]
	v_mfma_f32_16x16x32_bf16 v[42:45], v[158:161], v[206:209], v[42:45]
	v_mfma_f32_16x16x32_bf16 v[38:41], v[166:169], v[206:209], v[38:41]
	v_mfma_f32_16x16x32_bf16 v[66:69], v[162:165], v[178:181], v[66:69]
	v_mfma_f32_16x16x32_bf16 v[62:65], v[170:173], v[178:181], v[62:65]
	v_mfma_f32_16x16x32_bf16 v[58:61], v[162:165], v[186:189], v[58:61]
	v_mfma_f32_16x16x32_bf16 v[54:57], v[170:173], v[186:189], v[54:57]
	v_mfma_f32_16x16x32_bf16 v[50:53], v[162:165], v[202:205], v[50:53]
	v_mfma_f32_16x16x32_bf16 v[46:49], v[170:173], v[202:205], v[46:49]
	v_mfma_f32_16x16x32_bf16 v[42:45], v[162:165], v[210:213], v[42:45]
	s_setprio 2
	s_barrier
	v_mfma_f32_16x16x32_bf16 v[38:41], v[170:173], v[210:213], v[38:41]
	s_setprio 0
	ds_read_b128 v[174:177], v200 offset:16384
	ds_read_b128 v[178:181], v200 offset:17408
	ds_read_b128 v[182:185], v200 offset:18432
	ds_read_b128 v[186:189], v200 offset:19456
	ds_read_b128 v[190:193], v200 offset:20480
	ds_read_b128 v[202:205], v200 offset:21504
	ds_read_b128 v[206:209], v200 offset:22528
	ds_read_b128 v[210:213], v200 offset:23552
	s_mov_b32 m0, s63
	s_nop 0
	global_load_lds_dwordx4 v194, s[46:47]
	s_add_u32 s42, s46, 0x100000
	s_mov_b32 m0, s64
	s_nop 0
	global_load_lds_dwordx4 v196, s[46:47]
	s_addc_u32 s43, s47, 0
	s_mov_b32 m0, s65
	s_nop 0
	global_load_lds_dwordx4 v194, s[42:43]
	s_nop 0
	s_mov_b32 m0, s66
	s_nop 0
	global_load_lds_dwordx4 v196, s[42:43]
	s_nop 0
	s_mov_b32 m0, s62
	s_nop 0
	global_load_lds_dwordx4 v1, s[56:57]
	s_nop 0
	s_mov_b32 m0, s67
	s_nop 0
	global_load_lds_dwordx4 v195, s[56:57]
	s_waitcnt vmcnt(8)
	s_waitcnt lgkmcnt(0)
	s_barrier
; #define PG8_STAGE(bufoff, gbase, voff) do { _Pragma("unroll") for (int _i = 0; _i < 2; ++_i) \
;         asm volatile("s_mov_b32 m0, %2\n\ts_nop 0\n\tglobal_load_lds_dwordx4 %0, %1" :: "v"((voff)[_i]), "s"((const char*)(gbase)), "s"(ldsbase + (unsigned)(bufoff) + ldsw + (unsigned)_i * 8192u) : "memory", "m0"); } while (0)
; #define PG8_LDA(dst, b, h) do { _Pragma("unroll") for (int m = 0; m < 4; ++m) _Pragma("unroll") for (int k = 0; k < 2; ++k) dst[m][k] = *(const PG8_LAS bf16x8*)(lds + PG8_SA(b, h) + aoff + m * 2048 + k * 1024); } while (0)
; #define PG8_LDB(dst, b, h) do { _Pragma("unroll") for (int n = 0; n < 2; ++n) _Pragma("unroll") for (int k = 0; k < 2; ++k) dst[n][k] = *(const PG8_LAS bf16x8*)(lds + PG8_SB(b, h) + boff + n * 2048 + k * 1024); } while (0)
; #define PG8_MMA(ai, bj, At, Bt) do { __builtin_amdgcn_s_setprio(1); _Pragma("unroll") for (int m = 0; m < 4; ++m) _Pragma("unroll") for (int n = 0; n < 2; ++n) _Pragma("unroll") for (int k = 0; k < 2; ++k) \
;         acc[ai][bj][m][n] = __builtin_amdgcn_mfma_f32_16x16x32_bf16(Bt[n][k], At[m][k], acc[ai][bj][m][n], 0, 0, 0); __builtin_amdgcn_s_setprio(0); } while (0)
; #define PG8_WAIT_V(n) asm volatile("s_waitcnt vmcnt(" #n ")" ::: "memory")
; #define PG8_WAIT_L(n) asm volatile("s_waitcnt lgkmcnt(" #n ")" ::: "memory")
; #define PG8_BAR __builtin_amdgcn_s_barrier()
; #define PG8_SCHED __builtin_amdgcn_sched_barrier(0)
; template <class Epi, class Sched, bool ALIGN_EPI = false, bool SP2 = false>
; __device__ __forceinline__ void gemm_phase(PG8_LAS unsigned char* lds, const Gemm g, const Sched& S, const Epi& E) {
;     ...
;             PG8_WAIT_V(8); PG8_WAIT_L(0); PG8_BAR; PG8_MMA(1, 0, At, B0); PG8_MMA(1, 1, At, B1); PG8_BAR; PG8_SCHED;
;             PG8_LDB(B0, 1, 0); PG8_LDB(B1, 1, 1); PG8_SCHED; PG8_LDA(At, 1, 0); PG8_STAGE(PG8_SA(0, 1), a2 + hstep, voffA);
;             PG8_WAIT_V(8); PG8_WAIT_L(0); PG8_BAR; PG8_MMA(0, 0, At, B0); PG8_MMA(0, 1, At, B1); PG8_BAR; PG8_SCHED;
	s_setprio 1
	s_waitcnt lgkmcnt(7)
	v_mfma_f32_16x16x32_bf16 v[98:101], v[134:137], v[174:177], v[98:101]
	v_mfma_f32_16x16x32_bf16 v[94:97], v[142:145], v[174:177], v[94:97]
	s_waitcnt lgkmcnt(5)
	v_mfma_f32_16x16x32_bf16 v[90:93], v[134:137], v[182:185], v[90:93]
	v_mfma_f32_16x16x32_bf16 v[86:89], v[142:145], v[182:185], v[86:89]
	s_waitcnt lgkmcnt(3)
	v_mfma_f32_16x16x32_bf16 v[82:85], v[134:137], v[190:193], v[82:85]
	v_mfma_f32_16x16x32_bf16 v[78:81], v[142:145], v[190:193], v[78:81]
	s_waitcnt lgkmcnt(1)
	v_mfma_f32_16x16x32_bf16 v[74:77], v[134:137], v[206:209], v[74:77]
	v_mfma_f32_16x16x32_bf16 v[70:73], v[142:145], v[206:209], v[70:73]
	v_mfma_f32_16x16x32_bf16 v[98:101], v[138:141], v[178:181], v[98:101]
	v_mfma_f32_16x16x32_bf16 v[94:97], v[146:149], v[178:181], v[94:97]
	v_mfma_f32_16x16x32_bf16 v[90:93], v[138:141], v[186:189], v[90:93]
	v_mfma_f32_16x16x32_bf16 v[86:89], v[146:149], v[186:189], v[86:89]
	v_mfma_f32_16x16x32_bf16 v[82:85], v[138:141], v[202:205], v[82:85]
	v_mfma_f32_16x16x32_bf16 v[78:81], v[146:149], v[202:205], v[78:81]
	s_waitcnt lgkmcnt(0)
	v_mfma_f32_16x16x32_bf16 v[74:77], v[138:141], v[210:213], v[74:77]
	v_mfma_f32_16x16x32_bf16 v[70:73], v[146:149], v[210:213], v[70:73]
	s_setprio 0
	s_setprio 1
	v_mfma_f32_16x16x32_bf16 v[34:37], v[158:161], v[174:177], v[34:37]
	v_mfma_f32_16x16x32_bf16 v[30:33], v[166:169], v[174:177], v[30:33]
	v_mfma_f32_16x16x32_bf16 v[26:29], v[158:161], v[182:185], v[26:29]
	v_mfma_f32_16x16x32_bf16 v[22:25], v[166:169], v[182:185], v[22:25]
	v_mfma_f32_16x16x32_bf16 v[18:21], v[158:161], v[190:193], v[18:21]
	v_mfma_f32_16x16x32_bf16 v[14:17], v[166:169], v[190:193], v[14:17]
	v_mfma_f32_16x16x32_bf16 v[10:13], v[158:161], v[206:209], v[10:13]
	v_mfma_f32_16x16x32_bf16 v[4:7], v[166:169], v[206:209], v[6:9]
	v_mfma_f32_16x16x32_bf16 v[34:37], v[162:165], v[178:181], v[34:37]
	v_mfma_f32_16x16x32_bf16 v[30:33], v[170:173], v[178:181], v[30:33]
	v_mfma_f32_16x16x32_bf16 v[26:29], v[162:165], v[186:189], v[26:29]
	v_mfma_f32_16x16x32_bf16 v[22:25], v[170:173], v[186:189], v[22:25]
	v_mfma_f32_16x16x32_bf16 v[18:21], v[162:165], v[202:205], v[18:21]
	v_mfma_f32_16x16x32_bf16 v[14:17], v[170:173], v[202:205], v[14:17]
	v_mfma_f32_16x16x32_bf16 v[10:13], v[162:165], v[210:213], v[10:13]
	s_setprio 2
	s_barrier
	v_mfma_f32_16x16x32_bf16 v[4:7], v[170:173], v[210:213], v[4:7]
	s_setprio 0
	v_add_u32_e32 v3, 0x18000, v199
	ds_read_b128 v[134:137], v3
	ds_read_b128 v[138:141], v3 offset:1024
	ds_read_b128 v[142:145], v3 offset:2048
	ds_read_b128 v[146:149], v3 offset:3072
	v_add_u32_e32 v3, 0x1c000, v199
	ds_read_b128 v[158:161], v3
	ds_read_b128 v[162:165], v3 offset:1024
	ds_read_b128 v[166:169], v3 offset:2048
	ds_read_b128 v[170:173], v3 offset:3072
	ds_read_b128 v[174:177], v200 offset:32768
	ds_read_b128 v[178:181], v200 offset:33792
	ds_read_b128 v[182:185], v200 offset:34816
	ds_read_b128 v[186:189], v200 offset:35840
	ds_read_b128 v[190:193], v200 offset:36864
	ds_read_b128 v[202:205], v200 offset:37888
	ds_read_b128 v[206:209], v200 offset:38912
	ds_read_b128 v[210:213], v200 offset:39936
	s_add_u32 s42, s56, 0x100000
	s_addc_u32 s43, s57, 0
	s_mov_b32 m0, s76
	s_nop 0
	global_load_lds_dwordx4 v1, s[42:43]
	s_nop 0
	s_mov_b32 m0, s77
	s_nop 0
	global_load_lds_dwordx4 v195, s[42:43]
	s_waitcnt vmcnt(8)
	s_waitcnt lgkmcnt(0)
	s_barrier
	s_setprio 1
	s_waitcnt lgkmcnt(7)
	v_mfma_f32_16x16x32_bf16 v[130:133], v[134:137], v[174:177], v[130:133]
	v_mfma_f32_16x16x32_bf16 v[126:129], v[142:145], v[174:177], v[126:129]
	s_waitcnt lgkmcnt(5)
	v_mfma_f32_16x16x32_bf16 v[122:125], v[134:137], v[182:185], v[122:125]
	v_mfma_f32_16x16x32_bf16 v[118:121], v[142:145], v[182:185], v[118:121]
	s_waitcnt lgkmcnt(3)
	v_mfma_f32_16x16x32_bf16 v[114:117], v[134:137], v[190:193], v[114:117]
	v_mfma_f32_16x16x32_bf16 v[110:113], v[142:145], v[190:193], v[110:113]
	s_waitcnt lgkmcnt(1)
	v_mfma_f32_16x16x32_bf16 v[106:109], v[134:137], v[206:209], v[106:109]
	v_mfma_f32_16x16x32_bf16 v[102:105], v[142:145], v[206:209], v[102:105]
	v_mfma_f32_16x16x32_bf16 v[130:133], v[138:141], v[178:181], v[130:133]
	v_mfma_f32_16x16x32_bf16 v[126:129], v[146:149], v[178:181], v[126:129]
	v_mfma_f32_16x16x32_bf16 v[122:125], v[138:141], v[186:189], v[122:125]
	v_mfma_f32_16x16x32_bf16 v[118:121], v[146:149], v[186:189], v[118:121]
	v_mfma_f32_16x16x32_bf16 v[114:117], v[138:141], v[202:205], v[114:117]
	v_mfma_f32_16x16x32_bf16 v[110:113], v[146:149], v[202:205], v[110:113]
	s_waitcnt lgkmcnt(0)
	v_mfma_f32_16x16x32_bf16 v[106:109], v[138:141], v[210:213], v[106:109]
	v_mfma_f32_16x16x32_bf16 v[102:105], v[146:149], v[210:213], v[102:105]
	s_setprio 0
	s_setprio 1
	v_mfma_f32_16x16x32_bf16 v[66:69], v[158:161], v[174:177], v[66:69]
	v_mfma_f32_16x16x32_bf16 v[62:65], v[166:169], v[174:177], v[62:65]
	v_mfma_f32_16x16x32_bf16 v[58:61], v[158:161], v[182:185], v[58:61]
	v_mfma_f32_16x16x32_bf16 v[54:57], v[166:169], v[182:185], v[54:57]
	v_mfma_f32_16x16x32_bf16 v[50:53], v[158:161], v[190:193], v[50:53]
	v_mfma_f32_16x16x32_bf16 v[46:49], v[166:169], v[190:193], v[46:49]
	v_mfma_f32_16x16x32_bf16 v[42:45], v[158:161], v[206:209], v[42:45]
	v_mfma_f32_16x16x32_bf16 v[38:41], v[166:169], v[206:209], v[38:41]
	v_mfma_f32_16x16x32_bf16 v[66:69], v[162:165], v[178:181], v[66:69]
	v_mfma_f32_16x16x32_bf16 v[62:65], v[170:173], v[178:181], v[62:65]
	v_mfma_f32_16x16x32_bf16 v[58:61], v[162:165], v[186:189], v[58:61]
	v_mfma_f32_16x16x32_bf16 v[54:57], v[170:173], v[186:189], v[54:57]
	v_mfma_f32_16x16x32_bf16 v[50:53], v[162:165], v[202:205], v[50:53]
	v_mfma_f32_16x16x32_bf16 v[46:49], v[170:173], v[202:205], v[46:49]
	v_mfma_f32_16x16x32_bf16 v[42:45], v[162:165], v[210:213], v[42:45]
	s_setprio 2
	s_barrier
; #define PG8_STAGE(bufoff, gbase, voff) do { _Pragma("unroll") for (int _i = 0; _i < 2; ++_i) \
;         asm volatile("s_mov_b32 m0, %2\n\ts_nop 0\n\tglobal_load_lds_dwordx4 %0, %1" :: "v"((voff)[_i]), "s"((const char*)(gbase)), "s"(ldsbase + (unsigned)(bufoff) + ldsw + (unsigned)_i * 8192u) : "memory", "m0"); } while (0)
; #define PG8_LDA(dst, b, h) do { _Pragma("unroll") for (int m = 0; m < 4; ++m) _Pragma("unroll") for (int k = 0; k < 2; ++k) dst[m][k] = *(const PG8_LAS bf16x8*)(lds + PG8_SA(b, h) + aoff + m * 2048 + k * 1024); } while (0)
; #define PG8_MMA(ai, bj, At, Bt) do { __builtin_amdgcn_s_setprio(1); _Pragma("unroll") for (int m = 0; m < 4; ++m) _Pragma("unroll") for (int n = 0; n < 2; ++n) _Pragma("unroll") for (int k = 0; k < 2; ++k) \
;         acc[ai][bj][m][n] = __builtin_amdgcn_mfma_f32_16x16x32_bf16(Bt[n][k], At[m][k], acc[ai][bj][m][n], 0, 0, 0); __builtin_amdgcn_s_setprio(0); } while (0)
; #define PG8_WAIT_V(n) asm volatile("s_waitcnt vmcnt(" #n ")" ::: "memory")
; #define PG8_WAIT_L(n) asm volatile("s_waitcnt lgkmcnt(" #n ")" ::: "memory")
; #define PG8_BAR __builtin_amdgcn_s_barrier()
; #define PG8_SCHED __builtin_amdgcn_sched_barrier(0)
; template <class Epi, class Sched, bool ALIGN_EPI = false, bool SP2 = false>
; __device__ __forceinline__ void gemm_phase(PG8_LAS unsigned char* lds, const Gemm g, const Sched& S, const Epi& E) {
;     ...
;             if constexpr (epi_has_mid<Epi>::value) { if (t == Epi::MID_T) E.mid(acc, cur, wr, wc, fr, fq); }
;     ...
;             PG8_WAIT_V(8); PG8_WAIT_L(0); PG8_BAR; PG8_MMA(0, 0, At, B0); PG8_MMA(0, 1, At, B1); PG8_BAR; PG8_SCHED;
;             PG8_LDA(At, 1, 1); PG8_STAGE(PG8_SB(1, 0), b3, voffB); PG8_STAGE(PG8_SB(1, 1), b3 + hstep, voffB); PG8_STAGE(PG8_SA(1, 0), a3, voffA);
;             PG8_WAIT_V(8); PG8_WAIT_L(0); PG8_BAR; PG8_MMA(1, 0, At, B0); PG8_MMA(1, 1, At, B1); PG8_BAR; PG8_SCHED;
	v_mfma_f32_16x16x32_bf16 v[38:41], v[170:173], v[210:213], v[38:41]
	s_setprio 0
	ds_read_b128 v[174:177], v200 offset:49152
	ds_read_b128 v[178:181], v200 offset:50176
	ds_read_b128 v[182:185], v200 offset:51200
	ds_read_b128 v[186:189], v200 offset:52224
	ds_read_b128 v[190:193], v200 offset:53248
	ds_read_b128 v[202:205], v200 offset:54272
	ds_read_b128 v[206:209], v200 offset:55296
	ds_read_b128 v[210:213], v200 offset:56320
	s_mov_b32 m0, s78
	s_nop 0
	global_load_lds_dwordx4 v194, s[54:55]
	s_add_u32 s42, s46, 0x100080
	s_mov_b32 m0, s79
	s_nop 0
	global_load_lds_dwordx4 v196, s[54:55]
	s_addc_u32 s43, s47, 0
	s_mov_b32 m0, s83
	s_nop 0
	global_load_lds_dwordx4 v194, s[42:43]
	s_nop 0
	s_mov_b32 m0, s84
	s_nop 0
	global_load_lds_dwordx4 v196, s[42:43]
	s_nop 0
	s_mov_b32 m0, s80
	s_nop 0
	global_load_lds_dwordx4 v1, s[50:51]
	s_nop 0
	s_mov_b32 m0, s82
	s_nop 0
	global_load_lds_dwordx4 v195, s[50:51]
	s_waitcnt vmcnt(8)
	s_waitcnt lgkmcnt(0)
	s_barrier
	s_setprio 1
	s_waitcnt lgkmcnt(7)
	v_mfma_f32_16x16x32_bf16 v[98:101], v[134:137], v[174:177], v[98:101]
	v_mfma_f32_16x16x32_bf16 v[94:97], v[142:145], v[174:177], v[94:97]
	s_waitcnt lgkmcnt(5)
	v_mfma_f32_16x16x32_bf16 v[90:93], v[134:137], v[182:185], v[90:93]
	v_mfma_f32_16x16x32_bf16 v[86:89], v[142:145], v[182:185], v[86:89]
	s_waitcnt lgkmcnt(3)
	v_mfma_f32_16x16x32_bf16 v[82:85], v[134:137], v[190:193], v[82:85]
	v_mfma_f32_16x16x32_bf16 v[78:81], v[142:145], v[190:193], v[78:81]
	s_waitcnt lgkmcnt(1)
	v_mfma_f32_16x16x32_bf16 v[74:77], v[134:137], v[206:209], v[74:77]
	v_mfma_f32_16x16x32_bf16 v[70:73], v[142:145], v[206:209], v[70:73]
	v_mfma_f32_16x16x32_bf16 v[98:101], v[138:141], v[178:181], v[98:101]
	v_mfma_f32_16x16x32_bf16 v[94:97], v[146:149], v[178:181], v[94:97]
	v_mfma_f32_16x16x32_bf16 v[90:93], v[138:141], v[186:189], v[90:93]
	v_mfma_f32_16x16x32_bf16 v[86:89], v[146:149], v[186:189], v[86:89]
	v_mfma_f32_16x16x32_bf16 v[82:85], v[138:141], v[202:205], v[82:85]
	v_mfma_f32_16x16x32_bf16 v[78:81], v[146:149], v[202:205], v[78:81]
	s_waitcnt lgkmcnt(0)
	v_mfma_f32_16x16x32_bf16 v[74:77], v[138:141], v[210:213], v[74:77]
	v_mfma_f32_16x16x32_bf16 v[70:73], v[146:149], v[210:213], v[70:73]
	s_setprio 0
	s_setprio 1
	v_mfma_f32_16x16x32_bf16 v[34:37], v[158:161], v[174:177], v[34:37]
	v_mfma_f32_16x16x32_bf16 v[30:33], v[166:169], v[174:177], v[30:33]
	v_mfma_f32_16x16x32_bf16 v[26:29], v[158:161], v[182:185], v[26:29]
	v_mfma_f32_16x16x32_bf16 v[22:25], v[166:169], v[182:185], v[22:25]
	v_mfma_f32_16x16x32_bf16 v[18:21], v[158:161], v[190:193], v[18:21]
	v_mfma_f32_16x16x32_bf16 v[14:17], v[166:169], v[190:193], v[14:17]
	v_mfma_f32_16x16x32_bf16 v[8:11], v[158:161], v[206:209], v[10:13]
	v_mfma_f32_16x16x32_bf16 v[4:7], v[166:169], v[206:209], v[4:7]
	v_mfma_f32_16x16x32_bf16 v[34:37], v[162:165], v[178:181], v[34:37]
	v_mfma_f32_16x16x32_bf16 v[30:33], v[170:173], v[178:181], v[30:33]
	v_mfma_f32_16x16x32_bf16 v[26:29], v[162:165], v[186:189], v[26:29]
	v_mfma_f32_16x16x32_bf16 v[22:25], v[170:173], v[186:189], v[22:25]
	v_mfma_f32_16x16x32_bf16 v[18:21], v[162:165], v[202:205], v[18:21]
	v_mfma_f32_16x16x32_bf16 v[14:17], v[170:173], v[202:205], v[14:17]
	v_mfma_f32_16x16x32_bf16 v[10:13], v[162:165], v[210:213], v[8:11]
	s_setprio 2
	s_barrier
	v_mfma_f32_16x16x32_bf16 v[6:9], v[170:173], v[210:213], v[4:7]
	s_setprio 0
	s_add_i32 s92, s92, 2
	s_add_u32 s90, s90, 0x100
	s_addc_u32 s91, s91, 0
	s_cmp_gt_u32 s92, 61
	s_cbranch_scc1 .LBB0_622
	s_mov_b64 s[42:43], s[44:45]
	s_cmp_lg_u32 s92, 30
	s_cbranch_scc0 .LBB0_619
	s_branch .LBB0_620

; #define PG8_STAGE(bufoff, gbase, voff) do { _Pragma("unroll") for (int _i = 0; _i < 2; ++_i) \
;         asm volatile("s_mov_b32 m0, %2\n\ts_nop 0\n\tglobal_load_lds_dwordx4 %0, %1" :: "v"((voff)[_i]), "s"((const char*)(gbase)), "s"(ldsbase + (unsigned)(bufoff) + ldsw + (unsigned)_i * 8192u) : "memory", "m0"); } while (0)
; #define PG8_LDA(dst, b, h) do { _Pragma("unroll") for (int m = 0; m < 4; ++m) _Pragma("unroll") for (int k = 0; k < 2; ++k) dst[m][k] = *(const PG8_LAS bf16x8*)(lds + PG8_SA(b, h) + aoff + m * 2048 + k * 1024); } while (0)
; #define PG8_LDB(dst, b, h) do { _Pragma("unroll") for (int n = 0; n < 2; ++n) _Pragma("unroll") for (int k = 0; k < 2; ++k) dst[n][k] = *(const PG8_LAS bf16x8*)(lds + PG8_SB(b, h) + boff + n * 2048 + k * 1024); } while (0)
; #define PG8_MMA(ai, bj, At, Bt) do { __builtin_amdgcn_s_setprio(1); _Pragma("unroll") for (int m = 0; m < 4; ++m) _Pragma("unroll") for (int n = 0; n < 2; ++n) _Pragma("unroll") for (int k = 0; k < 2; ++k) \
;         acc[ai][bj][m][n] = __builtin_amdgcn_mfma_f32_16x16x32_bf16(Bt[n][k], At[m][k], acc[ai][bj][m][n], 0, 0, 0); __builtin_amdgcn_s_setprio(0); } while (0)
; template <class Epi, class Sched, bool ALIGN_EPI = false, bool SP2 = false>
; __device__ __forceinline__ void gemm_phase(PG8_LAS unsigned char* lds, const Gemm g, const Sched& S, const Epi& E) {
;     ...
;             const bool last = (t == nt - 2);
;             const char* a1 = cA + (size_t)(t + 1) * kstep;
;             const char* a2 = last ? nA : cA + (size_t)(t + 2) * kstep; const char* b2 = last ? nB : cB + (size_t)(t + 2) * kstep;
;             const char* a3 = a2 + kstep; const char* b3 = b2 + kstep;
;             if (last && has_next) S.a_ready(nxt);
;             if constexpr (epi_has_mid<Epi>::value) { if (t == Epi::MID_T) E.mid(acc, cur, wr, wc, fr, fq); }
;             if constexpr (SP2) {
;             PG8_LDB(B0, 0, 0); PG8_LDB(B1, 0, 1); PG8_SCHED; PG8_LDA(At, 0, 0); PG8_STAGE(PG8_SA(1, 1), a1 + hstep, voffA);
;             PG8_WAIT_V(8); PG8_WAIT_L(0); PG8_BAR; PG8_MMA(0, 0, At, B0); PG8_MMA(0, 1, At, B1); PG8_BAR; PG8_SCHED;
;             PG8_LDA(At, 0, 1); PG8_STAGE(PG8_SB(0, 0), b2, voffB); PG8_STAGE(PG8_SB(0, 1), b2 + hstep, voffB); PG8_STAGE(PG8_SA(0, 0), a2, voffA);
;             PG8_WAIT_V(8); PG8_WAIT_L(0); PG8_BAR; PG8_MMA(1, 0, At, B0); PG8_MMA(1, 1, At, B1); PG8_BAR; PG8_SCHED;
.LBB0_698:
	ds_read_b128 v[134:137], v145
	ds_read_b128 v[152:155], v145 offset:1024
	ds_read_b128 v[156:159], v145 offset:2048
	ds_read_b128 v[160:163], v145 offset:3072
	ds_read_b128 v[164:167], v146
	ds_read_b128 v[168:171], v146 offset:1024
	ds_read_b128 v[172:175], v146 offset:2048
	ds_read_b128 v[176:179], v146 offset:3072
	s_cmp_eq_u32 s69, 60
	s_cselect_b32 s48, s41, s53
	s_cselect_b32 s49, s19, s58
	s_cselect_b32 s46, s52, s59
	s_cselect_b32 s47, s17, s68
	s_add_u32 s44, s48, 0x80
	s_addc_u32 s45, s49, 0
	ds_read_b128 v[180:183], v147
	ds_read_b128 v[184:187], v147 offset:1024
	ds_read_b128 v[188:191], v147 offset:2048
	ds_read_b128 v[192:195], v147 offset:3072
	ds_read_b128 v[196:199], v147 offset:4096
	ds_read_b128 v[200:203], v147 offset:5120
	ds_read_b128 v[204:207], v147 offset:6144
	ds_read_b128 v[208:211], v147 offset:7168
	s_mov_b32 m0, s67
	s_nop 0
	global_load_lds_dwordx4 v1, s[42:43]
	s_nop 0
	s_mov_b32 m0, s74
	s_nop 0
	global_load_lds_dwordx4 v141, s[42:43]
	s_waitcnt vmcnt(8)
	s_waitcnt lgkmcnt(0)
	s_barrier
	s_setprio 1
	s_waitcnt lgkmcnt(7)
	v_mfma_f32_16x16x32_bf16 v[126:129], v[134:137], v[180:183], v[126:129]
	v_mfma_f32_16x16x32_bf16 v[122:125], v[156:159], v[180:183], v[122:125]
	s_waitcnt lgkmcnt(5)
	v_mfma_f32_16x16x32_bf16 v[110:113], v[134:137], v[188:191], v[110:113]
	v_mfma_f32_16x16x32_bf16 v[106:109], v[156:159], v[188:191], v[106:109]
	s_waitcnt lgkmcnt(3)
	v_mfma_f32_16x16x32_bf16 v[94:97], v[134:137], v[196:199], v[94:97]
	v_mfma_f32_16x16x32_bf16 v[90:93], v[156:159], v[196:199], v[90:93]
	s_waitcnt lgkmcnt(1)
	v_mfma_f32_16x16x32_bf16 v[78:81], v[134:137], v[204:207], v[78:81]
	v_mfma_f32_16x16x32_bf16 v[74:77], v[156:159], v[204:207], v[74:77]
	v_mfma_f32_16x16x32_bf16 v[126:129], v[152:155], v[184:187], v[126:129]
	v_mfma_f32_16x16x32_bf16 v[122:125], v[160:163], v[184:187], v[122:125]
	v_mfma_f32_16x16x32_bf16 v[110:113], v[152:155], v[192:195], v[110:113]
	v_mfma_f32_16x16x32_bf16 v[106:109], v[160:163], v[192:195], v[106:109]
	v_mfma_f32_16x16x32_bf16 v[94:97], v[152:155], v[200:203], v[94:97]
	v_mfma_f32_16x16x32_bf16 v[90:93], v[160:163], v[200:203], v[90:93]
	s_waitcnt lgkmcnt(0)
	v_mfma_f32_16x16x32_bf16 v[78:81], v[152:155], v[208:211], v[78:81]
	v_mfma_f32_16x16x32_bf16 v[74:77], v[160:163], v[208:211], v[74:77]
	s_setprio 0
	s_setprio 1
	v_mfma_f32_16x16x32_bf16 v[118:121], v[164:167], v[180:183], v[118:121]
	v_mfma_f32_16x16x32_bf16 v[114:117], v[172:175], v[180:183], v[114:117]
	v_mfma_f32_16x16x32_bf16 v[102:105], v[164:167], v[188:191], v[102:105]
	v_mfma_f32_16x16x32_bf16 v[98:101], v[172:175], v[188:191], v[98:101]
	v_mfma_f32_16x16x32_bf16 v[86:89], v[164:167], v[196:199], v[86:89]
	v_mfma_f32_16x16x32_bf16 v[82:85], v[172:175], v[196:199], v[82:85]
	v_mfma_f32_16x16x32_bf16 v[70:73], v[164:167], v[204:207], v[70:73]
	v_mfma_f32_16x16x32_bf16 v[66:69], v[172:175], v[204:207], v[66:69]
	v_mfma_f32_16x16x32_bf16 v[118:121], v[168:171], v[184:187], v[118:121]
	v_mfma_f32_16x16x32_bf16 v[114:117], v[176:179], v[184:187], v[114:117]
	v_mfma_f32_16x16x32_bf16 v[102:105], v[168:171], v[192:195], v[102:105]
	v_mfma_f32_16x16x32_bf16 v[98:101], v[176:179], v[192:195], v[98:101]
	v_mfma_f32_16x16x32_bf16 v[86:89], v[168:171], v[200:203], v[86:89]
	v_mfma_f32_16x16x32_bf16 v[82:85], v[176:179], v[200:203], v[82:85]
	v_mfma_f32_16x16x32_bf16 v[70:73], v[168:171], v[208:211], v[70:73]
	s_setprio 2
	s_barrier
	v_mfma_f32_16x16x32_bf16 v[66:69], v[176:179], v[208:211], v[66:69]
	s_setprio 0
	ds_read_b128 v[180:183], v147 offset:16384
	ds_read_b128 v[184:187], v147 offset:17408
	ds_read_b128 v[188:191], v147 offset:18432
	ds_read_b128 v[192:195], v147 offset:19456
	ds_read_b128 v[196:199], v147 offset:20480
	ds_read_b128 v[200:203], v147 offset:21504
	ds_read_b128 v[204:207], v147 offset:22528
	ds_read_b128 v[208:211], v147 offset:23552
	s_mov_b32 m0, s35
	s_nop 0
	global_load_lds_dwordx4 v140, s[46:47]
	s_add_u32 s70, s46, 0x100000
	s_mov_b32 m0, s50
	s_nop 0
	global_load_lds_dwordx4 v142, s[46:47]
	s_addc_u32 s71, s47, 0
	s_mov_b32 m0, s51
	s_nop 0
	global_load_lds_dwordx4 v140, s[70:71]
	s_nop 0
	s_mov_b32 m0, s54
	s_nop 0
	global_load_lds_dwordx4 v142, s[70:71]
	s_nop 0
	s_mov_b32 m0, s3
	s_nop 0
	global_load_lds_dwordx4 v1, s[48:49]
	s_nop 0
	s_mov_b32 m0, s55
	s_nop 0
	global_load_lds_dwordx4 v141, s[48:49]
	s_waitcnt vmcnt(8)
	s_waitcnt lgkmcnt(0)
	s_barrier
	s_setprio 1
	s_waitcnt lgkmcnt(7)
	v_mfma_f32_16x16x32_bf16 v[62:65], v[134:137], v[180:183], v[62:65]
	v_mfma_f32_16x16x32_bf16 v[58:61], v[156:159], v[180:183], v[58:61]
	s_waitcnt lgkmcnt(5)
	v_mfma_f32_16x16x32_bf16 v[46:49], v[134:137], v[188:191], v[46:49]
	v_mfma_f32_16x16x32_bf16 v[42:45], v[156:159], v[188:191], v[42:45]
	s_waitcnt lgkmcnt(3)
	v_mfma_f32_16x16x32_bf16 v[30:33], v[134:137], v[196:199], v[30:33]
	v_mfma_f32_16x16x32_bf16 v[26:29], v[156:159], v[196:199], v[26:29]
	s_waitcnt lgkmcnt(1)
	v_mfma_f32_16x16x32_bf16 v[14:17], v[134:137], v[204:207], v[14:17]
	v_mfma_f32_16x16x32_bf16 v[10:13], v[156:159], v[204:207], v[10:13]
	v_mfma_f32_16x16x32_bf16 v[62:65], v[152:155], v[184:187], v[62:65]
	v_mfma_f32_16x16x32_bf16 v[58:61], v[160:163], v[184:187], v[58:61]
	v_mfma_f32_16x16x32_bf16 v[46:49], v[152:155], v[192:195], v[46:49]
	v_mfma_f32_16x16x32_bf16 v[42:45], v[160:163], v[192:195], v[42:45]
	v_mfma_f32_16x16x32_bf16 v[30:33], v[152:155], v[200:203], v[30:33]
	v_mfma_f32_16x16x32_bf16 v[26:29], v[160:163], v[200:203], v[26:29]
	s_waitcnt lgkmcnt(0)
	v_mfma_f32_16x16x32_bf16 v[14:17], v[152:155], v[208:211], v[14:17]
	v_mfma_f32_16x16x32_bf16 v[10:13], v[160:163], v[208:211], v[10:13]
	s_setprio 0
	s_setprio 1
	v_mfma_f32_16x16x32_bf16 v[54:57], v[164:167], v[180:183], v[54:57]
	v_mfma_f32_16x16x32_bf16 v[50:53], v[172:175], v[180:183], v[50:53]
	v_mfma_f32_16x16x32_bf16 v[38:41], v[164:167], v[188:191], v[38:41]
	v_mfma_f32_16x16x32_bf16 v[34:37], v[172:175], v[188:191], v[34:37]
	v_mfma_f32_16x16x32_bf16 v[22:25], v[164:167], v[196:199], v[22:25]
	v_mfma_f32_16x16x32_bf16 v[18:21], v[172:175], v[196:199], v[18:21]
	v_mfma_f32_16x16x32_bf16 v[6:9], v[164:167], v[204:207], v[6:9]
	v_mfma_f32_16x16x32_bf16 v[2:5], v[172:175], v[204:207], v[2:5]
	v_mfma_f32_16x16x32_bf16 v[54:57], v[168:171], v[184:187], v[54:57]
	v_mfma_f32_16x16x32_bf16 v[50:53], v[176:179], v[184:187], v[50:53]
	v_mfma_f32_16x16x32_bf16 v[38:41], v[168:171], v[192:195], v[38:41]
	v_mfma_f32_16x16x32_bf16 v[34:37], v[176:179], v[192:195], v[34:37]
	v_mfma_f32_16x16x32_bf16 v[22:25], v[168:171], v[200:203], v[22:25]
	v_mfma_f32_16x16x32_bf16 v[18:21], v[176:179], v[200:203], v[18:21]
	v_mfma_f32_16x16x32_bf16 v[6:9], v[168:171], v[208:211], v[6:9]
	s_setprio 2
	s_barrier
; #define PG8_STAGE(bufoff, gbase, voff) do { _Pragma("unroll") for (int _i = 0; _i < 2; ++_i) \
;         asm volatile("s_mov_b32 m0, %2\n\ts_nop 0\n\tglobal_load_lds_dwordx4 %0, %1" :: "v"((voff)[_i]), "s"((const char*)(gbase)), "s"(ldsbase + (unsigned)(bufoff) + ldsw + (unsigned)_i * 8192u) : "memory", "m0"); } while (0)
; #define PG8_LDA(dst, b, h) do { _Pragma("unroll") for (int m = 0; m < 4; ++m) _Pragma("unroll") for (int k = 0; k < 2; ++k) dst[m][k] = *(const PG8_LAS bf16x8*)(lds + PG8_SA(b, h) + aoff + m * 2048 + k * 1024); } while (0)
; #define PG8_LDB(dst, b, h) do { _Pragma("unroll") for (int n = 0; n < 2; ++n) _Pragma("unroll") for (int k = 0; k < 2; ++k) dst[n][k] = *(const PG8_LAS bf16x8*)(lds + PG8_SB(b, h) + boff + n * 2048 + k * 1024); } while (0)
; #define PG8_MMA(ai, bj, At, Bt) do { __builtin_amdgcn_s_setprio(1); _Pragma("unroll") for (int m = 0; m < 4; ++m) _Pragma("unroll") for (int n = 0; n < 2; ++n) _Pragma("unroll") for (int k = 0; k < 2; ++k) \
;         acc[ai][bj][m][n] = __builtin_amdgcn_mfma_f32_16x16x32_bf16(Bt[n][k], At[m][k], acc[ai][bj][m][n], 0, 0, 0); __builtin_amdgcn_s_setprio(0); } while (0)
; #define PG8_WAIT_V(n) asm volatile("s_waitcnt vmcnt(" #n ")" ::: "memory")
; #define PG8_WAIT_L(n) asm volatile("s_waitcnt lgkmcnt(" #n ")" ::: "memory")
; #define PG8_BAR __builtin_amdgcn_s_barrier()
; #define PG8_SCHED __builtin_amdgcn_sched_barrier(0)
; template <class Epi, class Sched, bool ALIGN_EPI = false, bool SP2 = false>
; __device__ __forceinline__ void gemm_phase(PG8_LAS unsigned char* lds, const Gemm g, const Sched& S, const Epi& E) {
;     ...
;             PG8_WAIT_V(8); PG8_WAIT_L(0); PG8_BAR; PG8_MMA(1, 0, At, B0); PG8_MMA(1, 1, At, B1); PG8_BAR; PG8_SCHED;
;             PG8_LDB(B0, 1, 0); PG8_LDB(B1, 1, 1); PG8_SCHED; PG8_LDA(At, 1, 0); PG8_STAGE(PG8_SA(0, 1), a2 + hstep, voffA);
;             PG8_WAIT_V(8); PG8_WAIT_L(0); PG8_BAR; PG8_MMA(0, 0, At, B0); PG8_MMA(0, 1, At, B1); PG8_BAR; PG8_SCHED;
	v_mfma_f32_16x16x32_bf16 v[2:5], v[176:179], v[208:211], v[2:5]
	s_setprio 0
	ds_read_b128 v[134:137], v148
	ds_read_b128 v[152:155], v148 offset:1024
	ds_read_b128 v[156:159], v148 offset:2048
	ds_read_b128 v[160:163], v148 offset:3072
	ds_read_b128 v[164:167], v149
	ds_read_b128 v[168:171], v149 offset:1024
	ds_read_b128 v[172:175], v149 offset:2048
	ds_read_b128 v[176:179], v149 offset:3072
	ds_read_b128 v[180:183], v147 offset:32768
	ds_read_b128 v[184:187], v147 offset:33792
	ds_read_b128 v[188:191], v147 offset:34816
	ds_read_b128 v[192:195], v147 offset:35840
	ds_read_b128 v[196:199], v147 offset:36864
	ds_read_b128 v[200:203], v147 offset:37888
	ds_read_b128 v[204:207], v147 offset:38912
	ds_read_b128 v[208:211], v147 offset:39936
	s_add_u32 s48, s48, 0x100000
	s_addc_u32 s49, s49, 0
	s_mov_b32 m0, s56
	s_nop 0
	global_load_lds_dwordx4 v1, s[48:49]
	s_nop 0
	s_mov_b32 m0, s57
	s_nop 0
	global_load_lds_dwordx4 v141, s[48:49]
	s_waitcnt vmcnt(8)
	s_waitcnt lgkmcnt(0)
	s_barrier
	s_setprio 1
	s_waitcnt lgkmcnt(7)
	v_mfma_f32_16x16x32_bf16 v[126:129], v[134:137], v[180:183], v[126:129]
	v_mfma_f32_16x16x32_bf16 v[122:125], v[156:159], v[180:183], v[122:125]
	s_waitcnt lgkmcnt(5)
	v_mfma_f32_16x16x32_bf16 v[110:113], v[134:137], v[188:191], v[110:113]
	v_mfma_f32_16x16x32_bf16 v[106:109], v[156:159], v[188:191], v[106:109]
	s_waitcnt lgkmcnt(3)
	v_mfma_f32_16x16x32_bf16 v[94:97], v[134:137], v[196:199], v[94:97]
	v_mfma_f32_16x16x32_bf16 v[90:93], v[156:159], v[196:199], v[90:93]
	s_waitcnt lgkmcnt(1)
	v_mfma_f32_16x16x32_bf16 v[78:81], v[134:137], v[204:207], v[78:81]
	v_mfma_f32_16x16x32_bf16 v[74:77], v[156:159], v[204:207], v[74:77]
	v_mfma_f32_16x16x32_bf16 v[126:129], v[152:155], v[184:187], v[126:129]
	v_mfma_f32_16x16x32_bf16 v[122:125], v[160:163], v[184:187], v[122:125]
	v_mfma_f32_16x16x32_bf16 v[110:113], v[152:155], v[192:195], v[110:113]
	v_mfma_f32_16x16x32_bf16 v[106:109], v[160:163], v[192:195], v[106:109]
	v_mfma_f32_16x16x32_bf16 v[94:97], v[152:155], v[200:203], v[94:97]
	v_mfma_f32_16x16x32_bf16 v[90:93], v[160:163], v[200:203], v[90:93]
	s_waitcnt lgkmcnt(0)
	v_mfma_f32_16x16x32_bf16 v[78:81], v[152:155], v[208:211], v[78:81]
	v_mfma_f32_16x16x32_bf16 v[74:77], v[160:163], v[208:211], v[74:77]
	s_setprio 0
	s_setprio 1
	v_mfma_f32_16x16x32_bf16 v[118:121], v[164:167], v[180:183], v[118:121]
	v_mfma_f32_16x16x32_bf16 v[114:117], v[172:175], v[180:183], v[114:117]
	v_mfma_f32_16x16x32_bf16 v[102:105], v[164:167], v[188:191], v[102:105]
	v_mfma_f32_16x16x32_bf16 v[98:101], v[172:175], v[188:191], v[98:101]
	v_mfma_f32_16x16x32_bf16 v[86:89], v[164:167], v[196:199], v[86:89]
	v_mfma_f32_16x16x32_bf16 v[82:85], v[172:175], v[196:199], v[82:85]
	v_mfma_f32_16x16x32_bf16 v[70:73], v[164:167], v[204:207], v[70:73]
	v_mfma_f32_16x16x32_bf16 v[66:69], v[172:175], v[204:207], v[66:69]
	v_mfma_f32_16x16x32_bf16 v[118:121], v[168:171], v[184:187], v[118:121]
	v_mfma_f32_16x16x32_bf16 v[114:117], v[176:179], v[184:187], v[114:117]
	v_mfma_f32_16x16x32_bf16 v[102:105], v[168:171], v[192:195], v[102:105]
	v_mfma_f32_16x16x32_bf16 v[98:101], v[176:179], v[192:195], v[98:101]
	v_mfma_f32_16x16x32_bf16 v[86:89], v[168:171], v[200:203], v[86:89]
	v_mfma_f32_16x16x32_bf16 v[82:85], v[176:179], v[200:203], v[82:85]
	v_mfma_f32_16x16x32_bf16 v[70:73], v[168:171], v[208:211], v[70:73]
	s_setprio 2
	s_barrier
; #define PG8_STAGE(bufoff, gbase, voff) do { _Pragma("unroll") for (int _i = 0; _i < 2; ++_i) \
;         asm volatile("s_mov_b32 m0, %2\n\ts_nop 0\n\tglobal_load_lds_dwordx4 %0, %1" :: "v"((voff)[_i]), "s"((const char*)(gbase)), "s"(ldsbase + (unsigned)(bufoff) + ldsw + (unsigned)_i * 8192u) : "memory", "m0"); } while (0)
; #define PG8_LDA(dst, b, h) do { _Pragma("unroll") for (int m = 0; m < 4; ++m) _Pragma("unroll") for (int k = 0; k < 2; ++k) dst[m][k] = *(const PG8_LAS bf16x8*)(lds + PG8_SA(b, h) + aoff + m * 2048 + k * 1024); } while (0)
; #define PG8_MMA(ai, bj, At, Bt) do { __builtin_amdgcn_s_setprio(1); _Pragma("unroll") for (int m = 0; m < 4; ++m) _Pragma("unroll") for (int n = 0; n < 2; ++n) _Pragma("unroll") for (int k = 0; k < 2; ++k) \
;         acc[ai][bj][m][n] = __builtin_amdgcn_mfma_f32_16x16x32_bf16(Bt[n][k], At[m][k], acc[ai][bj][m][n], 0, 0, 0); __builtin_amdgcn_s_setprio(0); } while (0)
; #define PG8_WAIT_V(n) asm volatile("s_waitcnt vmcnt(" #n ")" ::: "memory")
; #define PG8_WAIT_L(n) asm volatile("s_waitcnt lgkmcnt(" #n ")" ::: "memory")
; #define PG8_BAR __builtin_amdgcn_s_barrier()
; #define PG8_SCHED __builtin_amdgcn_sched_barrier(0)
; template <class Epi, class Sched, bool ALIGN_EPI = false, bool SP2 = false>
; __device__ __forceinline__ void gemm_phase(PG8_LAS unsigned char* lds, const Gemm g, const Sched& S, const Epi& E) {
;     ...
;             PG8_WAIT_V(8); PG8_WAIT_L(0); PG8_BAR; PG8_MMA(0, 0, At, B0); PG8_MMA(0, 1, At, B1); PG8_BAR; PG8_SCHED;
;             PG8_LDA(At, 1, 1); PG8_STAGE(PG8_SB(1, 0), b3, voffB); PG8_STAGE(PG8_SB(1, 1), b3 + hstep, voffB); PG8_STAGE(PG8_SA(1, 0), a3, voffA);
;             PG8_WAIT_V(8); PG8_WAIT_L(0); PG8_BAR; PG8_MMA(1, 0, At, B0); PG8_MMA(1, 1, At, B1); PG8_BAR; PG8_SCHED;
;     ...
;         if constexpr (ALIGN_EPI) { if (wr == 0) PG8_BAR; }
	v_mfma_f32_16x16x32_bf16 v[66:69], v[176:179], v[208:211], v[66:69]
	s_setprio 0
	ds_read_b128 v[180:183], v147 offset:49152
	ds_read_b128 v[184:187], v147 offset:50176
	ds_read_b128 v[188:191], v147 offset:51200
	ds_read_b128 v[192:195], v147 offset:52224
	ds_read_b128 v[196:199], v147 offset:53248
	ds_read_b128 v[200:203], v147 offset:54272
	ds_read_b128 v[204:207], v147 offset:55296
	ds_read_b128 v[208:211], v147 offset:56320
	s_add_u32 s48, s46, 0x80
	s_addc_u32 s49, s47, 0
	s_mov_b32 m0, s61
	s_nop 0
	global_load_lds_dwordx4 v140, s[48:49]
	s_add_u32 s46, s46, 0x100080
	s_mov_b32 m0, s62
	s_nop 0
	global_load_lds_dwordx4 v142, s[48:49]
	s_addc_u32 s47, s47, 0
	s_mov_b32 m0, s65
	s_nop 0
	global_load_lds_dwordx4 v140, s[46:47]
	s_nop 0
	s_mov_b32 m0, s66
	s_nop 0
	global_load_lds_dwordx4 v142, s[46:47]
	s_nop 0
	s_mov_b32 m0, s63
	s_nop 0
	global_load_lds_dwordx4 v1, s[44:45]
	s_nop 0
	s_mov_b32 m0, s64
	s_nop 0
	global_load_lds_dwordx4 v141, s[44:45]
	s_waitcnt vmcnt(8)
	s_waitcnt lgkmcnt(0)
	s_barrier
	s_setprio 1
	s_waitcnt lgkmcnt(7)
	v_mfma_f32_16x16x32_bf16 v[62:65], v[134:137], v[180:183], v[62:65]
	v_mfma_f32_16x16x32_bf16 v[58:61], v[156:159], v[180:183], v[58:61]
	s_waitcnt lgkmcnt(5)
	v_mfma_f32_16x16x32_bf16 v[46:49], v[134:137], v[188:191], v[46:49]
	v_mfma_f32_16x16x32_bf16 v[42:45], v[156:159], v[188:191], v[42:45]
	s_waitcnt lgkmcnt(3)
	v_mfma_f32_16x16x32_bf16 v[30:33], v[134:137], v[196:199], v[30:33]
	v_mfma_f32_16x16x32_bf16 v[26:29], v[156:159], v[196:199], v[26:29]
	s_waitcnt lgkmcnt(1)
	v_mfma_f32_16x16x32_bf16 v[14:17], v[134:137], v[204:207], v[14:17]
	v_mfma_f32_16x16x32_bf16 v[10:13], v[156:159], v[204:207], v[10:13]
	v_mfma_f32_16x16x32_bf16 v[62:65], v[152:155], v[184:187], v[62:65]
	v_mfma_f32_16x16x32_bf16 v[58:61], v[160:163], v[184:187], v[58:61]
	v_mfma_f32_16x16x32_bf16 v[46:49], v[152:155], v[192:195], v[46:49]
	v_mfma_f32_16x16x32_bf16 v[42:45], v[160:163], v[192:195], v[42:45]
	v_mfma_f32_16x16x32_bf16 v[30:33], v[152:155], v[200:203], v[30:33]
	v_mfma_f32_16x16x32_bf16 v[26:29], v[160:163], v[200:203], v[26:29]
	s_waitcnt lgkmcnt(0)
	v_mfma_f32_16x16x32_bf16 v[14:17], v[152:155], v[208:211], v[14:17]
	v_mfma_f32_16x16x32_bf16 v[10:13], v[160:163], v[208:211], v[10:13]
	s_setprio 0
	s_setprio 1
	v_mfma_f32_16x16x32_bf16 v[54:57], v[164:167], v[180:183], v[54:57]
	v_mfma_f32_16x16x32_bf16 v[50:53], v[172:175], v[180:183], v[50:53]
	v_mfma_f32_16x16x32_bf16 v[38:41], v[164:167], v[188:191], v[38:41]
	v_mfma_f32_16x16x32_bf16 v[34:37], v[172:175], v[188:191], v[34:37]
	v_mfma_f32_16x16x32_bf16 v[22:25], v[164:167], v[196:199], v[22:25]
	v_mfma_f32_16x16x32_bf16 v[18:21], v[172:175], v[196:199], v[18:21]
	v_mfma_f32_16x16x32_bf16 v[6:9], v[164:167], v[204:207], v[6:9]
	v_mfma_f32_16x16x32_bf16 v[2:5], v[172:175], v[204:207], v[2:5]
	v_mfma_f32_16x16x32_bf16 v[54:57], v[168:171], v[184:187], v[54:57]
	v_mfma_f32_16x16x32_bf16 v[50:53], v[176:179], v[184:187], v[50:53]
	v_mfma_f32_16x16x32_bf16 v[38:41], v[168:171], v[192:195], v[38:41]
	v_mfma_f32_16x16x32_bf16 v[34:37], v[176:179], v[192:195], v[34:37]
	v_mfma_f32_16x16x32_bf16 v[22:25], v[168:171], v[200:203], v[22:25]
	v_mfma_f32_16x16x32_bf16 v[18:21], v[176:179], v[200:203], v[18:21]
	v_mfma_f32_16x16x32_bf16 v[6:9], v[168:171], v[208:211], v[6:9]
	s_setprio 2
	s_barrier
	v_mfma_f32_16x16x32_bf16 v[2:5], v[176:179], v[208:211], v[2:5]
	s_setprio 0
	s_add_i32 s69, s69, 2
	s_add_u32 s53, s53, 0x100
	s_addc_u32 s58, s58, 0
	s_add_u32 s59, s59, 0x100
	s_addc_u32 s68, s68, 0
	s_add_u32 s42, s42, 0x100
	s_addc_u32 s43, s43, 0
	s_cmp_gt_u32 s69, 61
	s_cbranch_scc0 .LBB0_698
	s_and_b64 vcc, exec, s[14:15]
	s_cbranch_vccz .LBB0_701
	s_barrier

; #define PG8_STAGE(bufoff, gbase, voff) do { _Pragma("unroll") for (int _i = 0; _i < 2; ++_i) \
;         asm volatile("s_mov_b32 m0, %2\n\ts_nop 0\n\tglobal_load_lds_dwordx4 %0, %1" :: "v"((voff)[_i]), "s"((const char*)(gbase)), "s"(ldsbase + (unsigned)(bufoff) + ldsw + (unsigned)_i * 8192u) : "memory", "m0"); } while (0)
; #define PG8_LDA(dst, b, h) do { _Pragma("unroll") for (int m = 0; m < 4; ++m) _Pragma("unroll") for (int k = 0; k < 2; ++k) dst[m][k] = *(const PG8_LAS bf16x8*)(lds + PG8_SA(b, h) + aoff + m * 2048 + k * 1024); } while (0)
; #define PG8_LDB(dst, b, h) do { _Pragma("unroll") for (int n = 0; n < 2; ++n) _Pragma("unroll") for (int k = 0; k < 2; ++k) dst[n][k] = *(const PG8_LAS bf16x8*)(lds + PG8_SB(b, h) + boff + n * 2048 + k * 1024); } while (0)
; #define PG8_MMA(ai, bj, At, Bt) do { __builtin_amdgcn_s_setprio(1); _Pragma("unroll") for (int m = 0; m < 4; ++m) _Pragma("unroll") for (int n = 0; n < 2; ++n) _Pragma("unroll") for (int k = 0; k < 2; ++k) \
;         acc[ai][bj][m][n] = __builtin_amdgcn_mfma_f32_16x16x32_bf16(Bt[n][k], At[m][k], acc[ai][bj][m][n], 0, 0, 0); __builtin_amdgcn_s_setprio(0); } while (0)
; #define PG8_WAIT_V(n) asm volatile("s_waitcnt vmcnt(" #n ")" ::: "memory")
; #define PG8_BAR __builtin_amdgcn_s_barrier()
; template <class Epi, class Sched, bool ALIGN_EPI = false, bool SP2 = false>
; __device__ __forceinline__ void gemm_phase(PG8_LAS unsigned char* lds, const Gemm g, const Sched& S, const Epi& E) {
;     ...
;             const char* a2 = last ? nA : cA + (size_t)(t + 2) * kstep; const char* b2 = last ? nB : cB + (size_t)(t + 2) * kstep;
;             const char* a3 = a2 + kstep; const char* b3 = b2 + kstep;
;             if (last && has_next) S.a_ready(nxt);
;             if constexpr (epi_has_mid<Epi>::value) { if (t == Epi::MID_T) E.mid(acc, cur, wr, wc, fr, fq); }
;             if constexpr (SP2) {
;             PG8_LDB(B0, 0, 0); PG8_LDB(B1, 0, 1); PG8_SCHED; PG8_LDA(At, 0, 0); PG8_STAGE(PG8_SA(1, 1), a1 + hstep, voffA);
;             PG8_WAIT_V(8); PG8_WAIT_L(0); PG8_BAR; PG8_MMA(0, 0, At, B0); PG8_MMA(0, 1, At, B1); PG8_BAR; PG8_SCHED;
;             PG8_LDA(At, 0, 1); PG8_STAGE(PG8_SB(0, 0), b2, voffB); PG8_STAGE(PG8_SB(0, 1), b2 + hstep, voffB); PG8_STAGE(PG8_SA(0, 0), a2, voffA);
;             PG8_WAIT_V(8); PG8_WAIT_L(0); PG8_BAR; PG8_MMA(1, 0, At, B0); PG8_MMA(1, 1, At, B1); PG8_BAR; PG8_SCHED;
.LBB0_789:
	v_add_u32_e32 v164, 0x10000, v149
	v_add_u32_e32 v180, 0x14000, v149
	s_add_u32 s8, s40, 0x100
	s_waitcnt lgkmcnt(0)
	ds_read_b128 v[152:155], v164
	ds_read_b128 v[156:159], v164 offset:1024
	ds_read_b128 v[160:163], v164 offset:2048
	ds_read_b128 v[164:167], v164 offset:3072
	ds_read_b128 v[168:171], v180
	ds_read_b128 v[172:175], v180 offset:1024
	ds_read_b128 v[176:179], v180 offset:2048
	ds_read_b128 v[180:183], v180 offset:3072
	s_addc_u32 s9, s41, 0
	s_and_b64 s[38:39], s[38:39], exec
	s_cselect_b32 s46, s59, s8
	s_cselect_b32 s47, s17, s9
	s_cselect_b32 s39, s15, s75
	s_cselect_b32 s38, s71, s74
	s_add_u32 s42, s46, 0x80
	s_addc_u32 s43, s47, 0
	s_add_u32 s44, s38, 0x80
	s_addc_u32 s45, s39, 0
	ds_read_b128 v[184:187], v150
	ds_read_b128 v[188:191], v150 offset:1024
	ds_read_b128 v[192:195], v150 offset:2048
	ds_read_b128 v[196:199], v150 offset:3072
	ds_read_b128 v[200:203], v150 offset:4096
	ds_read_b128 v[204:207], v150 offset:5120
	ds_read_b128 v[208:211], v150 offset:6144
	ds_read_b128 v[212:215], v150 offset:7168
	s_add_u32 s40, s40, 0x100080
	s_addc_u32 s41, s41, 0
	s_mov_b32 m0, s64
	s_nop 0
	global_load_lds_dwordx4 v139, s[40:41]
	s_nop 0
	s_mov_b32 m0, s65
	s_nop 0
	global_load_lds_dwordx4 v141, s[40:41]
	s_waitcnt vmcnt(8)
	s_waitcnt lgkmcnt(0)
	s_barrier
	s_setprio 1
	s_waitcnt lgkmcnt(7)
	v_mfma_f32_16x16x32_bf16 v[126:129], v[152:155], v[184:187], v[126:129]
	v_mfma_f32_16x16x32_bf16 v[122:125], v[160:163], v[184:187], v[122:125]
	s_waitcnt lgkmcnt(5)
	v_mfma_f32_16x16x32_bf16 v[110:113], v[152:155], v[192:195], v[110:113]
	v_mfma_f32_16x16x32_bf16 v[106:109], v[160:163], v[192:195], v[106:109]
	s_waitcnt lgkmcnt(3)
	v_mfma_f32_16x16x32_bf16 v[94:97], v[152:155], v[200:203], v[94:97]
	v_mfma_f32_16x16x32_bf16 v[90:93], v[160:163], v[200:203], v[90:93]
	s_waitcnt lgkmcnt(1)
	v_mfma_f32_16x16x32_bf16 v[78:81], v[152:155], v[208:211], v[78:81]
	v_mfma_f32_16x16x32_bf16 v[74:77], v[160:163], v[208:211], v[74:77]
	v_mfma_f32_16x16x32_bf16 v[126:129], v[156:159], v[188:191], v[126:129]
	v_mfma_f32_16x16x32_bf16 v[122:125], v[164:167], v[188:191], v[122:125]
	v_mfma_f32_16x16x32_bf16 v[110:113], v[156:159], v[196:199], v[110:113]
	v_mfma_f32_16x16x32_bf16 v[106:109], v[164:167], v[196:199], v[106:109]
	v_mfma_f32_16x16x32_bf16 v[94:97], v[156:159], v[204:207], v[94:97]
	v_mfma_f32_16x16x32_bf16 v[90:93], v[164:167], v[204:207], v[90:93]
	s_waitcnt lgkmcnt(0)
	v_mfma_f32_16x16x32_bf16 v[78:81], v[156:159], v[212:215], v[78:81]
	v_mfma_f32_16x16x32_bf16 v[74:77], v[164:167], v[212:215], v[74:77]
	s_setprio 0
	s_setprio 1
	v_mfma_f32_16x16x32_bf16 v[118:121], v[168:171], v[184:187], v[118:121]
	v_mfma_f32_16x16x32_bf16 v[114:117], v[176:179], v[184:187], v[114:117]
	v_mfma_f32_16x16x32_bf16 v[102:105], v[168:171], v[192:195], v[102:105]
	v_mfma_f32_16x16x32_bf16 v[98:101], v[176:179], v[192:195], v[98:101]
	v_mfma_f32_16x16x32_bf16 v[86:89], v[168:171], v[200:203], v[86:89]
	v_mfma_f32_16x16x32_bf16 v[82:85], v[176:179], v[200:203], v[82:85]
	v_mfma_f32_16x16x32_bf16 v[70:73], v[168:171], v[208:211], v[70:73]
	v_mfma_f32_16x16x32_bf16 v[66:69], v[176:179], v[208:211], v[66:69]
	v_mfma_f32_16x16x32_bf16 v[118:121], v[172:175], v[188:191], v[118:121]
	v_mfma_f32_16x16x32_bf16 v[114:117], v[180:183], v[188:191], v[114:117]
	v_mfma_f32_16x16x32_bf16 v[102:105], v[172:175], v[196:199], v[102:105]
	v_mfma_f32_16x16x32_bf16 v[98:101], v[180:183], v[196:199], v[98:101]
	v_mfma_f32_16x16x32_bf16 v[86:89], v[172:175], v[204:207], v[86:89]
	v_mfma_f32_16x16x32_bf16 v[82:85], v[180:183], v[204:207], v[82:85]
	v_mfma_f32_16x16x32_bf16 v[70:73], v[172:175], v[212:215], v[70:73]
	s_setprio 2
	s_barrier
	v_mfma_f32_16x16x32_bf16 v[66:69], v[180:183], v[212:215], v[66:69]
	s_setprio 0
	ds_read_b128 v[184:187], v150 offset:16384
	ds_read_b128 v[188:191], v150 offset:17408
	ds_read_b128 v[192:195], v150 offset:18432
	ds_read_b128 v[196:199], v150 offset:19456
	ds_read_b128 v[200:203], v150 offset:20480
	ds_read_b128 v[204:207], v150 offset:21504
	ds_read_b128 v[208:211], v150 offset:22528
	ds_read_b128 v[212:215], v150 offset:23552
	s_mov_b32 m0, s49
	s_nop 0
	global_load_lds_dwordx4 v140, s[38:39]
	s_add_u32 s40, s38, 0x100000
	s_mov_b32 m0, s50
	s_nop 0
	global_load_lds_dwordx4 v142, s[38:39]
	s_addc_u32 s41, s39, 0
	s_mov_b32 m0, s51
	s_nop 0
	global_load_lds_dwordx4 v140, s[40:41]
	s_nop 0
	s_mov_b32 m0, s52
	s_nop 0
	global_load_lds_dwordx4 v142, s[40:41]
	s_nop 0
	s_mov_b32 m0, s37
	s_nop 0
	global_load_lds_dwordx4 v139, s[46:47]
	s_nop 0
	s_mov_b32 m0, s53
	s_nop 0
	global_load_lds_dwordx4 v141, s[46:47]
	s_waitcnt vmcnt(8)
	s_waitcnt lgkmcnt(0)
	s_barrier
; #define PG8_STAGE(bufoff, gbase, voff) do { _Pragma("unroll") for (int _i = 0; _i < 2; ++_i) \
;         asm volatile("s_mov_b32 m0, %2\n\ts_nop 0\n\tglobal_load_lds_dwordx4 %0, %1" :: "v"((voff)[_i]), "s"((const char*)(gbase)), "s"(ldsbase + (unsigned)(bufoff) + ldsw + (unsigned)_i * 8192u) : "memory", "m0"); } while (0)
; #define PG8_LDA(dst, b, h) do { _Pragma("unroll") for (int m = 0; m < 4; ++m) _Pragma("unroll") for (int k = 0; k < 2; ++k) dst[m][k] = *(const PG8_LAS bf16x8*)(lds + PG8_SA(b, h) + aoff + m * 2048 + k * 1024); } while (0)
; #define PG8_LDB(dst, b, h) do { _Pragma("unroll") for (int n = 0; n < 2; ++n) _Pragma("unroll") for (int k = 0; k < 2; ++k) dst[n][k] = *(const PG8_LAS bf16x8*)(lds + PG8_SB(b, h) + boff + n * 2048 + k * 1024); } while (0)
; #define PG8_MMA(ai, bj, At, Bt) do { __builtin_amdgcn_s_setprio(1); _Pragma("unroll") for (int m = 0; m < 4; ++m) _Pragma("unroll") for (int n = 0; n < 2; ++n) _Pragma("unroll") for (int k = 0; k < 2; ++k) \
;         acc[ai][bj][m][n] = __builtin_amdgcn_mfma_f32_16x16x32_bf16(Bt[n][k], At[m][k], acc[ai][bj][m][n], 0, 0, 0); __builtin_amdgcn_s_setprio(0); } while (0)
; #define PG8_WAIT_V(n) asm volatile("s_waitcnt vmcnt(" #n ")" ::: "memory")
; #define PG8_WAIT_L(n) asm volatile("s_waitcnt lgkmcnt(" #n ")" ::: "memory")
; #define PG8_BAR __builtin_amdgcn_s_barrier()
; #define PG8_SCHED __builtin_amdgcn_sched_barrier(0)
; template <class Epi, class Sched, bool ALIGN_EPI = false, bool SP2 = false>
; __device__ __forceinline__ void gemm_phase(PG8_LAS unsigned char* lds, const Gemm g, const Sched& S, const Epi& E) {
;     ...
;             PG8_WAIT_V(8); PG8_WAIT_L(0); PG8_BAR; PG8_MMA(1, 0, At, B0); PG8_MMA(1, 1, At, B1); PG8_BAR; PG8_SCHED;
;             PG8_LDB(B0, 1, 0); PG8_LDB(B1, 1, 1); PG8_SCHED; PG8_LDA(At, 1, 0); PG8_STAGE(PG8_SA(0, 1), a2 + hstep, voffA);
;             PG8_WAIT_V(8); PG8_WAIT_L(0); PG8_BAR; PG8_MMA(0, 0, At, B0); PG8_MMA(0, 1, At, B1); PG8_BAR; PG8_SCHED;
	s_setprio 1
	s_waitcnt lgkmcnt(7)
	v_mfma_f32_16x16x32_bf16 v[62:65], v[152:155], v[184:187], v[62:65]
	v_mfma_f32_16x16x32_bf16 v[58:61], v[160:163], v[184:187], v[58:61]
	s_waitcnt lgkmcnt(5)
	v_mfma_f32_16x16x32_bf16 v[46:49], v[152:155], v[192:195], v[46:49]
	v_mfma_f32_16x16x32_bf16 v[42:45], v[160:163], v[192:195], v[42:45]
	s_waitcnt lgkmcnt(3)
	v_mfma_f32_16x16x32_bf16 v[30:33], v[152:155], v[200:203], v[30:33]
	v_mfma_f32_16x16x32_bf16 v[26:29], v[160:163], v[200:203], v[26:29]
	s_waitcnt lgkmcnt(1)
	v_mfma_f32_16x16x32_bf16 v[14:17], v[152:155], v[208:211], v[14:17]
	v_mfma_f32_16x16x32_bf16 v[10:13], v[160:163], v[208:211], v[10:13]
	v_mfma_f32_16x16x32_bf16 v[62:65], v[156:159], v[188:191], v[62:65]
	v_mfma_f32_16x16x32_bf16 v[58:61], v[164:167], v[188:191], v[58:61]
	v_mfma_f32_16x16x32_bf16 v[46:49], v[156:159], v[196:199], v[46:49]
	v_mfma_f32_16x16x32_bf16 v[42:45], v[164:167], v[196:199], v[42:45]
	v_mfma_f32_16x16x32_bf16 v[30:33], v[156:159], v[204:207], v[30:33]
	v_mfma_f32_16x16x32_bf16 v[26:29], v[164:167], v[204:207], v[26:29]
	s_waitcnt lgkmcnt(0)
	v_mfma_f32_16x16x32_bf16 v[14:17], v[156:159], v[212:215], v[14:17]
	v_mfma_f32_16x16x32_bf16 v[10:13], v[164:167], v[212:215], v[10:13]
	s_setprio 0
	s_setprio 1
	v_mfma_f32_16x16x32_bf16 v[54:57], v[168:171], v[184:187], v[54:57]
	v_mfma_f32_16x16x32_bf16 v[50:53], v[176:179], v[184:187], v[50:53]
	v_mfma_f32_16x16x32_bf16 v[38:41], v[168:171], v[192:195], v[38:41]
	v_mfma_f32_16x16x32_bf16 v[34:37], v[176:179], v[192:195], v[34:37]
	v_mfma_f32_16x16x32_bf16 v[22:25], v[168:171], v[200:203], v[22:25]
	v_mfma_f32_16x16x32_bf16 v[18:21], v[176:179], v[200:203], v[18:21]
	v_mfma_f32_16x16x32_bf16 v[6:9], v[168:171], v[208:211], v[6:9]
	v_mfma_f32_16x16x32_bf16 v[2:5], v[176:179], v[208:211], v[2:5]
	v_mfma_f32_16x16x32_bf16 v[54:57], v[172:175], v[188:191], v[54:57]
	v_mfma_f32_16x16x32_bf16 v[50:53], v[180:183], v[188:191], v[50:53]
	v_mfma_f32_16x16x32_bf16 v[38:41], v[172:175], v[196:199], v[38:41]
	v_mfma_f32_16x16x32_bf16 v[34:37], v[180:183], v[196:199], v[34:37]
	v_mfma_f32_16x16x32_bf16 v[22:25], v[172:175], v[204:207], v[22:25]
	v_mfma_f32_16x16x32_bf16 v[18:21], v[180:183], v[204:207], v[18:21]
	v_mfma_f32_16x16x32_bf16 v[6:9], v[172:175], v[212:215], v[6:9]
	s_setprio 2
	s_barrier
	v_mfma_f32_16x16x32_bf16 v[2:5], v[180:183], v[212:215], v[2:5]
	s_setprio 0
	v_add_u32_e32 v164, 0x18000, v149
	v_add_u32_e32 v180, 0x1c000, v149
	ds_read_b128 v[152:155], v164
	ds_read_b128 v[156:159], v164 offset:1024
	ds_read_b128 v[160:163], v164 offset:2048
	ds_read_b128 v[164:167], v164 offset:3072
	ds_read_b128 v[168:171], v180
	ds_read_b128 v[172:175], v180 offset:1024
	ds_read_b128 v[176:179], v180 offset:2048
	ds_read_b128 v[180:183], v180 offset:3072
	ds_read_b128 v[184:187], v150 offset:32768
	ds_read_b128 v[188:191], v150 offset:33792
	ds_read_b128 v[192:195], v150 offset:34816
	ds_read_b128 v[196:199], v150 offset:35840
	ds_read_b128 v[200:203], v150 offset:36864
	ds_read_b128 v[204:207], v150 offset:37888
	ds_read_b128 v[208:211], v150 offset:38912
	ds_read_b128 v[212:215], v150 offset:39936
	s_add_u32 s40, s46, 0x100000
	s_addc_u32 s41, s47, 0
	s_mov_b32 m0, s54
	s_nop 0
	global_load_lds_dwordx4 v139, s[40:41]
	s_nop 0
	s_mov_b32 m0, s55
	s_nop 0
	global_load_lds_dwordx4 v141, s[40:41]
	s_waitcnt vmcnt(8)
	s_waitcnt lgkmcnt(0)
	s_barrier
	s_setprio 1
	s_waitcnt lgkmcnt(7)
	v_mfma_f32_16x16x32_bf16 v[126:129], v[152:155], v[184:187], v[126:129]
	v_mfma_f32_16x16x32_bf16 v[122:125], v[160:163], v[184:187], v[122:125]
	s_waitcnt lgkmcnt(5)
	v_mfma_f32_16x16x32_bf16 v[110:113], v[152:155], v[192:195], v[110:113]
	v_mfma_f32_16x16x32_bf16 v[106:109], v[160:163], v[192:195], v[106:109]
	s_waitcnt lgkmcnt(3)
	v_mfma_f32_16x16x32_bf16 v[94:97], v[152:155], v[200:203], v[94:97]
	v_mfma_f32_16x16x32_bf16 v[90:93], v[160:163], v[200:203], v[90:93]
	s_waitcnt lgkmcnt(1)
	v_mfma_f32_16x16x32_bf16 v[78:81], v[152:155], v[208:211], v[78:81]
	v_mfma_f32_16x16x32_bf16 v[74:77], v[160:163], v[208:211], v[74:77]
	v_mfma_f32_16x16x32_bf16 v[126:129], v[156:159], v[188:191], v[126:129]
	v_mfma_f32_16x16x32_bf16 v[122:125], v[164:167], v[188:191], v[122:125]
	v_mfma_f32_16x16x32_bf16 v[110:113], v[156:159], v[196:199], v[110:113]
	v_mfma_f32_16x16x32_bf16 v[106:109], v[164:167], v[196:199], v[106:109]
	v_mfma_f32_16x16x32_bf16 v[94:97], v[156:159], v[204:207], v[94:97]
	v_mfma_f32_16x16x32_bf16 v[90:93], v[164:167], v[204:207], v[90:93]
	s_waitcnt lgkmcnt(0)
	v_mfma_f32_16x16x32_bf16 v[78:81], v[156:159], v[212:215], v[78:81]
	v_mfma_f32_16x16x32_bf16 v[74:77], v[164:167], v[212:215], v[74:77]
	s_setprio 0
	s_setprio 1
	v_mfma_f32_16x16x32_bf16 v[118:121], v[168:171], v[184:187], v[118:121]
	v_mfma_f32_16x16x32_bf16 v[114:117], v[176:179], v[184:187], v[114:117]
	v_mfma_f32_16x16x32_bf16 v[102:105], v[168:171], v[192:195], v[102:105]
	v_mfma_f32_16x16x32_bf16 v[98:101], v[176:179], v[192:195], v[98:101]
	v_mfma_f32_16x16x32_bf16 v[86:89], v[168:171], v[200:203], v[86:89]
	v_mfma_f32_16x16x32_bf16 v[82:85], v[176:179], v[200:203], v[82:85]
	v_mfma_f32_16x16x32_bf16 v[70:73], v[168:171], v[208:211], v[70:73]
	v_mfma_f32_16x16x32_bf16 v[66:69], v[176:179], v[208:211], v[66:69]
	v_mfma_f32_16x16x32_bf16 v[118:121], v[172:175], v[188:191], v[118:121]
	v_mfma_f32_16x16x32_bf16 v[114:117], v[180:183], v[188:191], v[114:117]
	v_mfma_f32_16x16x32_bf16 v[102:105], v[172:175], v[196:199], v[102:105]
	v_mfma_f32_16x16x32_bf16 v[98:101], v[180:183], v[196:199], v[98:101]
	v_mfma_f32_16x16x32_bf16 v[86:89], v[172:175], v[204:207], v[86:89]
	v_mfma_f32_16x16x32_bf16 v[82:85], v[180:183], v[204:207], v[82:85]
	v_mfma_f32_16x16x32_bf16 v[70:73], v[172:175], v[212:215], v[70:73]
	s_setprio 2
	s_barrier
; #define PG8_STAGE(bufoff, gbase, voff) do { _Pragma("unroll") for (int _i = 0; _i < 2; ++_i) \
;         asm volatile("s_mov_b32 m0, %2\n\ts_nop 0\n\tglobal_load_lds_dwordx4 %0, %1" :: "v"((voff)[_i]), "s"((const char*)(gbase)), "s"(ldsbase + (unsigned)(bufoff) + ldsw + (unsigned)_i * 8192u) : "memory", "m0"); } while (0)
; #define PG8_LDA(dst, b, h) do { _Pragma("unroll") for (int m = 0; m < 4; ++m) _Pragma("unroll") for (int k = 0; k < 2; ++k) dst[m][k] = *(const PG8_LAS bf16x8*)(lds + PG8_SA(b, h) + aoff + m * 2048 + k * 1024); } while (0)
; #define PG8_MMA(ai, bj, At, Bt) do { __builtin_amdgcn_s_setprio(1); _Pragma("unroll") for (int m = 0; m < 4; ++m) _Pragma("unroll") for (int n = 0; n < 2; ++n) _Pragma("unroll") for (int k = 0; k < 2; ++k) \
;         acc[ai][bj][m][n] = __builtin_amdgcn_mfma_f32_16x16x32_bf16(Bt[n][k], At[m][k], acc[ai][bj][m][n], 0, 0, 0); __builtin_amdgcn_s_setprio(0); } while (0)
; #define PG8_WAIT_V(n) asm volatile("s_waitcnt vmcnt(" #n ")" ::: "memory")
; #define PG8_WAIT_L(n) asm volatile("s_waitcnt lgkmcnt(" #n ")" ::: "memory")
; #define PG8_BAR __builtin_amdgcn_s_barrier()
; #define PG8_SCHED __builtin_amdgcn_sched_barrier(0)
; template <class Epi, class Sched, bool ALIGN_EPI = false, bool SP2 = false>
; __device__ __forceinline__ void gemm_phase(PG8_LAS unsigned char* lds, const Gemm g, const Sched& S, const Epi& E) {
;     ...
;             PG8_WAIT_V(8); PG8_WAIT_L(0); PG8_BAR; PG8_MMA(0, 0, At, B0); PG8_MMA(0, 1, At, B1); PG8_BAR; PG8_SCHED;
;             PG8_LDA(At, 1, 1); PG8_STAGE(PG8_SB(1, 0), b3, voffB); PG8_STAGE(PG8_SB(1, 1), b3 + hstep, voffB); PG8_STAGE(PG8_SA(1, 0), a3, voffA);
;             PG8_WAIT_V(8); PG8_WAIT_L(0); PG8_BAR; PG8_MMA(1, 0, At, B0); PG8_MMA(1, 1, At, B1); PG8_BAR; PG8_SCHED;
	v_mfma_f32_16x16x32_bf16 v[66:69], v[180:183], v[212:215], v[66:69]
	s_setprio 0
	ds_read_b128 v[184:187], v150 offset:49152
	ds_read_b128 v[188:191], v150 offset:50176
	ds_read_b128 v[192:195], v150 offset:51200
	ds_read_b128 v[196:199], v150 offset:52224
	ds_read_b128 v[200:203], v150 offset:53248
	ds_read_b128 v[204:207], v150 offset:54272
	ds_read_b128 v[208:211], v150 offset:55296
	ds_read_b128 v[212:215], v150 offset:56320
	s_mov_b32 m0, s56
	s_nop 0
	global_load_lds_dwordx4 v140, s[44:45]
	s_add_u32 s38, s38, 0x100080
	s_mov_b32 m0, s57
	s_nop 0
	global_load_lds_dwordx4 v142, s[44:45]
	s_addc_u32 s39, s39, 0
	s_mov_b32 m0, s62
	s_nop 0
	global_load_lds_dwordx4 v140, s[38:39]
	s_nop 0
	s_mov_b32 m0, s63
	s_nop 0
	global_load_lds_dwordx4 v142, s[38:39]
	s_nop 0
	s_mov_b32 m0, s60
	s_nop 0
	global_load_lds_dwordx4 v139, s[42:43]
	s_nop 0
	s_mov_b32 m0, s61
	s_nop 0
	global_load_lds_dwordx4 v141, s[42:43]
	s_waitcnt vmcnt(8)
	s_waitcnt lgkmcnt(0)
	s_barrier
	s_setprio 1
	s_waitcnt lgkmcnt(7)
	v_mfma_f32_16x16x32_bf16 v[62:65], v[152:155], v[184:187], v[62:65]
	v_mfma_f32_16x16x32_bf16 v[58:61], v[160:163], v[184:187], v[58:61]
	s_waitcnt lgkmcnt(5)
	v_mfma_f32_16x16x32_bf16 v[46:49], v[152:155], v[192:195], v[46:49]
	v_mfma_f32_16x16x32_bf16 v[42:45], v[160:163], v[192:195], v[42:45]
	s_waitcnt lgkmcnt(3)
	v_mfma_f32_16x16x32_bf16 v[30:33], v[152:155], v[200:203], v[30:33]
	v_mfma_f32_16x16x32_bf16 v[26:29], v[160:163], v[200:203], v[26:29]
	s_waitcnt lgkmcnt(1)
	v_mfma_f32_16x16x32_bf16 v[14:17], v[152:155], v[208:211], v[14:17]
	v_mfma_f32_16x16x32_bf16 v[10:13], v[160:163], v[208:211], v[10:13]
	v_mfma_f32_16x16x32_bf16 v[62:65], v[156:159], v[188:191], v[62:65]
	v_mfma_f32_16x16x32_bf16 v[58:61], v[164:167], v[188:191], v[58:61]
	v_mfma_f32_16x16x32_bf16 v[46:49], v[156:159], v[196:199], v[46:49]
	v_mfma_f32_16x16x32_bf16 v[42:45], v[164:167], v[196:199], v[42:45]
	v_mfma_f32_16x16x32_bf16 v[30:33], v[156:159], v[204:207], v[30:33]
	v_mfma_f32_16x16x32_bf16 v[26:29], v[164:167], v[204:207], v[26:29]
	s_waitcnt lgkmcnt(0)
	v_mfma_f32_16x16x32_bf16 v[14:17], v[156:159], v[212:215], v[14:17]
	v_mfma_f32_16x16x32_bf16 v[10:13], v[164:167], v[212:215], v[10:13]
	s_setprio 0
	s_setprio 1
	v_mfma_f32_16x16x32_bf16 v[54:57], v[168:171], v[184:187], v[54:57]
	v_mfma_f32_16x16x32_bf16 v[50:53], v[176:179], v[184:187], v[50:53]
	v_mfma_f32_16x16x32_bf16 v[38:41], v[168:171], v[192:195], v[38:41]
	v_mfma_f32_16x16x32_bf16 v[34:37], v[176:179], v[192:195], v[34:37]
	v_mfma_f32_16x16x32_bf16 v[22:25], v[168:171], v[200:203], v[22:25]
	v_mfma_f32_16x16x32_bf16 v[18:21], v[176:179], v[200:203], v[18:21]
	v_mfma_f32_16x16x32_bf16 v[6:9], v[168:171], v[208:211], v[6:9]
	v_mfma_f32_16x16x32_bf16 v[2:5], v[176:179], v[208:211], v[2:5]
	v_mfma_f32_16x16x32_bf16 v[54:57], v[172:175], v[188:191], v[54:57]
	v_mfma_f32_16x16x32_bf16 v[50:53], v[180:183], v[188:191], v[50:53]
	v_mfma_f32_16x16x32_bf16 v[38:41], v[172:175], v[196:199], v[38:41]
	v_mfma_f32_16x16x32_bf16 v[34:37], v[180:183], v[196:199], v[34:37]
	v_mfma_f32_16x16x32_bf16 v[22:25], v[172:175], v[204:207], v[22:25]
	v_mfma_f32_16x16x32_bf16 v[18:21], v[180:183], v[204:207], v[18:21]
	v_mfma_f32_16x16x32_bf16 v[6:9], v[172:175], v[212:215], v[6:9]
	s_setprio 2
	s_barrier
	v_mfma_f32_16x16x32_bf16 v[2:5], v[180:183], v[212:215], v[2:5]
	s_setprio 0
	s_add_i32 s76, s76, 2
	s_add_u32 s74, s74, 0x100
	s_addc_u32 s75, s75, 0
	s_cmp_gt_u32 s76, 61
	s_cbranch_scc1 .LBB0_780
	s_mov_b64 s[40:41], s[8:9]
	s_branch .LBB0_784

; #define PG8_STAGE(bufoff, gbase, voff) do { _Pragma("unroll") for (int _i = 0; _i < 2; ++_i) \
;         asm volatile("s_mov_b32 m0, %2\n\ts_nop 0\n\tglobal_load_lds_dwordx4 %0, %1" :: "v"((voff)[_i]), "s"((const char*)(gbase)), "s"(ldsbase + (unsigned)(bufoff) + ldsw + (unsigned)_i * 8192u) : "memory", "m0"); } while (0)
; #define PG8_LDA(dst, b, h) do { _Pragma("unroll") for (int m = 0; m < 4; ++m) _Pragma("unroll") for (int k = 0; k < 2; ++k) dst[m][k] = *(const PG8_LAS bf16x8*)(lds + PG8_SA(b, h) + aoff + m * 2048 + k * 1024); } while (0)
; #define PG8_LDB(dst, b, h) do { _Pragma("unroll") for (int n = 0; n < 2; ++n) _Pragma("unroll") for (int k = 0; k < 2; ++k) dst[n][k] = *(const PG8_LAS bf16x8*)(lds + PG8_SB(b, h) + boff + n * 2048 + k * 1024); } while (0)
; #define PG8_MMA(ai, bj, At, Bt) do { __builtin_amdgcn_s_setprio(1); _Pragma("unroll") for (int m = 0; m < 4; ++m) _Pragma("unroll") for (int n = 0; n < 2; ++n) _Pragma("unroll") for (int k = 0; k < 2; ++k) \
;         acc[ai][bj][m][n] = __builtin_amdgcn_mfma_f32_16x16x32_bf16(Bt[n][k], At[m][k], acc[ai][bj][m][n], 0, 0, 0); __builtin_amdgcn_s_setprio(0); } while (0)
; template <class Epi, class Sched, bool ALIGN_EPI = false, bool SP2 = false>
; __device__ __forceinline__ void gemm_phase(PG8_LAS unsigned char* lds, const Gemm g, const Sched& S, const Epi& E) {
;     ...
;             const bool last = (t == nt - 2);
;             const char* a1 = cA + (size_t)(t + 1) * kstep;
;             const char* a2 = last ? nA : cA + (size_t)(t + 2) * kstep; const char* b2 = last ? nB : cB + (size_t)(t + 2) * kstep;
;             const char* a3 = a2 + kstep; const char* b3 = b2 + kstep;
;             if (last && has_next) S.a_ready(nxt);
;             if constexpr (epi_has_mid<Epi>::value) { if (t == Epi::MID_T) E.mid(acc, cur, wr, wc, fr, fq); }
;             if constexpr (SP2) {
;             PG8_LDB(B0, 0, 0); PG8_LDB(B1, 0, 1); PG8_SCHED; PG8_LDA(At, 0, 0); PG8_STAGE(PG8_SA(1, 1), a1 + hstep, voffA);
;             PG8_WAIT_V(8); PG8_WAIT_L(0); PG8_BAR; PG8_MMA(0, 0, At, B0); PG8_MMA(0, 1, At, B1); PG8_BAR; PG8_SCHED;
;             PG8_LDA(At, 0, 1); PG8_STAGE(PG8_SB(0, 0), b2, voffB); PG8_STAGE(PG8_SB(0, 1), b2 + hstep, voffB); PG8_STAGE(PG8_SA(0, 0), a2, voffA);
;             PG8_WAIT_V(8); PG8_WAIT_L(0); PG8_BAR; PG8_MMA(1, 0, At, B0); PG8_MMA(1, 1, At, B1); PG8_BAR; PG8_SCHED;
.LBB0_873:
	ds_read_b128 v[134:137], v145
	ds_read_b128 v[150:153], v145 offset:1024
	ds_read_b128 v[154:157], v145 offset:2048
	ds_read_b128 v[158:161], v145 offset:3072
	ds_read_b128 v[162:165], v146
	ds_read_b128 v[166:169], v146 offset:1024
	ds_read_b128 v[170:173], v146 offset:2048
	ds_read_b128 v[174:177], v146 offset:3072
	s_add_u32 s38, s36, 0x100
	s_addc_u32 s39, s37, 0
	s_cmpk_eq_i32 s69, 0xa8
	s_cselect_b32 s44, s4, s38
	s_cselect_b32 s45, s5, s39
	s_cselect_b32 s42, s22, s67
	s_cselect_b32 s43, s23, s68
	s_add_u32 s40, s44, 0x80
	s_addc_u32 s41, s45, 0
	ds_read_b128 v[178:181], v147
	ds_read_b128 v[182:185], v147 offset:1024
	ds_read_b128 v[186:189], v147 offset:2048
	ds_read_b128 v[190:193], v147 offset:3072
	ds_read_b128 v[194:197], v147 offset:4096
	ds_read_b128 v[198:201], v147 offset:5120
	ds_read_b128 v[202:205], v147 offset:6144
	ds_read_b128 v[206:209], v147 offset:7168
	s_add_u32 s36, s36, 0x2b0080
	s_addc_u32 s37, s37, 0
	s_mov_b32 m0, s60
	s_nop 0
	global_load_lds_dwordx4 v1, s[36:37]
	s_nop 0
	s_mov_b32 m0, s61
	s_nop 0
	global_load_lds_dwordx4 v141, s[36:37]
	s_waitcnt vmcnt(8)
	s_waitcnt lgkmcnt(0)
	s_barrier
	s_setprio 1
	s_waitcnt lgkmcnt(7)
	v_mfma_f32_16x16x32_bf16 v[126:129], v[134:137], v[178:181], v[126:129]
	v_mfma_f32_16x16x32_bf16 v[122:125], v[154:157], v[178:181], v[122:125]
	s_waitcnt lgkmcnt(5)
	v_mfma_f32_16x16x32_bf16 v[110:113], v[134:137], v[186:189], v[110:113]
	v_mfma_f32_16x16x32_bf16 v[106:109], v[154:157], v[186:189], v[106:109]
	s_waitcnt lgkmcnt(3)
	v_mfma_f32_16x16x32_bf16 v[94:97], v[134:137], v[194:197], v[94:97]
	v_mfma_f32_16x16x32_bf16 v[90:93], v[154:157], v[194:197], v[90:93]
	s_waitcnt lgkmcnt(1)
	v_mfma_f32_16x16x32_bf16 v[78:81], v[134:137], v[202:205], v[78:81]
	v_mfma_f32_16x16x32_bf16 v[74:77], v[154:157], v[202:205], v[74:77]
	v_mfma_f32_16x16x32_bf16 v[126:129], v[150:153], v[182:185], v[126:129]
	v_mfma_f32_16x16x32_bf16 v[122:125], v[158:161], v[182:185], v[122:125]
	v_mfma_f32_16x16x32_bf16 v[110:113], v[150:153], v[190:193], v[110:113]
	v_mfma_f32_16x16x32_bf16 v[106:109], v[158:161], v[190:193], v[106:109]
	v_mfma_f32_16x16x32_bf16 v[94:97], v[150:153], v[198:201], v[94:97]
	v_mfma_f32_16x16x32_bf16 v[90:93], v[158:161], v[198:201], v[90:93]
	s_waitcnt lgkmcnt(0)
	v_mfma_f32_16x16x32_bf16 v[78:81], v[150:153], v[206:209], v[78:81]
	v_mfma_f32_16x16x32_bf16 v[74:77], v[158:161], v[206:209], v[74:77]
	s_setprio 0
	s_setprio 1
	v_mfma_f32_16x16x32_bf16 v[118:121], v[162:165], v[178:181], v[118:121]
	v_mfma_f32_16x16x32_bf16 v[114:117], v[170:173], v[178:181], v[114:117]
	v_mfma_f32_16x16x32_bf16 v[102:105], v[162:165], v[186:189], v[102:105]
	v_mfma_f32_16x16x32_bf16 v[98:101], v[170:173], v[186:189], v[98:101]
	v_mfma_f32_16x16x32_bf16 v[86:89], v[162:165], v[194:197], v[86:89]
	v_mfma_f32_16x16x32_bf16 v[82:85], v[170:173], v[194:197], v[82:85]
	v_mfma_f32_16x16x32_bf16 v[70:73], v[162:165], v[202:205], v[70:73]
	v_mfma_f32_16x16x32_bf16 v[66:69], v[170:173], v[202:205], v[66:69]
	v_mfma_f32_16x16x32_bf16 v[118:121], v[166:169], v[182:185], v[118:121]
	v_mfma_f32_16x16x32_bf16 v[114:117], v[174:177], v[182:185], v[114:117]
	v_mfma_f32_16x16x32_bf16 v[102:105], v[166:169], v[190:193], v[102:105]
	v_mfma_f32_16x16x32_bf16 v[98:101], v[174:177], v[190:193], v[98:101]
	v_mfma_f32_16x16x32_bf16 v[86:89], v[166:169], v[198:201], v[86:89]
	v_mfma_f32_16x16x32_bf16 v[82:85], v[174:177], v[198:201], v[82:85]
	v_mfma_f32_16x16x32_bf16 v[70:73], v[166:169], v[206:209], v[70:73]
	s_setprio 2
	s_barrier
	v_mfma_f32_16x16x32_bf16 v[66:69], v[174:177], v[206:209], v[66:69]
	s_setprio 0
	ds_read_b128 v[178:181], v147 offset:16384
	ds_read_b128 v[182:185], v147 offset:17408
	ds_read_b128 v[186:189], v147 offset:18432
	ds_read_b128 v[190:193], v147 offset:19456
	ds_read_b128 v[194:197], v147 offset:20480
	ds_read_b128 v[198:201], v147 offset:21504
	ds_read_b128 v[202:205], v147 offset:22528
	ds_read_b128 v[206:209], v147 offset:23552
	s_mov_b32 m0, s47
	s_nop 0
	global_load_lds_dwordx4 v140, s[42:43]
	s_add_u32 s36, s42, 0x2b0000
	s_mov_b32 m0, s48
	s_nop 0
	global_load_lds_dwordx4 v142, s[42:43]
	s_addc_u32 s37, s43, 0
	s_mov_b32 m0, s49
	s_nop 0
	global_load_lds_dwordx4 v140, s[36:37]
	s_nop 0
	s_mov_b32 m0, s50
	s_nop 0
	global_load_lds_dwordx4 v142, s[36:37]
	s_nop 0
	s_mov_b32 m0, s46
	s_nop 0
	global_load_lds_dwordx4 v1, s[44:45]
	s_nop 0
	s_mov_b32 m0, s51
	s_nop 0
	global_load_lds_dwordx4 v141, s[44:45]
	s_waitcnt vmcnt(8)
	s_waitcnt lgkmcnt(0)
	s_barrier
; #define PG8_STAGE(bufoff, gbase, voff) do { _Pragma("unroll") for (int _i = 0; _i < 2; ++_i) \
;         asm volatile("s_mov_b32 m0, %2\n\ts_nop 0\n\tglobal_load_lds_dwordx4 %0, %1" :: "v"((voff)[_i]), "s"((const char*)(gbase)), "s"(ldsbase + (unsigned)(bufoff) + ldsw + (unsigned)_i * 8192u) : "memory", "m0"); } while (0)
; #define PG8_LDA(dst, b, h) do { _Pragma("unroll") for (int m = 0; m < 4; ++m) _Pragma("unroll") for (int k = 0; k < 2; ++k) dst[m][k] = *(const PG8_LAS bf16x8*)(lds + PG8_SA(b, h) + aoff + m * 2048 + k * 1024); } while (0)
; #define PG8_LDB(dst, b, h) do { _Pragma("unroll") for (int n = 0; n < 2; ++n) _Pragma("unroll") for (int k = 0; k < 2; ++k) dst[n][k] = *(const PG8_LAS bf16x8*)(lds + PG8_SB(b, h) + boff + n * 2048 + k * 1024); } while (0)
; #define PG8_MMA(ai, bj, At, Bt) do { __builtin_amdgcn_s_setprio(1); _Pragma("unroll") for (int m = 0; m < 4; ++m) _Pragma("unroll") for (int n = 0; n < 2; ++n) _Pragma("unroll") for (int k = 0; k < 2; ++k) \
;         acc[ai][bj][m][n] = __builtin_amdgcn_mfma_f32_16x16x32_bf16(Bt[n][k], At[m][k], acc[ai][bj][m][n], 0, 0, 0); __builtin_amdgcn_s_setprio(0); } while (0)
; #define PG8_WAIT_V(n) asm volatile("s_waitcnt vmcnt(" #n ")" ::: "memory")
; #define PG8_WAIT_L(n) asm volatile("s_waitcnt lgkmcnt(" #n ")" ::: "memory")
; #define PG8_BAR __builtin_amdgcn_s_barrier()
; #define PG8_SCHED __builtin_amdgcn_sched_barrier(0)
; template <class Epi, class Sched, bool ALIGN_EPI = false, bool SP2 = false>
; __device__ __forceinline__ void gemm_phase(PG8_LAS unsigned char* lds, const Gemm g, const Sched& S, const Epi& E) {
;     ...
;             PG8_WAIT_V(8); PG8_WAIT_L(0); PG8_BAR; PG8_MMA(1, 0, At, B0); PG8_MMA(1, 1, At, B1); PG8_BAR; PG8_SCHED;
;             PG8_LDB(B0, 1, 0); PG8_LDB(B1, 1, 1); PG8_SCHED; PG8_LDA(At, 1, 0); PG8_STAGE(PG8_SA(0, 1), a2 + hstep, voffA);
;             PG8_WAIT_V(8); PG8_WAIT_L(0); PG8_BAR; PG8_MMA(0, 0, At, B0); PG8_MMA(0, 1, At, B1); PG8_BAR; PG8_SCHED;
	s_setprio 1
	s_waitcnt lgkmcnt(7)
	v_mfma_f32_16x16x32_bf16 v[62:65], v[134:137], v[178:181], v[62:65]
	v_mfma_f32_16x16x32_bf16 v[58:61], v[154:157], v[178:181], v[58:61]
	s_waitcnt lgkmcnt(5)
	v_mfma_f32_16x16x32_bf16 v[46:49], v[134:137], v[186:189], v[46:49]
	v_mfma_f32_16x16x32_bf16 v[42:45], v[154:157], v[186:189], v[42:45]
	s_waitcnt lgkmcnt(3)
	v_mfma_f32_16x16x32_bf16 v[30:33], v[134:137], v[194:197], v[30:33]
	v_mfma_f32_16x16x32_bf16 v[26:29], v[154:157], v[194:197], v[26:29]
	s_waitcnt lgkmcnt(1)
	v_mfma_f32_16x16x32_bf16 v[14:17], v[134:137], v[202:205], v[14:17]
	v_mfma_f32_16x16x32_bf16 v[10:13], v[154:157], v[202:205], v[10:13]
	v_mfma_f32_16x16x32_bf16 v[62:65], v[150:153], v[182:185], v[62:65]
	v_mfma_f32_16x16x32_bf16 v[58:61], v[158:161], v[182:185], v[58:61]
	v_mfma_f32_16x16x32_bf16 v[46:49], v[150:153], v[190:193], v[46:49]
	v_mfma_f32_16x16x32_bf16 v[42:45], v[158:161], v[190:193], v[42:45]
	v_mfma_f32_16x16x32_bf16 v[30:33], v[150:153], v[198:201], v[30:33]
	v_mfma_f32_16x16x32_bf16 v[26:29], v[158:161], v[198:201], v[26:29]
	s_waitcnt lgkmcnt(0)
	v_mfma_f32_16x16x32_bf16 v[14:17], v[150:153], v[206:209], v[14:17]
	v_mfma_f32_16x16x32_bf16 v[10:13], v[158:161], v[206:209], v[10:13]
	s_setprio 0
	s_setprio 1
	v_mfma_f32_16x16x32_bf16 v[54:57], v[162:165], v[178:181], v[54:57]
	v_mfma_f32_16x16x32_bf16 v[50:53], v[170:173], v[178:181], v[50:53]
	v_mfma_f32_16x16x32_bf16 v[38:41], v[162:165], v[186:189], v[38:41]
	v_mfma_f32_16x16x32_bf16 v[34:37], v[170:173], v[186:189], v[34:37]
	v_mfma_f32_16x16x32_bf16 v[22:25], v[162:165], v[194:197], v[22:25]
	v_mfma_f32_16x16x32_bf16 v[18:21], v[170:173], v[194:197], v[18:21]
	v_mfma_f32_16x16x32_bf16 v[6:9], v[162:165], v[202:205], v[6:9]
	v_mfma_f32_16x16x32_bf16 v[2:5], v[170:173], v[202:205], v[2:5]
	v_mfma_f32_16x16x32_bf16 v[54:57], v[166:169], v[182:185], v[54:57]
	v_mfma_f32_16x16x32_bf16 v[50:53], v[174:177], v[182:185], v[50:53]
	v_mfma_f32_16x16x32_bf16 v[38:41], v[166:169], v[190:193], v[38:41]
	v_mfma_f32_16x16x32_bf16 v[34:37], v[174:177], v[190:193], v[34:37]
	v_mfma_f32_16x16x32_bf16 v[22:25], v[166:169], v[198:201], v[22:25]
	v_mfma_f32_16x16x32_bf16 v[18:21], v[174:177], v[198:201], v[18:21]
	v_mfma_f32_16x16x32_bf16 v[6:9], v[166:169], v[206:209], v[6:9]
	s_setprio 2
	s_barrier
	v_mfma_f32_16x16x32_bf16 v[2:5], v[174:177], v[206:209], v[2:5]
	s_setprio 0
	ds_read_b128 v[134:137], v148
	ds_read_b128 v[150:153], v148 offset:1024
	ds_read_b128 v[154:157], v148 offset:2048
	ds_read_b128 v[158:161], v148 offset:3072
	ds_read_b128 v[162:165], v149
	ds_read_b128 v[166:169], v149 offset:1024
	ds_read_b128 v[170:173], v149 offset:2048
	ds_read_b128 v[174:177], v149 offset:3072
	ds_read_b128 v[178:181], v147 offset:32768
	ds_read_b128 v[182:185], v147 offset:33792
	ds_read_b128 v[186:189], v147 offset:34816
	ds_read_b128 v[190:193], v147 offset:35840
	ds_read_b128 v[194:197], v147 offset:36864
	ds_read_b128 v[198:201], v147 offset:37888
	ds_read_b128 v[202:205], v147 offset:38912
	ds_read_b128 v[206:209], v147 offset:39936
	s_add_u32 s36, s44, 0x2b0000
	s_addc_u32 s37, s45, 0
	s_mov_b32 m0, s52
	s_nop 0
	global_load_lds_dwordx4 v1, s[36:37]
	s_nop 0
	s_mov_b32 m0, s53
	s_nop 0
	global_load_lds_dwordx4 v141, s[36:37]
	s_waitcnt vmcnt(8)
	s_waitcnt lgkmcnt(0)
	s_barrier
	s_setprio 1
	s_waitcnt lgkmcnt(7)
	v_mfma_f32_16x16x32_bf16 v[126:129], v[134:137], v[178:181], v[126:129]
	v_mfma_f32_16x16x32_bf16 v[122:125], v[154:157], v[178:181], v[122:125]
	s_waitcnt lgkmcnt(5)
	v_mfma_f32_16x16x32_bf16 v[110:113], v[134:137], v[186:189], v[110:113]
	v_mfma_f32_16x16x32_bf16 v[106:109], v[154:157], v[186:189], v[106:109]
	s_waitcnt lgkmcnt(3)
	v_mfma_f32_16x16x32_bf16 v[94:97], v[134:137], v[194:197], v[94:97]
	v_mfma_f32_16x16x32_bf16 v[90:93], v[154:157], v[194:197], v[90:93]
	s_waitcnt lgkmcnt(1)
	v_mfma_f32_16x16x32_bf16 v[78:81], v[134:137], v[202:205], v[78:81]
	v_mfma_f32_16x16x32_bf16 v[74:77], v[154:157], v[202:205], v[74:77]
	v_mfma_f32_16x16x32_bf16 v[126:129], v[150:153], v[182:185], v[126:129]
	v_mfma_f32_16x16x32_bf16 v[122:125], v[158:161], v[182:185], v[122:125]
	v_mfma_f32_16x16x32_bf16 v[110:113], v[150:153], v[190:193], v[110:113]
	v_mfma_f32_16x16x32_bf16 v[106:109], v[158:161], v[190:193], v[106:109]
	v_mfma_f32_16x16x32_bf16 v[94:97], v[150:153], v[198:201], v[94:97]
	v_mfma_f32_16x16x32_bf16 v[90:93], v[158:161], v[198:201], v[90:93]
	s_waitcnt lgkmcnt(0)
	v_mfma_f32_16x16x32_bf16 v[78:81], v[150:153], v[206:209], v[78:81]
	v_mfma_f32_16x16x32_bf16 v[74:77], v[158:161], v[206:209], v[74:77]
	s_setprio 0
	s_setprio 1
	v_mfma_f32_16x16x32_bf16 v[118:121], v[162:165], v[178:181], v[118:121]
	v_mfma_f32_16x16x32_bf16 v[114:117], v[170:173], v[178:181], v[114:117]
	v_mfma_f32_16x16x32_bf16 v[102:105], v[162:165], v[186:189], v[102:105]
	v_mfma_f32_16x16x32_bf16 v[98:101], v[170:173], v[186:189], v[98:101]
	v_mfma_f32_16x16x32_bf16 v[86:89], v[162:165], v[194:197], v[86:89]
	v_mfma_f32_16x16x32_bf16 v[82:85], v[170:173], v[194:197], v[82:85]
	v_mfma_f32_16x16x32_bf16 v[70:73], v[162:165], v[202:205], v[70:73]
	v_mfma_f32_16x16x32_bf16 v[66:69], v[170:173], v[202:205], v[66:69]
	v_mfma_f32_16x16x32_bf16 v[118:121], v[166:169], v[182:185], v[118:121]
	v_mfma_f32_16x16x32_bf16 v[114:117], v[174:177], v[182:185], v[114:117]
	v_mfma_f32_16x16x32_bf16 v[102:105], v[166:169], v[190:193], v[102:105]
	v_mfma_f32_16x16x32_bf16 v[98:101], v[174:177], v[190:193], v[98:101]
	v_mfma_f32_16x16x32_bf16 v[86:89], v[166:169], v[198:201], v[86:89]
	v_mfma_f32_16x16x32_bf16 v[82:85], v[174:177], v[198:201], v[82:85]
	v_mfma_f32_16x16x32_bf16 v[70:73], v[166:169], v[206:209], v[70:73]
	s_setprio 2
	s_barrier
; #define PG8_STAGE(bufoff, gbase, voff) do { _Pragma("unroll") for (int _i = 0; _i < 2; ++_i) \
;         asm volatile("s_mov_b32 m0, %2\n\ts_nop 0\n\tglobal_load_lds_dwordx4 %0, %1" :: "v"((voff)[_i]), "s"((const char*)(gbase)), "s"(ldsbase + (unsigned)(bufoff) + ldsw + (unsigned)_i * 8192u) : "memory", "m0"); } while (0)
; #define PG8_LDA(dst, b, h) do { _Pragma("unroll") for (int m = 0; m < 4; ++m) _Pragma("unroll") for (int k = 0; k < 2; ++k) dst[m][k] = *(const PG8_LAS bf16x8*)(lds + PG8_SA(b, h) + aoff + m * 2048 + k * 1024); } while (0)
; #define PG8_MMA(ai, bj, At, Bt) do { __builtin_amdgcn_s_setprio(1); _Pragma("unroll") for (int m = 0; m < 4; ++m) _Pragma("unroll") for (int n = 0; n < 2; ++n) _Pragma("unroll") for (int k = 0; k < 2; ++k) \
;         acc[ai][bj][m][n] = __builtin_amdgcn_mfma_f32_16x16x32_bf16(Bt[n][k], At[m][k], acc[ai][bj][m][n], 0, 0, 0); __builtin_amdgcn_s_setprio(0); } while (0)
; #define PG8_WAIT_V(n) asm volatile("s_waitcnt vmcnt(" #n ")" ::: "memory")
; #define PG8_WAIT_L(n) asm volatile("s_waitcnt lgkmcnt(" #n ")" ::: "memory")
; #define PG8_BAR __builtin_amdgcn_s_barrier()
; #define PG8_SCHED __builtin_amdgcn_sched_barrier(0)
; template <class Epi, class Sched, bool ALIGN_EPI = false, bool SP2 = false>
; __device__ __forceinline__ void gemm_phase(PG8_LAS unsigned char* lds, const Gemm g, const Sched& S, const Epi& E) {
;     ...
;             PG8_WAIT_V(8); PG8_WAIT_L(0); PG8_BAR; PG8_MMA(0, 0, At, B0); PG8_MMA(0, 1, At, B1); PG8_BAR; PG8_SCHED;
;             PG8_LDA(At, 1, 1); PG8_STAGE(PG8_SB(1, 0), b3, voffB); PG8_STAGE(PG8_SB(1, 1), b3 + hstep, voffB); PG8_STAGE(PG8_SA(1, 0), a3, voffA);
;             PG8_WAIT_V(8); PG8_WAIT_L(0); PG8_BAR; PG8_MMA(1, 0, At, B0); PG8_MMA(1, 1, At, B1); PG8_BAR; PG8_SCHED;
;     ...
;         if constexpr (ALIGN_EPI) { if (wr == 0) PG8_BAR; }
	v_mfma_f32_16x16x32_bf16 v[66:69], v[174:177], v[206:209], v[66:69]
	s_setprio 0
	ds_read_b128 v[178:181], v147 offset:49152
	ds_read_b128 v[182:185], v147 offset:50176
	ds_read_b128 v[186:189], v147 offset:51200
	ds_read_b128 v[190:193], v147 offset:52224
	ds_read_b128 v[194:197], v147 offset:53248
	ds_read_b128 v[198:201], v147 offset:54272
	ds_read_b128 v[202:205], v147 offset:55296
	ds_read_b128 v[206:209], v147 offset:56320
	s_add_u32 s36, s42, 0x80
	s_addc_u32 s37, s43, 0
	s_mov_b32 m0, s54
	s_nop 0
	global_load_lds_dwordx4 v140, s[36:37]
	s_nop 0
	s_mov_b32 m0, s55
	s_nop 0
	global_load_lds_dwordx4 v142, s[36:37]
	s_add_u32 s36, s42, 0x2b0080
	s_addc_u32 s37, s43, 0
	s_mov_b32 m0, s58
	s_nop 0
	global_load_lds_dwordx4 v140, s[36:37]
	s_nop 0
	s_mov_b32 m0, s59
	s_nop 0
	global_load_lds_dwordx4 v142, s[36:37]
	s_nop 0
	s_mov_b32 m0, s56
	s_nop 0
	global_load_lds_dwordx4 v1, s[40:41]
	s_nop 0
	s_mov_b32 m0, s57
	s_nop 0
	global_load_lds_dwordx4 v141, s[40:41]
	s_waitcnt vmcnt(8)
	s_waitcnt lgkmcnt(0)
	s_barrier
	s_setprio 1
	s_waitcnt lgkmcnt(7)
	v_mfma_f32_16x16x32_bf16 v[62:65], v[134:137], v[178:181], v[62:65]
	v_mfma_f32_16x16x32_bf16 v[58:61], v[154:157], v[178:181], v[58:61]
	s_waitcnt lgkmcnt(5)
	v_mfma_f32_16x16x32_bf16 v[46:49], v[134:137], v[186:189], v[46:49]
	v_mfma_f32_16x16x32_bf16 v[42:45], v[154:157], v[186:189], v[42:45]
	s_waitcnt lgkmcnt(3)
	v_mfma_f32_16x16x32_bf16 v[30:33], v[134:137], v[194:197], v[30:33]
	v_mfma_f32_16x16x32_bf16 v[26:29], v[154:157], v[194:197], v[26:29]
	s_waitcnt lgkmcnt(1)
	v_mfma_f32_16x16x32_bf16 v[14:17], v[134:137], v[202:205], v[14:17]
	v_mfma_f32_16x16x32_bf16 v[10:13], v[154:157], v[202:205], v[10:13]
	v_mfma_f32_16x16x32_bf16 v[62:65], v[150:153], v[182:185], v[62:65]
	v_mfma_f32_16x16x32_bf16 v[58:61], v[158:161], v[182:185], v[58:61]
	v_mfma_f32_16x16x32_bf16 v[46:49], v[150:153], v[190:193], v[46:49]
	v_mfma_f32_16x16x32_bf16 v[42:45], v[158:161], v[190:193], v[42:45]
	v_mfma_f32_16x16x32_bf16 v[30:33], v[150:153], v[198:201], v[30:33]
	v_mfma_f32_16x16x32_bf16 v[26:29], v[158:161], v[198:201], v[26:29]
	s_waitcnt lgkmcnt(0)
	v_mfma_f32_16x16x32_bf16 v[14:17], v[150:153], v[206:209], v[14:17]
	v_mfma_f32_16x16x32_bf16 v[10:13], v[158:161], v[206:209], v[10:13]
	s_setprio 0
	s_setprio 1
	v_mfma_f32_16x16x32_bf16 v[54:57], v[162:165], v[178:181], v[54:57]
	v_mfma_f32_16x16x32_bf16 v[50:53], v[170:173], v[178:181], v[50:53]
	v_mfma_f32_16x16x32_bf16 v[38:41], v[162:165], v[186:189], v[38:41]
	v_mfma_f32_16x16x32_bf16 v[34:37], v[170:173], v[186:189], v[34:37]
	v_mfma_f32_16x16x32_bf16 v[22:25], v[162:165], v[194:197], v[22:25]
	v_mfma_f32_16x16x32_bf16 v[18:21], v[170:173], v[194:197], v[18:21]
	v_mfma_f32_16x16x32_bf16 v[6:9], v[162:165], v[202:205], v[6:9]
	v_mfma_f32_16x16x32_bf16 v[2:5], v[170:173], v[202:205], v[2:5]
	v_mfma_f32_16x16x32_bf16 v[54:57], v[166:169], v[182:185], v[54:57]
	v_mfma_f32_16x16x32_bf16 v[50:53], v[174:177], v[182:185], v[50:53]
	v_mfma_f32_16x16x32_bf16 v[38:41], v[166:169], v[190:193], v[38:41]
	v_mfma_f32_16x16x32_bf16 v[34:37], v[174:177], v[190:193], v[34:37]
	v_mfma_f32_16x16x32_bf16 v[22:25], v[166:169], v[198:201], v[22:25]
	v_mfma_f32_16x16x32_bf16 v[18:21], v[174:177], v[198:201], v[18:21]
	v_mfma_f32_16x16x32_bf16 v[6:9], v[166:169], v[206:209], v[6:9]
	s_setprio 2
	s_barrier
	v_mfma_f32_16x16x32_bf16 v[2:5], v[174:177], v[206:209], v[2:5]
	s_setprio 0
	s_add_i32 s69, s69, 2
	s_add_u32 s67, s67, 0x100
	s_addc_u32 s68, s68, 0
	s_cmpk_gt_u32 s69, 0xa9
	s_mov_b64 s[36:37], s[38:39]
	s_cbranch_scc0 .LBB0_873
	s_and_b64 vcc, exec, s[10:11]
	s_cbranch_vccz .LBB0_876
	s_barrier
